# v14 + packed f32 VALU ops in attention phase split into scalar ops (same f32 math)
# speedup vs baseline: 1.0090x; 1.0005x over previous
; __device__ __forceinline__ void compress_unit(int U, const Args& a, LAS unsigned char* lds, int tid, int wave, int lane) {
;     ...
;     { const int cl = tid >> 4, e4 = (tid & 15) * 4; float v[4]; float ss = 0.f;
; #pragma unroll
;       for (int q = 0; q < 4; ++q) { v[q] = out2[cl * 65 + e4 + q]; ss += v[q] * v[q]; }
;       if (kv == 0) { ss += __shfl_xor(ss, 1); ss += __shfl_xor(ss, 2); ss += __shfl_xor(ss, 4); ss += __shfl_xor(ss, 8);
;           const float rs = __builtin_amdgcn_rsqf(ss * (1.0f / 64.0f) + RMS_EPS);
; #pragma unroll
;           for (int q = 0; q < 4; ++q) v[q] = v[q] * rs * gnv[q]; }
.LBB0_754:
	s_nop 2
	v_ashrrev_i32_e32 v0, 4, v77
	v_mul_lo_u32 v1, v0, s48
	v_add3_u32 v1, s50, v1, v78
	s_waitcnt lgkmcnt(0)
	s_barrier
	ds_read2_b32 v[2:3], v1 offset1:1
	ds_read2_b32 v[4:5], v1 offset0:2 offset1:3
	s_andn2_b64 vcc, exec, s[12:13]
	s_cbranch_vccnz .LBB0_756
	s_waitcnt lgkmcnt(1)
	v_mul_f32_e32 v6, v2, v2
	v_mul_f32_e32 v7, v3, v3
	s_waitcnt lgkmcnt(0)
	v_mul_f32_e32 v8, v4, v4
	v_mul_f32_e32 v9, v5, v5
	v_add_f32_e32 v1, v6, v7
	v_add_f32_e32 v1, v1, v8
	v_add_f32_e32 v1, v1, v9
	ds_bpermute_b32 v6, v72, v1
	s_waitcnt lgkmcnt(0)
	v_add_f32_e32 v1, v1, v6
	ds_bpermute_b32 v6, v73, v1
	s_waitcnt lgkmcnt(0)
	v_add_f32_e32 v1, v1, v6
	ds_bpermute_b32 v6, v74, v1
	s_waitcnt lgkmcnt(0)
	v_add_f32_e32 v1, v1, v6
	ds_bpermute_b32 v6, v75, v1
	s_waitcnt lgkmcnt(0)
	v_add_f32_e32 v1, v1, v6
	v_fmamk_f32 v1, v1, 0x3c800000, v76
	v_rsq_f32_e32 v6, v1
	s_nop 0
	v_mul_f32_e32 v2, v2, v6
	v_mul_f32_e32 v3, v3, v6
	v_mul_f32_e32 v4, v4, v6
	v_mul_f32_e32 v5, v5, v6
	v_mul_f32_e32 v2, v16, v2
	v_mul_f32_e32 v3, v17, v3
	v_mul_f32_e32 v4, v18, v4
	v_mul_f32_e32 v5, v19, v5

; __device__ __forceinline__ void fox_cum(int b, int hh, const Args& a, LAS unsigned char* lds, int tid, int wave, int lane) {
;     ...
;     float base = 0.f;
;     for (int i = 0; i < wave; ++i) base += wsum[i];
;     const float excl = (tot - v[3]) + base;
; #pragma unroll
;     for (int i = 0; i < 4; ++i) cum2[4 * tid + i] = (v[i] + excl) * (-LOG2E);
;     __syncthreads();
.LBB0_780:
	v_cmp_gt_u32_e32 vcc, 32, v217
	s_mov_b64 s[8:9], 0
	s_nop 0
	v_cndmask_b32_e32 v5, v6, v5, vcc
	v_sub_f32_e32 v5, v5, v3
	v_add_f32_e32 v6, v5, v7
	v_lshl_add_u32 v5, v56, 4, 0
	v_add_f32_e32 v0, v0, v6
	v_add_f32_e32 v1, v1, v6
	v_add_f32_e32 v2, v2, v6
	v_add_f32_e32 v3, v3, v6
	v_add_u32_e32 v5, 0x15000, v5
	v_mul_f32_e32 v0, s14, v0
	v_mul_f32_e32 v1, s14, v1
	v_mul_f32_e32 v2, s14, v2
	v_mul_f32_e32 v3, s14, v3
	ds_write_b128 v5, v[0:3]
	s_waitcnt lgkmcnt(0)
	s_barrier

; #define WAIT_BAR(N) asm volatile("s_waitcnt vmcnt(" #N ") lgkmcnt(0)\n\ts_barrier":::"memory")
;   #define BIAS(P0,P1,t) do{ const __attribute__((address_space(3))) f32x4v*nbp_=(const __attribute__((address_space(3))) f32x4v*)(nb+64*(t)+4*hi); \
;     _Pragma("unroll") for(int g_=0;g_<4;++g_){ const f32x4v c0_=nbp_[2*g_],c1_=nbp_[2*g_+8]; _Pragma("unroll") for(int i_=0;i_<4;++i_){P0[4*g_+i_]+=c0_[i_];P1[4*g_+i_]+=c1_[i_];} SBAR(); } }while(0)
;   #define DMA_K(t,slot) glds16(ksrc+(long)(t)*KVBLK*DM,(unsigned)__builtin_amdgcn_readfirstlane(kdst+(slot)))
;   #define DMA_V(t,slot) glds16(vsrc+(long)(t)*KVBLK*DM,(unsigned)__builtin_amdgcn_readfirstlane(vdst+(slot)))
;   #define CMASK(P0,P1,t) do{}while(0)
; template<int THRL> __device__ __forceinline__ void attn_unit(int b,int h,int qb,const bf16*Q,const bf16*__restrict__ K,const bf16*__restrict__ V,bf16*O,char*shm,int tid,const __attribute__((address_space(3))) float*nb){
;     ...
;   const long rowbase=(long)b*SEQ; const int q0=qb*QB;
;   const bf16*Qw=Q+(rowbase+q0+wid*QBLK)*DM+h*D;
;   const bf16*Kh=K+rowbase*DM+h*D,*Vh=V+rowbase*DM+h*D;
;   const unsigned lds0=(unsigned)(uintptr_t)shm;
;   float*wsf=(float*)(shm+LDS_WS)+wid*64;
;   const bf16*ksrc=Kh+(long)lane*DM+wid*8;
;   const bf16*vsrc=Vh+(long)(16*(wid&3)+(lane>>2))*DM+(wid>>2)*32+(lane&3)*8;
;   const unsigned kdst=lds0+LDS_K+wid*1024, vdst=lds0+LDS_V+wid*1024;
;     ...
;   const int vb0=(int)(lds0+LDS_V)+((lane>>4)&1)*32+(lane&3)*8+(4*hi+((lane&15)>>2))*64;
;   const char*Kbase=shm+LDS_K; bf16x8 kf[8];
;   const lds_cptr shm3=(lds_cptr)shm; const lds_cptr kp0=shm3+LDS_K+hi*1024+r32*16; const lds_cptr vp0=shm3+LDS_V+((lane>>4)&1)*32+(lane&3)*8+(4*hi+((lane&15)>>2))*64;
;   const int NT=(q0+QB)/KVBLK;
;   DMA_K(0,0);DMA_V(0,0);DMA_K(1,SLOTB);
;   bf16x8 qr[4];
;   #pragma unroll
;   for(int d0=0;d0<4;++d0)qr[d0]=*reinterpret_cast<const bf16x8*>(&Qw[(long)r32*DM+d0*16+hi*8]);
;   float mhat=0.f,l_reg=0.f;f32x16 o[2];float zf_=0.f;asm volatile("":"+v"(zf_));f32x16 negm;_Pragma("unroll") for(int r=0;r<16;++r)negm[r]=zf_;asm volatile("":"+v"(negm));o[0]=negm;o[1]=negm;
;   const int qrel=wid*QBLK+r32;
;     ...
;   bool resc=false;
;     ...
;   f32x16 pA0,pA1,pB0,pB1;
;   int sl_prev=0,sl_cur=0,sl_next=SLOTB;
;     ...
;   DMA_K(2,2*SLOTB);
;   WAIT_BAR(3);
;   qkt(pA0,pA1,Kbase,qr,negm,r32,hi);asm volatile("s_nop 15\n\ts_nop 7":"+v"(pA0),"+v"(pA1));BIAS(pA0,pA1,0);CMASK(pA0,pA1,0);
.LBB0_783:
	s_lshr_b32 s9, s1, 3
	v_readfirstlane_b32 s1, v56
	s_ashr_i32 s64, s1, 6
	s_lshl_b32 s8, s9, 11
	s_lshl_b32 s35, s34, 8
	s_add_i32 s10, s35, s8
	s_lshl_b32 s8, s64, 5
	s_lshr_b32 s0, s58, 1
	s_ashr_i32 s11, s8, 31
	s_add_u32 s28, s8, s10
	s_addc_u32 s29, s11, 0
	s_lshl_b64 s[10:11], s[28:29], 10
	s_add_u32 s10, s48, s10
	s_addc_u32 s11, s49, s11
	s_lshl_b32 s0, s0, 6
	s_and_b32 s0, s0, 0x1c0
	s_lshl_b32 s63, s0, 1
	s_add_u32 s10, s10, s63
	s_addc_u32 s11, s11, 0
	s_lshl_b32 s0, s9, 21
	s_add_u32 s9, s50, s0
	s_addc_u32 s12, s51, 0
	s_add_u32 s30, s9, s63
	s_addc_u32 s31, s12, 0
	s_add_u32 s0, s52, s0
	s_addc_u32 s9, s53, 0
	s_add_u32 s36, s0, s63
	v_lshlrev_b32_e32 v208, 10, v217
	s_addc_u32 s37, s9, 0
	v_lshl_add_u64 v[0:1], s[30:31], 0, v[208:209]
	s_lshl_b32 s30, s64, 3
	s_ashr_i32 s31, s30, 31
	v_lshl_add_u64 v[188:189], s[30:31], 1, v[0:1]
	s_lshl_b32 s0, s64, 4
	v_lshrrev_b32_e32 v0, 2, v217
	v_and_or_b32 v0, s0, 48, v0
	s_ashr_i32 s0, s1, 3
	s_and_b32 s30, s0, 0xffffffe0
	s_ashr_i32 s31, s30, 31
	s_lshl_b32 s0, s64, 10
	v_lshlrev_b32_e32 v208, 10, v0
	v_lshlrev_b32_e32 v218, 3, v56
	s_cmp_lg_u32 0, -1
	v_lshl_add_u64 v[0:1], s[36:37], 0, v[208:209]
	v_and_b32_e32 v221, 24, v218
	s_cselect_b32 s9, 0, 0
	v_lshrrev_b32_e32 v220, 5, v217
	v_lshl_add_u64 v[0:1], s[30:31], 1, v[0:1]
	v_lshlrev_b32_e32 v208, 1, v221
	s_add_i32 s65, s0, s9
	s_mov_b32 m0, s65
	s_nop 0
	global_load_lds_dwordx4 v[188:189], off
	v_and_b32_e32 v219, 31, v56
	v_lshl_add_u64 v[80:81], v[0:1], 0, v[208:209]
	s_add_i32 s68, s65, 0x6000
	s_mov_b32 m0, s68
	s_nop 0
	global_load_lds_dwordx4 v[80:81], off
	v_lshl_add_u64 v[0:1], v[188:189], 0, s[16:17]
	v_lshlrev_b32_e32 v52, 4, v220
	s_add_i32 s9, s65, 0x2000
	s_mov_b32 m0, s9
	s_nop 0
	global_load_lds_dwordx4 v[0:1], off
	v_lshl_or_b32 v1, v219, 10, v52
	global_load_dwordx4 v[128:131], v1, s[10:11]
	global_load_dwordx4 v[120:123], v1, s[10:11] offset:32
	global_load_dwordx4 v[116:119], v1, s[10:11] offset:64
	global_load_dwordx4 v[112:115], v1, s[10:11] offset:96
	v_mov_b32_e32 v0, v209
	v_lshlrev_b32_e32 v2, 10, v220
	v_lshlrev_b32_e32 v3, 4, v219
	v_add3_u32 v228, 0, v2, v3
	v_lshl_add_u64 v[16:17], v[188:189], 0, s[18:19]
	v_mov_b32_e32 v1, v0
	v_mov_b32_e32 v2, v0
	v_mov_b32_e32 v3, v0
	v_mov_b32_e32 v4, v0
	v_mov_b32_e32 v5, v0
	v_mov_b32_e32 v6, v0
	v_mov_b32_e32 v7, v0
	v_mov_b32_e32 v8, v0
	v_mov_b32_e32 v9, v0
	v_mov_b32_e32 v10, v0
	v_mov_b32_e32 v11, v0
	v_mov_b32_e32 v12, v0
	v_mov_b32_e32 v13, v0
	v_mov_b32_e32 v14, v0
	v_mov_b32_e32 v15, v0
	s_add_i32 s9, s65, 0x4000
	s_mov_b32 m0, s9
	s_nop 0
	global_load_lds_dwordx4 v[16:17], off
	s_waitcnt vmcnt(3) lgkmcnt(0)
	s_barrier
	ds_read_b128 v[16:19], v228
	ds_read_b128 v[48:51], v228 offset:512
	v_lshlrev_b32_e32 v225, 2, v220
	s_waitcnt vmcnt(0) lgkmcnt(0)
	v_mfma_f32_32x32x16_bf16 v[32:47], v[16:19], v[128:131], v[0:15]
	v_mfma_f32_32x32x16_bf16 v[16:31], v[48:51], v[128:131], v[0:15]
	ds_read_b128 v[48:51], v228 offset:2048
	s_waitcnt lgkmcnt(0)
	v_mfma_f32_32x32x16_bf16 v[32:47], v[48:51], v[120:123], v[32:47]
	ds_read_b128 v[48:51], v228 offset:2560
	s_waitcnt lgkmcnt(0)
	v_mfma_f32_32x32x16_bf16 v[16:31], v[48:51], v[120:123], v[16:31]
	ds_read_b128 v[48:51], v228 offset:4096
	s_waitcnt lgkmcnt(0)
	v_mfma_f32_32x32x16_bf16 v[32:47], v[48:51], v[116:119], v[32:47]
	ds_read_b128 v[48:51], v228 offset:4608
	s_waitcnt lgkmcnt(0)
	v_mfma_f32_32x32x16_bf16 v[16:31], v[48:51], v[116:119], v[16:31]
	ds_read_b128 v[48:51], v228 offset:6144
	s_waitcnt lgkmcnt(0)
	v_mfma_f32_32x32x16_bf16 v[32:47], v[48:51], v[112:115], v[32:47]
	ds_read_b128 v[48:51], v228 offset:6656
	s_waitcnt lgkmcnt(0)
	v_mfma_f32_32x32x16_bf16 v[16:31], v[48:51], v[112:115], v[16:31]
	v_add_u32_e32 v48, 0, v52
	v_add_u32_e32 v54, 0x15000, v48
	s_nop 15
	s_nop 7
	ds_read_b128 v[48:51], v54
	ds_read_b128 v[58:61], v54 offset:128
	s_waitcnt lgkmcnt(1)
	s_nop 3
	v_add_f32_e32 v52, v48, v32
	v_add_f32_e32 v53, v49, v33
	v_add_f32_e32 v48, v50, v34
	v_add_f32_e32 v49, v51, v35
	ds_read_b128 v[32:35], v54 offset:32
	ds_read_b128 v[62:65], v54 offset:160
	s_waitcnt lgkmcnt(1)
	v_add_f32_e32 v50, v36, v32
	v_add_f32_e32 v51, v37, v33
	v_add_f32_e32 v34, v38, v34
	v_add_f32_e32 v35, v39, v35
	ds_read_b128 v[36:39], v54 offset:64
	ds_read_b128 v[66:69], v54 offset:192
	s_waitcnt lgkmcnt(1)
	v_add_f32_e32 v36, v40, v36
	v_add_f32_e32 v37, v41, v37
	v_add_f32_e32 v32, v42, v38
	v_add_f32_e32 v33, v43, v39
	ds_read_b128 v[70:73], v54 offset:96
	ds_read_b128 v[74:77], v54 offset:224
	v_add_f32_e32 v54, v18, v60
	v_add_f32_e32 v55, v19, v61
	v_add_f32_e32 v40, v20, v62
	v_add_f32_e32 v41, v21, v63
	v_add_f32_e32 v42, v22, v64
	v_add_f32_e32 v43, v23, v65
	s_waitcnt lgkmcnt(1)
	v_add_f32_e32 v20, v44, v70
	v_add_f32_e32 v21, v45, v71
	v_add_f32_e32 v18, v46, v72
	v_add_f32_e32 v19, v47, v73
	v_add_f32_e32 v38, v24, v66
	v_add_f32_e32 v39, v25, v67
	v_add_f32_e32 v26, v26, v68
	v_add_f32_e32 v27, v27, v69
	s_waitcnt lgkmcnt(0)
	v_add_f32_e32 v24, v28, v74
	v_add_f32_e32 v25, v29, v75
	v_add_f32_e32 v22, v30, v76
	v_add_f32_e32 v23, v31, v77
	v_add_f32_e32 v16, v16, v58
	v_add_f32_e32 v17, v17, v59
	s_cmp_lg_u32 s34, 0
	v_or_b32_e32 v226, s8, v219
	s_cselect_b64 s[8:9], -1, 0
	s_and_b64 vcc, exec, s[8:9]
	s_cbranch_vccnz .LBB0_785
; __device__ __forceinline__ void cmask(f32x16&p0,f32x16&p1,int jb,int qrel,int hi){
;   const float NEG=-INFINITY; int kb=64*jb+4*hi;
;   #pragma unroll
;   for(int r=0;r<16;++r){int kv=kb+(r&3)+8*(r>>2); if(kv>qrel)p0[r]=NEG; if(kv+32>qrel)p1[r]=NEG;}
; }
	v_or_b32_e32 v28, 32, v225
	v_cmp_le_i32_e32 vcc, v28, v226
	v_or_b32_e32 v28, 33, v225
	s_nop 0
	v_cndmask_b32_e32 v16, v216, v16, vcc
	v_cmp_le_i32_e32 vcc, v225, v226
	s_nop 1
	v_cndmask_b32_e32 v52, v216, v52, vcc
	v_cmp_lt_i32_e32 vcc, v225, v226
	s_nop 1
	v_cndmask_b32_e32 v53, v216, v53, vcc
	v_cmp_le_i32_e32 vcc, v28, v226
	v_or_b32_e32 v28, 2, v225
	s_nop 0
	v_cndmask_b32_e32 v17, v216, v17, vcc
	v_cmp_le_i32_e32 vcc, v28, v226
	v_or_b32_e32 v28, 34, v225
	s_nop 0
	v_cndmask_b32_e32 v48, v216, v48, vcc
	v_cmp_le_i32_e32 vcc, v28, v226
	v_or_b32_e32 v28, 3, v225
	s_nop 0
	v_cndmask_b32_e32 v54, v216, v54, vcc
	v_cmp_le_i32_e32 vcc, v28, v226
	v_or_b32_e32 v28, 35, v225
	s_nop 0
	v_cndmask_b32_e32 v49, v216, v49, vcc
	v_cmp_le_i32_e32 vcc, v28, v226
	v_or_b32_e32 v28, 8, v225
	s_nop 0
	v_cndmask_b32_e32 v55, v216, v55, vcc
	v_cmp_le_i32_e32 vcc, v28, v226
	v_or_b32_e32 v28, 40, v225
	s_nop 0
	v_cndmask_b32_e32 v50, v216, v50, vcc
	v_cmp_le_i32_e32 vcc, v28, v226
	v_or_b32_e32 v28, 9, v225
	s_nop 0
	v_cndmask_b32_e32 v40, v216, v40, vcc
	v_cmp_le_i32_e32 vcc, v28, v226
	v_or_b32_e32 v28, 41, v225
	s_nop 0
	v_cndmask_b32_e32 v51, v216, v51, vcc
	v_cmp_le_i32_e32 vcc, v28, v226
	v_or_b32_e32 v28, 10, v225
	s_nop 0
	v_cndmask_b32_e32 v41, v216, v41, vcc
	v_cmp_le_i32_e32 vcc, v28, v226
	v_or_b32_e32 v28, 42, v225
	s_nop 0
	v_cndmask_b32_e32 v34, v216, v34, vcc
	v_cmp_le_i32_e32 vcc, v28, v226
	v_or_b32_e32 v28, 11, v225
	s_nop 0
	v_cndmask_b32_e32 v42, v216, v42, vcc
	v_cmp_le_i32_e32 vcc, v28, v226
	v_or_b32_e32 v28, 43, v225
	s_nop 0
	v_cndmask_b32_e32 v35, v216, v35, vcc
	v_cmp_le_i32_e32 vcc, v28, v226
	v_or_b32_e32 v28, 16, v225
	s_nop 0
	v_cndmask_b32_e32 v43, v216, v43, vcc
	v_cmp_le_i32_e32 vcc, v28, v226
	v_or_b32_e32 v28, 48, v225
	s_nop 0
	v_cndmask_b32_e32 v36, v216, v36, vcc
	v_cmp_le_i32_e32 vcc, v28, v226
	v_or_b32_e32 v28, 17, v225
	s_nop 0
	v_cndmask_b32_e32 v38, v216, v38, vcc
	v_cmp_le_i32_e32 vcc, v28, v226
	v_or_b32_e32 v28, 49, v225
	s_nop 0
	v_cndmask_b32_e32 v37, v216, v37, vcc
	v_cmp_le_i32_e32 vcc, v28, v226
	v_or_b32_e32 v28, 18, v225
	s_nop 0
	v_cndmask_b32_e32 v39, v216, v39, vcc
	v_cmp_le_i32_e32 vcc, v28, v226
	v_or_b32_e32 v28, 50, v225
	s_nop 0
	v_cndmask_b32_e32 v32, v216, v32, vcc
	v_cmp_le_i32_e32 vcc, v28, v226
	v_or_b32_e32 v28, 19, v225
	s_nop 0
	v_cndmask_b32_e32 v26, v216, v26, vcc
	v_cmp_le_i32_e32 vcc, v28, v226
	v_or_b32_e32 v28, 51, v225
	s_nop 0
	v_cndmask_b32_e32 v33, v216, v33, vcc
	v_cmp_le_i32_e32 vcc, v28, v226
	v_or_b32_e32 v28, 24, v225
	s_nop 0
	v_cndmask_b32_e32 v27, v216, v27, vcc
	v_cmp_le_i32_e32 vcc, v28, v226
	v_or_b32_e32 v28, 56, v225
	s_nop 0
	v_cndmask_b32_e32 v20, v216, v20, vcc
	v_cmp_le_i32_e32 vcc, v28, v226
	v_or_b32_e32 v28, 25, v225
	s_nop 0
	v_cndmask_b32_e32 v24, v216, v24, vcc
	v_cmp_le_i32_e32 vcc, v28, v226
	v_or_b32_e32 v28, 57, v225
	s_nop 0
	v_cndmask_b32_e32 v21, v216, v21, vcc
	v_cmp_le_i32_e32 vcc, v28, v226
	v_or_b32_e32 v28, 26, v225
	s_nop 0
	v_cndmask_b32_e32 v25, v216, v25, vcc
	v_cmp_le_i32_e32 vcc, v28, v226
	v_or_b32_e32 v28, 58, v225
	s_nop 0
	v_cndmask_b32_e32 v18, v216, v18, vcc
	v_cmp_le_i32_e32 vcc, v28, v226
	v_or_b32_e32 v28, 27, v225
	s_nop 0
	v_cndmask_b32_e32 v22, v216, v22, vcc
	v_cmp_le_i32_e32 vcc, v28, v226
	v_or_b32_e32 v28, 59, v225
	s_nop 0
	v_cndmask_b32_e32 v19, v216, v19, vcc
	v_cmp_le_i32_e32 vcc, v28, v226
	s_nop 1
	v_cndmask_b32_e32 v23, v216, v23, vcc

.LBB0_787:
	v_add_u32_e32 v180, s10, v229
	ds_read_b64_tr_b16 v[176:177], v180 offset:24576
	ds_read_b64_tr_b16 v[178:179], v180 offset:25088
	v_add_f32_e32 v80, v64, v65
	v_add_f32_e32 v80, v66, v80
	v_add_f32_e32 v80, v67, v80
	v_add_f32_e32 v80, v68, v80
	v_add_f32_e32 v96, v69, v80
	v_mfma_f32_32x32x16_bf16 v[80:95], v[172:175], v[128:131], v[32:47]
	v_cvt_pk_bf16_f32 v140, v64, v65
	v_cvt_pk_bf16_f32 v141, v66, v67
	ds_read_b64_tr_b16 v[172:173], v180 offset:28672
	ds_read_b64_tr_b16 v[174:175], v180 offset:29184
	v_add_f32_e32 v64, v70, v96
	v_add_f32_e32 v64, v71, v64
	v_add_f32_e32 v64, v72, v64
	v_add_f32_e32 v64, v73, v64
	v_cvt_pk_bf16_f32 v142, v68, v69
	v_cvt_pk_bf16_f32 v143, v70, v71
	v_mfma_f32_32x32x16_bf16 v[96:111], v[168:171], v[128:131], v[32:47]
	ds_read_b64_tr_b16 v[168:169], v180 offset:25600
	ds_read_b64_tr_b16 v[170:171], v180 offset:26112
	v_mfma_f32_32x32x16_bf16 v[80:95], v[164:167], v[120:123], v[80:95]
	v_add_f32_e32 v64, v74, v64
	v_add_f32_e32 v64, v75, v64
	v_add_f32_e32 v64, v76, v64
	v_add_f32_e32 v64, v77, v64
	v_cvt_pk_bf16_f32 v136, v72, v73
	v_cvt_pk_bf16_f32 v137, v74, v75
	ds_read_b64_tr_b16 v[164:165], v180 offset:29696
	ds_read_b64_tr_b16 v[166:167], v180 offset:30208
	v_add_f32_e32 v64, v78, v64
	v_add_f32_e32 v64, v79, v64
	v_add_f32_e32 v64, v48, v64
	v_add_f32_e32 v64, v49, v64
	v_cvt_pk_bf16_f32 v138, v76, v77
	v_cvt_pk_bf16_f32 v139, v78, v79
	v_mfma_f32_32x32x16_bf16 v[96:111], v[160:163], v[120:123], v[96:111]
	ds_read_b64_tr_b16 v[160:161], v180 offset:26624
	ds_read_b64_tr_b16 v[162:163], v180 offset:27136
	v_mfma_f32_32x32x16_bf16 v[80:95], v[156:159], v[116:119], v[80:95]
	v_add_f32_e32 v64, v50, v64
	v_add_f32_e32 v64, v51, v64
	v_add_f32_e32 v64, v52, v64
	v_add_f32_e32 v64, v53, v64
	v_cvt_pk_bf16_f32 v132, v48, v49
	v_cvt_pk_bf16_f32 v133, v50, v51
	ds_read_b64_tr_b16 v[156:157], v180 offset:30720
	ds_read_b64_tr_b16 v[158:159], v180 offset:31232
	v_add_f32_e32 v48, v54, v64
	v_add_f32_e32 v48, v55, v48
	v_add_f32_e32 v48, v56, v48
	v_add_f32_e32 v48, v57, v48
	v_cvt_pk_bf16_f32 v134, v52, v53
	v_cvt_pk_bf16_f32 v135, v54, v55
	v_mfma_f32_32x32x16_bf16 v[96:111], v[152:155], v[116:119], v[96:111]
	ds_read_b64_tr_b16 v[152:153], v180 offset:27648
	ds_read_b64_tr_b16 v[154:155], v180 offset:28160
	v_mfma_f32_32x32x16_bf16 v[80:95], v[148:151], v[112:115], v[80:95]
	v_add_f32_e32 v48, v58, v48
	v_add_f32_e32 v48, v59, v48
	v_add_f32_e32 v48, v60, v48
	v_add_f32_e32 v48, v61, v48
	v_cvt_pk_bf16_f32 v124, v56, v57
	v_cvt_pk_bf16_f32 v125, v58, v59
	ds_read_b64_tr_b16 v[148:149], v180 offset:31744
	ds_read_b64_tr_b16 v[150:151], v180 offset:32256
	v_add_f32_e32 v48, v62, v48
	v_add_f32_e32 v48, v63, v48
	v_add_f32_e32 v180, 0, v48
	v_cvt_pk_bf16_f32 v126, v60, v61
	v_cvt_pk_bf16_f32 v127, v62, v63
	v_mfma_f32_32x32x16_bf16 v[96:111], v[144:147], v[112:115], v[96:111]
	s_waitcnt lgkmcnt(8)
	ds_read_b128 v[64:67], v196
	ds_read_b128 v[68:71], v196 offset:32
	ds_read_b128 v[72:75], v196 offset:64
	ds_read_b128 v[76:79], v196 offset:96
	ds_read_b128 v[52:55], v196 offset:160
	ds_read_b128 v[56:59], v196 offset:192
	ds_read_b128 v[60:63], v196 offset:224
	v_lshl_add_u64 v[48:49], v[194:195], 0, s[24:25]
	s_add_i32 s0, s36, s65
	s_mov_b32 m0, s0
	s_nop 0
	global_load_lds_dwordx4 v[48:49], off
	v_lshl_add_u64 v[48:49], v[192:193], 0, s[24:25]
	s_add_i32 s0, s1, s68
	s_mov_b32 m0, s0
	s_nop 0
	global_load_lds_dwordx4 v[48:49], off
	ds_read_b128 v[48:51], v196 offset:128
	s_waitcnt lgkmcnt(4)
	v_add_f32_e32 v64, v80, v64
	v_add_f32_e32 v65, v81, v65
	v_add_f32_e32 v66, v82, v66
	v_add_f32_e32 v67, v83, v67
	v_add_f32_e32 v68, v84, v68
	v_add_f32_e32 v69, v85, v69
	v_add_f32_e32 v70, v86, v70
	v_add_f32_e32 v71, v87, v71
	v_add_f32_e32 v72, v88, v72
	v_add_f32_e32 v73, v89, v73
	v_add_f32_e32 v74, v90, v74
	v_add_f32_e32 v75, v91, v75
	v_add_f32_e32 v76, v92, v76
	v_add_f32_e32 v77, v93, v77
	v_add_f32_e32 v78, v94, v78
	v_add_f32_e32 v79, v95, v79
	s_waitcnt lgkmcnt(1)
	v_add_f32_e32 v52, v100, v52
	v_add_f32_e32 v53, v101, v53
	v_add_f32_e32 v54, v102, v54
	v_add_f32_e32 v55, v103, v55
	v_add_f32_e32 v56, v104, v56
	v_add_f32_e32 v57, v105, v57
	v_add_f32_e32 v58, v106, v58
	v_add_f32_e32 v59, v107, v59
	v_add_f32_e32 v60, v108, v60
	v_add_f32_e32 v61, v109, v61
	v_add_f32_e32 v62, v110, v62
	v_add_f32_e32 v63, v111, v63
	s_waitcnt lgkmcnt(0)
	v_add_f32_e32 v48, v96, v48
	v_add_f32_e32 v49, v97, v49
	v_add_f32_e32 v50, v98, v50
	v_add_f32_e32 v51, v99, v51
	v_max_f32_e32 v80, v64, v65
	v_max3_f32 v81, v66, v67, v49
	v_max3_f32 v80, v80, v48, v50
	v_max3_f32 v80, v80, v51, v68
	v_max3_f32 v81, v81, v70, v71
	v_max3_f32 v80, v80, v69, v52
	v_max3_f32 v81, v81, v54, v55
	v_max3_f32 v80, v80, v53, v72
	v_max3_f32 v81, v81, v74, v75
	v_max3_f32 v80, v80, v73, v56
	v_max3_f32 v81, v81, v58, v59
	v_max3_f32 v80, v80, v57, v76
	v_max3_f32 v81, v81, v78, v79
	v_max3_f32 v80, v80, v77, v60
	v_max3_f32 v81, v81, v62, v63
	v_max3_f32 v80, v80, v61, v81
	v_mov_b32_e32 v81, v80
	s_nop 1
	v_permlane32_swap_b32_e32 v80, v81
	v_max_f32_e32 v81, v81, v81
	v_max_f32_e32 v80, v80, v80
	v_max_f32_e32 v80, v80, v81
	v_cmp_lt_f32_e32 vcc, s61, v80
	s_cmp_lg_u64 vcc, 0
	v_add_f32_e32 v197, v231, v180
	s_cselect_b64 s[10:11], -1, 0
	s_cbranch_vccnz .LBB0_795
; #define WAIT_BAR(N) asm volatile("s_waitcnt vmcnt(" #N ") lgkmcnt(0)\n\ts_barrier":::"memory")
;   #define RESC() do{ if(resc){ asm volatile("s_waitcnt lgkmcnt(0)":::"memory"); \
;       _Pragma("unroll") for(int d_=0;d_<2;++d_) _Pragma("unroll") for(int r=0;r<16;++r)o[d_][r]*=wsf[crow(r,hi)]; } }while(0)
;   #define ROT() do{sl_prev=sl_cur;sl_cur=sl_next;sl_next=(sl_next==(NSLOT-1)*SLOTB)?0:sl_next+SLOTB;}while(0)
; template<int THRL> __device__ __forceinline__ void attn_unit(int b,int h,int qb,const bf16*Q,const bf16*__restrict__ K,const bf16*__restrict__ V,bf16*O,char*shm,int tid,const __attribute__((address_space(3))) float*nb){
;     ...
;   int t=1;
;     ...
;   for(;t+5<NT;t+=2){
;     STEP(pB0,pB1,pA0,pA1,t,true,true,true);     WAIT_BAR(2); RESC(); ROT();
;     STEP(pA0,pA1,pB0,pB1,t+1,true,true,true);   WAIT_BAR(2); RESC(); ROT();
.LBB0_788:
	v_mfma_f32_32x32x16_bf16 v[16:31], v[140:143], v[176:179], v[16:31]
	v_exp_f32_e32 v64, v64
	v_exp_f32_e32 v65, v65
	v_exp_f32_e32 v66, v66
	v_exp_f32_e32 v67, v67
	v_mfma_f32_32x32x16_bf16 v[0:15], v[140:143], v[172:175], v[0:15]
	v_exp_f32_e32 v68, v68
	v_exp_f32_e32 v69, v69
	v_exp_f32_e32 v70, v70
	v_exp_f32_e32 v71, v71
	v_add_u32_e32 v80, s1, v228
	ds_read_b128 v[96:99], v80
	ds_read_b128 v[180:183], v80 offset:512
	v_mfma_f32_32x32x16_bf16 v[16:31], v[136:139], v[168:171], v[16:31]
	v_exp_f32_e32 v72, v72
	v_exp_f32_e32 v73, v73
	v_exp_f32_e32 v74, v74
	v_exp_f32_e32 v75, v75
	ds_read_b128 v[184:187], v80 offset:2048
	ds_read_b128 v[144:147], v80 offset:2560
	v_mfma_f32_32x32x16_bf16 v[0:15], v[136:139], v[164:167], v[0:15]
	v_exp_f32_e32 v76, v76
	v_exp_f32_e32 v77, v77
	v_exp_f32_e32 v78, v78
	v_exp_f32_e32 v79, v79
	ds_read_b128 v[176:179], v80 offset:4096
	ds_read_b128 v[168:171], v80 offset:4608
	v_mfma_f32_32x32x16_bf16 v[16:31], v[132:135], v[160:163], v[16:31]
	v_exp_f32_e32 v48, v48
	v_exp_f32_e32 v49, v49
	v_exp_f32_e32 v50, v50
	v_exp_f32_e32 v51, v51
	ds_read_b128 v[172:175], v80 offset:6144
	ds_read_b128 v[164:167], v80 offset:6656
	v_mfma_f32_32x32x16_bf16 v[0:15], v[132:135], v[156:159], v[0:15]
	v_exp_f32_e32 v52, v52
	v_exp_f32_e32 v53, v53
	v_exp_f32_e32 v54, v54
	v_exp_f32_e32 v55, v55
	v_mfma_f32_32x32x16_bf16 v[16:31], v[124:127], v[152:155], v[16:31]
	v_exp_f32_e32 v56, v56
	v_exp_f32_e32 v57, v57
	v_exp_f32_e32 v58, v58
	v_exp_f32_e32 v59, v59
	v_mfma_f32_32x32x16_bf16 v[0:15], v[124:127], v[148:151], v[0:15]
	v_exp_f32_e32 v60, v60
	v_exp_f32_e32 v61, v61
	v_exp_f32_e32 v62, v62
	v_exp_f32_e32 v63, v63
	s_waitcnt vmcnt(2) lgkmcnt(0)
	s_barrier
	s_andn2_b64 vcc, exec, s[10:11]
	s_cbranch_vccnz .LBB0_790
	s_waitcnt lgkmcnt(0)
	ds_read_b128 v[80:83], v223 offset:49248
	ds_read_b128 v[84:87], v223 offset:49216
	ds_read_b128 v[88:91], v223 offset:49184
	ds_read_b128 v[92:95], v223 offset:49152
	s_waitcnt lgkmcnt(3)
	v_mul_f32_e32 v30, v30, v82
	v_mul_f32_e32 v31, v31, v83
	s_waitcnt lgkmcnt(2)
	v_mul_f32_e32 v26, v26, v86
	v_mul_f32_e32 v27, v27, v87
	s_waitcnt lgkmcnt(1)
	v_mul_f32_e32 v22, v22, v90
	v_mul_f32_e32 v23, v23, v91
	s_waitcnt lgkmcnt(0)
	v_mul_f32_e32 v18, v18, v94
	v_mul_f32_e32 v19, v19, v95
	v_mul_f32_e32 v28, v28, v80
	v_mul_f32_e32 v29, v29, v81
	v_mul_f32_e32 v24, v24, v84
	v_mul_f32_e32 v25, v25, v85
	v_mul_f32_e32 v20, v20, v88
	v_mul_f32_e32 v21, v21, v89
	v_mul_f32_e32 v16, v16, v92
	v_mul_f32_e32 v17, v17, v93
	v_mul_f32_e32 v14, v14, v82
	v_mul_f32_e32 v15, v15, v83
	v_mul_f32_e32 v10, v10, v86
	v_mul_f32_e32 v11, v11, v87
	v_mul_f32_e32 v6, v6, v90
	v_mul_f32_e32 v7, v7, v91
	v_mul_f32_e32 v2, v2, v94
	v_mul_f32_e32 v3, v3, v95
	v_mul_f32_e32 v12, v12, v80
	v_mul_f32_e32 v13, v13, v81
	v_mul_f32_e32 v8, v8, v84
	v_mul_f32_e32 v9, v9, v85
	v_mul_f32_e32 v4, v4, v88
	v_mul_f32_e32 v5, v5, v89
	v_mul_f32_e32 v0, v0, v92
	v_mul_f32_e32 v1, v1, v93
.LBB0_790:
	s_add_i32 s0, s1, 0x2000
	s_cmpk_lg_i32 s1, 0x4000
	s_cselect_b32 s71, s0, 0
	v_add_u32_e32 v198, s36, v229
	ds_read_b64_tr_b16 v[160:161], v198 offset:24576
	ds_read_b64_tr_b16 v[162:163], v198 offset:25088
	v_add_f32_e32 v80, v64, v65
	v_add_f32_e32 v80, v66, v80
	v_add_f32_e32 v80, v67, v80
	v_add_f32_e32 v80, v68, v80
	v_add_f32_e32 v100, v69, v80
	v_mfma_f32_32x32x16_bf16 v[80:95], v[96:99], v[128:131], v[32:47]
	v_cvt_pk_bf16_f32 v140, v64, v65
	v_cvt_pk_bf16_f32 v141, v66, v67
	ds_read_b64_tr_b16 v[156:157], v198 offset:28672
	ds_read_b64_tr_b16 v[158:159], v198 offset:29184
	v_add_f32_e32 v64, v70, v100
	v_add_f32_e32 v64, v71, v64
	v_add_f32_e32 v64, v72, v64
	v_add_f32_e32 v64, v73, v64
	v_cvt_pk_bf16_f32 v142, v68, v69
	v_cvt_pk_bf16_f32 v143, v70, v71
	v_mfma_f32_32x32x16_bf16 v[96:111], v[180:183], v[128:131], v[32:47]
	ds_read_b64_tr_b16 v[152:153], v198 offset:25600
	ds_read_b64_tr_b16 v[154:155], v198 offset:26112
	v_mfma_f32_32x32x16_bf16 v[80:95], v[184:187], v[120:123], v[80:95]
	v_add_f32_e32 v64, v74, v64
	v_add_f32_e32 v64, v75, v64
	v_add_f32_e32 v64, v76, v64
	v_add_f32_e32 v64, v77, v64
	v_cvt_pk_bf16_f32 v136, v72, v73
	v_cvt_pk_bf16_f32 v137, v74, v75
	ds_read_b64_tr_b16 v[148:149], v198 offset:29696
	ds_read_b64_tr_b16 v[150:151], v198 offset:30208
	v_add_f32_e32 v64, v78, v64
	v_add_f32_e32 v64, v79, v64
	v_add_f32_e32 v64, v48, v64
	v_add_f32_e32 v64, v49, v64
	v_cvt_pk_bf16_f32 v138, v76, v77
	v_cvt_pk_bf16_f32 v139, v78, v79
	v_mfma_f32_32x32x16_bf16 v[96:111], v[144:147], v[120:123], v[96:111]
	ds_read_b64_tr_b16 v[144:145], v198 offset:26624
	ds_read_b64_tr_b16 v[146:147], v198 offset:27136
	v_mfma_f32_32x32x16_bf16 v[80:95], v[176:179], v[116:119], v[80:95]
	v_add_f32_e32 v64, v50, v64
	v_add_f32_e32 v64, v51, v64
	v_add_f32_e32 v64, v52, v64
	v_add_f32_e32 v64, v53, v64
	v_cvt_pk_bf16_f32 v132, v48, v49
	v_cvt_pk_bf16_f32 v133, v50, v51
	ds_read_b64_tr_b16 v[184:185], v198 offset:30720
	ds_read_b64_tr_b16 v[186:187], v198 offset:31232
	v_add_f32_e32 v48, v54, v64
	v_add_f32_e32 v48, v55, v48
	v_add_f32_e32 v48, v56, v48
	v_add_f32_e32 v48, v57, v48
	v_cvt_pk_bf16_f32 v134, v52, v53
	v_cvt_pk_bf16_f32 v135, v54, v55
	v_mfma_f32_32x32x16_bf16 v[96:111], v[168:171], v[116:119], v[96:111]
	ds_read_b64_tr_b16 v[180:181], v198 offset:27648
	ds_read_b64_tr_b16 v[182:183], v198 offset:28160
	v_mfma_f32_32x32x16_bf16 v[80:95], v[172:175], v[112:115], v[80:95]
	v_add_f32_e32 v48, v58, v48
	v_add_f32_e32 v48, v59, v48
	v_add_f32_e32 v48, v60, v48
	v_add_f32_e32 v48, v61, v48
	v_cvt_pk_bf16_f32 v124, v56, v57
	v_cvt_pk_bf16_f32 v125, v58, v59
	ds_read_b64_tr_b16 v[176:177], v198 offset:31744
	ds_read_b64_tr_b16 v[178:179], v198 offset:32256
	v_add_f32_e32 v48, v62, v48
	v_add_f32_e32 v48, v63, v48
	v_add_f32_e32 v168, 0, v48
	v_cvt_pk_bf16_f32 v126, v60, v61
	v_cvt_pk_bf16_f32 v127, v62, v63
	v_mfma_f32_32x32x16_bf16 v[96:111], v[164:167], v[112:115], v[96:111]
	s_waitcnt lgkmcnt(8)
; #define WAIT_BAR(N) asm volatile("s_waitcnt vmcnt(" #N ") lgkmcnt(0)\n\ts_barrier":::"memory")
;   #define RESC() do{ if(resc){ asm volatile("s_waitcnt lgkmcnt(0)":::"memory"); \
;       _Pragma("unroll") for(int d_=0;d_<2;++d_) _Pragma("unroll") for(int r=0;r<16;++r)o[d_][r]*=wsf[crow(r,hi)]; } }while(0)
;   #define ROT() do{sl_prev=sl_cur;sl_cur=sl_next;sl_next=(sl_next==(NSLOT-1)*SLOTB)?0:sl_next+SLOTB;}while(0)
; template<int THRL> __device__ __forceinline__ void attn_unit(int b,int h,int qb,const bf16*Q,const bf16*__restrict__ K,const bf16*__restrict__ V,bf16*O,char*shm,int tid,const __attribute__((address_space(3))) float*nb){
;     ...
;   int t=1;
;     ...
;   for(;t+5<NT;t+=2){
;     STEP(pB0,pB1,pA0,pA1,t,true,true,true);     WAIT_BAR(2); RESC(); ROT();
;     STEP(pA0,pA1,pB0,pB1,t+1,true,true,true);   WAIT_BAR(2); RESC(); ROT();
	ds_read_b128 v[64:67], v196 offset:256
	ds_read_b128 v[68:71], v196 offset:288
	ds_read_b128 v[72:75], v196 offset:320
	ds_read_b128 v[76:79], v196 offset:352
	ds_read_b128 v[48:51], v196 offset:384
	ds_read_b128 v[52:55], v196 offset:416
	ds_read_b128 v[56:59], v196 offset:448
	ds_read_b128 v[60:63], v196 offset:480
	s_add_i32 s0, s1, s65
	s_mov_b32 m0, s0
	s_nop 0
	global_load_lds_dwordx4 v[194:195], off
	s_add_i32 s0, s71, s68
	s_mov_b32 m0, s0
	s_nop 0
	global_load_lds_dwordx4 v[192:193], off
	s_waitcnt lgkmcnt(4)
	v_add_f32_e32 v64, v80, v64
	v_add_f32_e32 v65, v81, v65
	v_add_f32_e32 v66, v82, v66
	v_add_f32_e32 v67, v83, v67
	v_add_f32_e32 v68, v84, v68
	v_add_f32_e32 v69, v85, v69
	v_add_f32_e32 v70, v86, v70
	v_add_f32_e32 v71, v87, v71
	v_add_f32_e32 v72, v88, v72
	v_add_f32_e32 v73, v89, v73
	v_add_f32_e32 v74, v90, v74
	v_add_f32_e32 v75, v91, v75
	v_add_f32_e32 v76, v92, v76
	v_add_f32_e32 v77, v93, v77
	v_add_f32_e32 v78, v94, v78
	v_add_f32_e32 v79, v95, v79
	s_waitcnt lgkmcnt(1)
	v_add_f32_e32 v48, v96, v48
	v_add_f32_e32 v49, v97, v49
	v_add_f32_e32 v50, v98, v50
	v_add_f32_e32 v51, v99, v51
	v_add_f32_e32 v52, v100, v52
	v_add_f32_e32 v53, v101, v53
	v_add_f32_e32 v54, v102, v54
	v_add_f32_e32 v55, v103, v55
	v_add_f32_e32 v56, v104, v56
	v_add_f32_e32 v57, v105, v57
	v_add_f32_e32 v58, v106, v58
	v_add_f32_e32 v59, v107, v59
	s_waitcnt lgkmcnt(0)
	v_add_f32_e32 v60, v108, v60
	v_add_f32_e32 v61, v109, v61
	v_add_f32_e32 v62, v110, v62
	v_add_f32_e32 v63, v111, v63
	v_max_f32_e32 v80, v64, v65
	v_max3_f32 v81, v66, v67, v49
	v_max3_f32 v80, v80, v48, v50
	v_max3_f32 v80, v80, v51, v68
	v_max3_f32 v81, v81, v70, v71
	v_max3_f32 v80, v80, v69, v52
	v_max3_f32 v81, v81, v54, v55
	v_max3_f32 v80, v80, v53, v72
	v_max3_f32 v81, v81, v74, v75
	v_max3_f32 v80, v80, v73, v56
	v_max3_f32 v81, v81, v58, v59
	v_max3_f32 v80, v80, v57, v76
	v_max3_f32 v81, v81, v78, v79
	v_max3_f32 v80, v80, v77, v60
	v_max3_f32 v81, v81, v62, v63
	v_max3_f32 v80, v80, v61, v81
	v_mov_b32_e32 v81, v80
	s_nop 1
	v_permlane32_swap_b32_e32 v80, v81
	v_max_f32_e32 v81, v81, v81
	v_max_f32_e32 v80, v80, v80
	v_max_f32_e32 v80, v80, v81
	v_cmp_lt_f32_e32 vcc, s61, v80
	s_cmp_lg_u64 vcc, 0
	v_add_f32_e32 v231, v197, v168
	s_cselect_b64 s[10:11], -1, 0
	s_cbranch_vccnz .LBB0_798
.LBB0_791:
	v_mfma_f32_32x32x16_bf16 v[16:31], v[140:143], v[160:163], v[16:31]
	v_exp_f32_e32 v64, v64
	v_exp_f32_e32 v65, v65
	v_exp_f32_e32 v66, v66
	v_exp_f32_e32 v67, v67
	v_mfma_f32_32x32x16_bf16 v[0:15], v[140:143], v[156:159], v[0:15]
	v_exp_f32_e32 v68, v68
	v_exp_f32_e32 v69, v69
	v_exp_f32_e32 v70, v70
	v_exp_f32_e32 v71, v71
	v_add_u32_e32 v80, s71, v228
	ds_read_b128 v[172:175], v80
	ds_read_b128 v[168:171], v80 offset:512
	v_mfma_f32_32x32x16_bf16 v[16:31], v[136:139], v[152:155], v[16:31]
	v_exp_f32_e32 v72, v72
	v_exp_f32_e32 v73, v73
	v_exp_f32_e32 v74, v74
	v_exp_f32_e32 v75, v75
	ds_read_b128 v[164:167], v80 offset:2048
	ds_read_b128 v[160:163], v80 offset:2560
	v_mfma_f32_32x32x16_bf16 v[0:15], v[136:139], v[148:151], v[0:15]
	v_exp_f32_e32 v76, v76
	v_exp_f32_e32 v77, v77
	v_exp_f32_e32 v78, v78
	v_exp_f32_e32 v79, v79
	ds_read_b128 v[156:159], v80 offset:4096
	ds_read_b128 v[152:155], v80 offset:4608
	v_mfma_f32_32x32x16_bf16 v[16:31], v[132:135], v[144:147], v[16:31]
	v_exp_f32_e32 v48, v48
	v_exp_f32_e32 v49, v49
	v_exp_f32_e32 v50, v50
	v_exp_f32_e32 v51, v51
	ds_read_b128 v[148:151], v80 offset:6144
	ds_read_b128 v[144:147], v80 offset:6656
	v_mfma_f32_32x32x16_bf16 v[0:15], v[132:135], v[184:187], v[0:15]
	v_exp_f32_e32 v52, v52
	v_exp_f32_e32 v53, v53
	v_exp_f32_e32 v54, v54
	v_exp_f32_e32 v55, v55
	v_mfma_f32_32x32x16_bf16 v[16:31], v[124:127], v[180:183], v[16:31]
	v_exp_f32_e32 v56, v56
	v_exp_f32_e32 v57, v57
	v_exp_f32_e32 v58, v58
	v_exp_f32_e32 v59, v59
	v_mfma_f32_32x32x16_bf16 v[0:15], v[124:127], v[176:179], v[0:15]
	v_exp_f32_e32 v60, v60
	v_exp_f32_e32 v61, v61
	v_exp_f32_e32 v62, v62
	v_exp_f32_e32 v63, v63
	s_waitcnt vmcnt(2) lgkmcnt(0)
	s_barrier
	s_andn2_b64 vcc, exec, s[10:11]
	s_cbranch_vccnz .LBB0_793
	s_waitcnt lgkmcnt(0)
	ds_read_b128 v[80:83], v223 offset:49248
	ds_read_b128 v[84:87], v223 offset:49216
	ds_read_b128 v[88:91], v223 offset:49184
	ds_read_b128 v[92:95], v223 offset:49152
	s_waitcnt lgkmcnt(3)
	v_mul_f32_e32 v30, v30, v82
	v_mul_f32_e32 v31, v31, v83
	s_waitcnt lgkmcnt(2)
	v_mul_f32_e32 v26, v26, v86
	v_mul_f32_e32 v27, v27, v87
	s_waitcnt lgkmcnt(1)
	v_mul_f32_e32 v22, v22, v90
	v_mul_f32_e32 v23, v23, v91
	s_waitcnt lgkmcnt(0)
	v_mul_f32_e32 v18, v18, v94
	v_mul_f32_e32 v19, v19, v95
	v_mul_f32_e32 v28, v28, v80
	v_mul_f32_e32 v29, v29, v81
	v_mul_f32_e32 v24, v24, v84
	v_mul_f32_e32 v25, v25, v85
	v_mul_f32_e32 v20, v20, v88
	v_mul_f32_e32 v21, v21, v89
	v_mul_f32_e32 v16, v16, v92
	v_mul_f32_e32 v17, v17, v93
	v_mul_f32_e32 v14, v14, v82
	v_mul_f32_e32 v15, v15, v83
	v_mul_f32_e32 v10, v10, v86
	v_mul_f32_e32 v11, v11, v87
	v_mul_f32_e32 v6, v6, v90
	v_mul_f32_e32 v7, v7, v91
	v_mul_f32_e32 v2, v2, v94
	v_mul_f32_e32 v3, v3, v95
	v_mul_f32_e32 v12, v12, v80
	v_mul_f32_e32 v13, v13, v81
	v_mul_f32_e32 v8, v8, v84
	v_mul_f32_e32 v9, v9, v85
	v_mul_f32_e32 v4, v4, v88
	v_mul_f32_e32 v5, v5, v89
	v_mul_f32_e32 v0, v0, v92
	v_mul_f32_e32 v1, v1, v93

; __device__ __forceinline__ void cmask(f32x16&p0,f32x16&p1,int jb,int qrel,int hi){
;   const float NEG=-INFINITY; int kb=64*jb+4*hi;
;   #pragma unroll
;   for(int r=0;r<16;++r){int kv=kb+(r&3)+8*(r>>2); if(kv>qrel)p0[r]=NEG; if(kv+32>qrel)p1[r]=NEG;}
; }
.LBB0_803:
	v_add_u32_e32 v98, s0, v229
	ds_read_b64_tr_b16 v[176:177], v98 offset:24576
	ds_read_b64_tr_b16 v[178:179], v98 offset:25088
	v_add_f32_e32 v80, v64, v65
	v_add_f32_e32 v80, v66, v80
	v_add_f32_e32 v80, v67, v80
	v_add_f32_e32 v80, v68, v80
	v_add_f32_e32 v96, v69, v80
	s_waitcnt lgkmcnt(3)
	v_mfma_f32_32x32x16_bf16 v[80:95], v[172:175], v[128:131], v[32:47]
	v_cvt_pk_bf16_f32 v140, v64, v65
	v_cvt_pk_bf16_f32 v141, v66, v67
	ds_read_b64_tr_b16 v[172:173], v98 offset:28672
	ds_read_b64_tr_b16 v[174:175], v98 offset:29184
	s_waitcnt lgkmcnt(4)
	v_mfma_f32_32x32x16_bf16 v[32:47], v[168:171], v[128:131], v[32:47]
	v_add_f32_e32 v64, v70, v96
	v_add_f32_e32 v64, v71, v64
	v_add_f32_e32 v64, v72, v64
	v_add_f32_e32 v64, v73, v64
	v_cvt_pk_bf16_f32 v142, v68, v69
	v_cvt_pk_bf16_f32 v143, v70, v71
	ds_read_b64_tr_b16 v[168:169], v98 offset:25600
	ds_read_b64_tr_b16 v[170:171], v98 offset:26112
	v_mfma_f32_32x32x16_bf16 v[80:95], v[164:167], v[120:123], v[80:95]
	v_add_f32_e32 v64, v74, v64
	v_add_f32_e32 v64, v75, v64
	v_add_f32_e32 v64, v76, v64
	v_add_f32_e32 v64, v77, v64
	v_cvt_pk_bf16_f32 v136, v72, v73
	v_cvt_pk_bf16_f32 v137, v74, v75
	ds_read_b64_tr_b16 v[128:129], v98 offset:29696
	ds_read_b64_tr_b16 v[130:131], v98 offset:30208
	v_mfma_f32_32x32x16_bf16 v[32:47], v[160:163], v[120:123], v[32:47]
	v_add_f32_e32 v64, v78, v64
	v_add_f32_e32 v64, v79, v64
	v_add_f32_e32 v64, v48, v64
	v_add_f32_e32 v64, v49, v64
	v_cvt_pk_bf16_f32 v138, v76, v77
	v_cvt_pk_bf16_f32 v139, v78, v79
	ds_read_b64_tr_b16 v[108:109], v98 offset:26624
	ds_read_b64_tr_b16 v[110:111], v98 offset:27136
	v_mfma_f32_32x32x16_bf16 v[80:95], v[156:159], v[116:119], v[80:95]
	v_add_f32_e32 v64, v50, v64
	v_add_f32_e32 v64, v51, v64
	v_add_f32_e32 v64, v52, v64
	v_add_f32_e32 v64, v53, v64
	v_cvt_pk_bf16_f32 v132, v48, v49
	v_cvt_pk_bf16_f32 v133, v50, v51
	ds_read_b64_tr_b16 v[104:105], v98 offset:30720
	ds_read_b64_tr_b16 v[106:107], v98 offset:31232
	v_mfma_f32_32x32x16_bf16 v[32:47], v[152:155], v[116:119], v[32:47]
	v_add_f32_e32 v48, v54, v64
	v_add_f32_e32 v48, v55, v48
	v_add_f32_e32 v48, v56, v48
	v_add_f32_e32 v48, v57, v48
	v_cvt_pk_bf16_f32 v134, v52, v53
	v_cvt_pk_bf16_f32 v135, v54, v55
	ds_read_b64_tr_b16 v[100:101], v98 offset:27648
	ds_read_b64_tr_b16 v[102:103], v98 offset:28160
	v_mfma_f32_32x32x16_bf16 v[80:95], v[148:151], v[112:115], v[80:95]
	v_add_f32_e32 v48, v58, v48
	v_add_f32_e32 v48, v59, v48
	v_add_f32_e32 v48, v60, v48
	v_add_f32_e32 v48, v61, v48
	v_cvt_pk_bf16_f32 v124, v56, v57
	v_cvt_pk_bf16_f32 v125, v58, v59
	ds_read_b64_tr_b16 v[96:97], v98 offset:31744
	ds_read_b64_tr_b16 v[98:99], v98 offset:32256
	v_mfma_f32_32x32x16_bf16 v[32:47], v[144:147], v[112:115], v[32:47]
	v_add_f32_e32 v48, v62, v48
	v_add_f32_e32 v48, v63, v48
	v_add_f32_e32 v116, 0, v48
	v_cvt_pk_bf16_f32 v126, v60, v61
	v_cvt_pk_bf16_f32 v127, v62, v63
	s_lshl_b32 s0, s69, 2
	s_add_i32 s0, s0, 0
	s_add_i32 s0, s0, 0x15000
	v_lshl_add_u32 v48, v225, 2, s0
	v_add_u32_e32 v76, 0xffffff00, v48
	ds_read_b128 v[48:51], v76
	ds_read_b128 v[52:55], v76 offset:128
	ds_read_b128 v[56:59], v76 offset:32
	ds_read_b128 v[60:63], v76 offset:160
	ds_read_b128 v[64:67], v76 offset:64
	ds_read_b128 v[68:71], v76 offset:192
	ds_read_b128 v[72:75], v76 offset:96
	ds_read_b128 v[76:79], v76 offset:224
	s_waitcnt lgkmcnt(7)
	v_add_f32_e32 v50, v82, v50
	v_add_f32_e32 v51, v83, v51
	s_waitcnt lgkmcnt(5)
	v_add_f32_e32 v56, v84, v56
	v_add_f32_e32 v57, v85, v57
	v_add_f32_e32 v58, v86, v58
	v_add_f32_e32 v59, v87, v59
	s_waitcnt lgkmcnt(3)
	v_add_f32_e32 v64, v88, v64
	v_add_f32_e32 v65, v89, v65
	v_add_f32_e32 v48, v80, v48
	v_add_f32_e32 v49, v81, v49
	v_add_f32_e32 v34, v34, v54
	v_add_f32_e32 v35, v35, v55
	v_add_f32_e32 v36, v36, v60
	v_add_f32_e32 v37, v37, v61
	v_add_f32_e32 v38, v38, v62
	v_add_f32_e32 v39, v39, v63
	s_waitcnt lgkmcnt(2)
	v_add_f32_e32 v40, v40, v68
	v_add_f32_e32 v41, v41, v69
	v_add_f32_e32 v42, v42, v70
	v_add_f32_e32 v43, v43, v71
	s_waitcnt lgkmcnt(0)
	v_add_f32_e32 v44, v44, v76
	v_add_f32_e32 v45, v45, v77
	v_add_f32_e32 v46, v46, v78
	v_add_f32_e32 v47, v47, v79
	v_add_f32_e32 v32, v32, v52
	v_add_f32_e32 v33, v33, v53
	v_add_f32_e32 v66, v90, v66
	v_add_f32_e32 v67, v91, v67
	v_add_f32_e32 v72, v92, v72
	v_add_f32_e32 v73, v93, v73
	v_add_f32_e32 v74, v94, v74
	v_add_f32_e32 v75, v95, v75
	v_or_b32_e32 v53, 0xe0, v225
	v_or_b32_e32 v52, 0xc0, v225
	v_cmp_le_i32_e32 vcc, v53, v226
	v_or_b32_e32 v53, 0xe8, v225
	v_or_b32_e32 v54, 0xe9, v225
	v_cndmask_b32_e32 v32, v216, v32, vcc
	v_cmp_lt_i32_e32 vcc, v52, v226
	v_or_b32_e32 v55, 0xea, v225
	v_or_b32_e32 v60, 0xf3, v225
	v_cndmask_b32_e32 v49, v216, v49, vcc
	v_cmp_le_i32_e32 vcc, v52, v226
	v_or_b32_e32 v52, 0xe1, v225
	v_or_b32_e32 v61, 0xf8, v225
	v_cndmask_b32_e32 v48, v216, v48, vcc
	v_cmp_le_i32_e32 vcc, v52, v226
	v_or_b32_e32 v52, 0xc2, v225
	v_or_b32_e32 v62, 0xf9, v225
	v_cndmask_b32_e32 v33, v216, v33, vcc
	v_cmp_le_i32_e32 vcc, v52, v226
	v_or_b32_e32 v52, 0xe2, v225
	v_or_b32_e32 v63, 0xfa, v225
	v_cndmask_b32_e32 v50, v216, v50, vcc
	v_cmp_le_i32_e32 vcc, v52, v226
	v_or_b32_e32 v52, 0xc3, v225
	v_add_f32_e32 v80, v231, v116
	v_cndmask_b32_e32 v34, v216, v34, vcc
	v_cmp_le_i32_e32 vcc, v52, v226
	v_or_b32_e32 v52, 0xe3, v225
	s_nop 0
	v_cndmask_b32_e32 v51, v216, v51, vcc
	v_cmp_le_i32_e32 vcc, v52, v226
	v_or_b32_e32 v52, 0xc8, v225
	s_nop 0
	v_cndmask_b32_e32 v35, v216, v35, vcc
	v_cmp_le_i32_e32 vcc, v52, v226
	s_nop 1
	v_cndmask_b32_e32 v52, v216, v56, vcc
	v_cmp_le_i32_e32 vcc, v53, v226
	v_or_b32_e32 v53, 0xc9, v225
	v_or_b32_e32 v56, 0xeb, v225
	v_cndmask_b32_e32 v36, v216, v36, vcc
	v_cmp_le_i32_e32 vcc, v53, v226
	s_nop 1
	v_cndmask_b32_e32 v53, v216, v57, vcc
	v_cmp_le_i32_e32 vcc, v54, v226
	v_or_b32_e32 v54, 0xca, v225
	v_or_b32_e32 v57, 0xf0, v225
	v_cndmask_b32_e32 v37, v216, v37, vcc
	v_cmp_le_i32_e32 vcc, v54, v226
	s_nop 1
	v_cndmask_b32_e32 v54, v216, v58, vcc
	v_cmp_le_i32_e32 vcc, v55, v226
	v_or_b32_e32 v55, 0xcb, v225
	v_or_b32_e32 v58, 0xf1, v225
	v_cndmask_b32_e32 v38, v216, v38, vcc
	v_cmp_le_i32_e32 vcc, v55, v226
	s_nop 1
	v_cndmask_b32_e32 v55, v216, v59, vcc
	v_cmp_le_i32_e32 vcc, v56, v226
	v_or_b32_e32 v56, 0xd0, v225
	v_or_b32_e32 v59, 0xf2, v225
	v_cndmask_b32_e32 v39, v216, v39, vcc
	v_cmp_le_i32_e32 vcc, v56, v226
	s_nop 1
	v_cndmask_b32_e32 v56, v216, v64, vcc
	v_cmp_le_i32_e32 vcc, v57, v226
	v_or_b32_e32 v57, 0xd1, v225
	v_or_b32_e32 v64, 0xfb, v225
	v_cndmask_b32_e32 v40, v216, v40, vcc
	v_cmp_le_i32_e32 vcc, v57, v226
	s_nop 1
	v_cndmask_b32_e32 v57, v216, v65, vcc
	v_cmp_le_i32_e32 vcc, v58, v226
	v_or_b32_e32 v58, 0xd2, v225
	v_max3_f32 v65, v50, v51, v33
	v_cndmask_b32_e32 v41, v216, v41, vcc
	v_cmp_le_i32_e32 vcc, v58, v226
	v_max3_f32 v65, v65, v54, v55
	v_max3_f32 v65, v65, v38, v39
	v_cndmask_b32_e32 v58, v216, v66, vcc
	v_cmp_le_i32_e32 vcc, v59, v226
	v_or_b32_e32 v59, 0xd3, v225
	s_nop 0
	v_cndmask_b32_e32 v42, v216, v42, vcc
	v_cmp_le_i32_e32 vcc, v59, v226
	s_nop 1
	v_cndmask_b32_e32 v59, v216, v67, vcc
	v_cmp_le_i32_e32 vcc, v60, v226
	v_or_b32_e32 v60, 0xd8, v225
	v_max3_f32 v65, v65, v58, v59
	v_cndmask_b32_e32 v43, v216, v43, vcc
	v_cmp_le_i32_e32 vcc, v60, v226
	v_max3_f32 v65, v65, v42, v43
	s_nop 0
	v_cndmask_b32_e32 v60, v216, v72, vcc
	v_cmp_le_i32_e32 vcc, v61, v226
	v_or_b32_e32 v61, 0xd9, v225
	s_nop 0
	v_cndmask_b32_e32 v44, v216, v44, vcc
	v_cmp_le_i32_e32 vcc, v61, v226
	s_nop 1
	v_cndmask_b32_e32 v61, v216, v73, vcc
	v_cmp_le_i32_e32 vcc, v62, v226
	v_or_b32_e32 v62, 0xda, v225
	s_nop 0
	v_cndmask_b32_e32 v45, v216, v45, vcc
	v_cmp_le_i32_e32 vcc, v62, v226
	s_nop 1
	v_cndmask_b32_e32 v62, v216, v74, vcc
	v_cmp_le_i32_e32 vcc, v63, v226
	v_or_b32_e32 v63, 0xdb, v225
	s_nop 0
	v_cndmask_b32_e32 v46, v216, v46, vcc
	v_cmp_le_i32_e32 vcc, v63, v226
	s_nop 1
	v_cndmask_b32_e32 v63, v216, v75, vcc
	v_cmp_le_i32_e32 vcc, v64, v226
	v_max_f32_e32 v64, v48, v49
	v_max3_f32 v64, v64, v32, v34
	v_max3_f32 v64, v64, v35, v52
	v_max3_f32 v64, v64, v53, v36
	v_max3_f32 v64, v64, v37, v56
	v_max3_f32 v64, v64, v57, v40
	v_cndmask_b32_e32 v47, v216, v47, vcc
	v_max3_f32 v64, v64, v41, v60
	v_max3_f32 v65, v65, v62, v63
	v_max3_f32 v64, v64, v61, v44
	v_max3_f32 v65, v65, v46, v47
	v_max3_f32 v64, v64, v45, v65
	v_mov_b32_e32 v65, v64
	s_nop 1
	v_permlane32_swap_b32_e32 v64, v65
	v_max_f32_e32 v65, v65, v65
	v_max_f32_e32 v64, v64, v64
	v_max_f32_e32 v64, v64, v65
	v_cmp_lt_f32_e32 vcc, s61, v64
	s_cmp_lg_u64 vcc, 0
	s_cselect_b64 s[8:9], -1, 0
	s_cbranch_vccnz .LBB0_858
.LBB0_804:
	v_mfma_f32_32x32x16_bf16 v[16:31], v[140:143], v[176:179], v[16:31]
	v_exp_f32_e32 v48, v48
	v_exp_f32_e32 v49, v49
	v_exp_f32_e32 v50, v50
	v_exp_f32_e32 v51, v51
	v_mfma_f32_32x32x16_bf16 v[0:15], v[140:143], v[172:175], v[0:15]
	v_exp_f32_e32 v52, v52
	v_exp_f32_e32 v53, v53
	v_exp_f32_e32 v54, v54
	v_exp_f32_e32 v55, v55
	v_mfma_f32_32x32x16_bf16 v[16:31], v[136:139], v[168:171], v[16:31]
	v_exp_f32_e32 v56, v56
	v_exp_f32_e32 v57, v57
	v_exp_f32_e32 v58, v58
	v_exp_f32_e32 v59, v59
	v_mfma_f32_32x32x16_bf16 v[0:15], v[136:139], v[128:131], v[0:15]
	v_exp_f32_e32 v60, v60
	v_exp_f32_e32 v61, v61
	v_exp_f32_e32 v62, v62
	v_exp_f32_e32 v63, v63
	v_mfma_f32_32x32x16_bf16 v[16:31], v[132:135], v[108:111], v[16:31]
	v_exp_f32_e32 v32, v32
	v_exp_f32_e32 v33, v33
	v_exp_f32_e32 v34, v34
	v_exp_f32_e32 v35, v35
	v_mfma_f32_32x32x16_bf16 v[0:15], v[132:135], v[104:107], v[0:15]
	v_exp_f32_e32 v36, v36
	v_exp_f32_e32 v37, v37
	v_exp_f32_e32 v38, v38
	v_exp_f32_e32 v39, v39
	v_mfma_f32_32x32x16_bf16 v[16:31], v[124:127], v[100:103], v[16:31]
	v_exp_f32_e32 v40, v40
	v_exp_f32_e32 v41, v41
	v_exp_f32_e32 v42, v42
	v_exp_f32_e32 v43, v43
	v_mfma_f32_32x32x16_bf16 v[0:15], v[124:127], v[96:99], v[0:15]
	v_exp_f32_e32 v44, v44
	v_exp_f32_e32 v45, v45
	v_exp_f32_e32 v46, v46
	v_exp_f32_e32 v47, v47
	s_andn2_b64 vcc, exec, s[8:9]
	s_cbranch_vccnz .LBB0_806
	s_waitcnt lgkmcnt(0)
	ds_read_b128 v[64:67], v223 offset:49248
	ds_read_b128 v[68:71], v223 offset:49216
	ds_read_b128 v[72:75], v223 offset:49184
	ds_read_b128 v[76:79], v223 offset:49152
	s_waitcnt lgkmcnt(3)
	v_mul_f32_e32 v30, v30, v66
	v_mul_f32_e32 v31, v31, v67
	s_waitcnt lgkmcnt(2)
	v_mul_f32_e32 v26, v26, v70
	v_mul_f32_e32 v27, v27, v71
	s_waitcnt lgkmcnt(1)
	v_mul_f32_e32 v22, v22, v74
	v_mul_f32_e32 v23, v23, v75
	s_waitcnt lgkmcnt(0)
	v_mul_f32_e32 v18, v18, v78
	v_mul_f32_e32 v19, v19, v79
	v_mul_f32_e32 v28, v28, v64
	v_mul_f32_e32 v29, v29, v65
	v_mul_f32_e32 v24, v24, v68
	v_mul_f32_e32 v25, v25, v69
	v_mul_f32_e32 v20, v20, v72
	v_mul_f32_e32 v21, v21, v73
	v_mul_f32_e32 v16, v16, v76
	v_mul_f32_e32 v17, v17, v77
	v_mul_f32_e32 v14, v14, v66
	v_mul_f32_e32 v15, v15, v67
	v_mul_f32_e32 v10, v10, v70
	v_mul_f32_e32 v11, v11, v71
	v_mul_f32_e32 v6, v6, v74
	v_mul_f32_e32 v7, v7, v75
	v_mul_f32_e32 v2, v2, v78
	v_mul_f32_e32 v3, v3, v79
	v_mul_f32_e32 v12, v12, v64
	v_mul_f32_e32 v13, v13, v65
	v_mul_f32_e32 v8, v8, v68
	v_mul_f32_e32 v9, v9, v69
	v_mul_f32_e32 v4, v4, v72
	v_mul_f32_e32 v5, v5, v73
	v_mul_f32_e32 v0, v0, v76
	v_mul_f32_e32 v1, v1, v77

; __device__ __forceinline__ void cmask(f32x16&p0,f32x16&p1,int jb,int qrel,int hi){
;   const float NEG=-INFINITY; int kb=64*jb+4*hi;
;   #pragma unroll
;   for(int r=0;r<16;++r){int kv=kb+(r&3)+8*(r>>2); if(kv>qrel)p0[r]=NEG; if(kv+32>qrel)p1[r]=NEG;}
; }
.LBB0_812:
	s_add_i32 s1, s0, s68
	s_mov_b32 m0, s1
	s_nop 0
	global_load_lds_dwordx4 v[210:211], off
	ds_read_b128 v[48:51], v233
	ds_read_b128 v[52:55], v233 offset:128
	ds_read_b128 v[56:59], v233 offset:32
	ds_read_b128 v[60:63], v233 offset:160
	ds_read_b128 v[72:75], v233 offset:64
	ds_read_b128 v[144:147], v233 offset:192
	ds_read_b128 v[76:79], v233 offset:96
	ds_read_b128 v[150:153], v233 offset:224
	s_waitcnt lgkmcnt(7)
	v_add_f32_e32 v66, v98, v50
	v_add_f32_e32 v67, v99, v51
	s_waitcnt lgkmcnt(5)
	v_add_f32_e32 v70, v102, v58
	v_add_f32_e32 v71, v103, v59
	s_waitcnt lgkmcnt(3)
	v_add_f32_e32 v74, v106, v74
	v_add_f32_e32 v75, v107, v75
	s_waitcnt lgkmcnt(1)
	v_add_f32_e32 v78, v110, v78
	v_add_f32_e32 v79, v111, v79
	v_add_f32_e32 v64, v96, v48
	v_add_f32_e32 v65, v97, v49
	v_add_f32_e32 v68, v100, v56
	v_add_f32_e32 v69, v101, v57
	v_add_f32_e32 v72, v104, v72
	v_add_f32_e32 v73, v105, v73
	v_add_f32_e32 v76, v108, v76
	v_add_f32_e32 v77, v109, v77
	v_add_f32_e32 v50, v82, v54
	v_add_f32_e32 v51, v83, v55
	v_add_f32_e32 v54, v86, v62
	v_add_f32_e32 v55, v87, v63
	v_add_f32_e32 v58, v90, v146
	v_add_f32_e32 v59, v91, v147
	s_waitcnt lgkmcnt(0)
	v_add_f32_e32 v62, v94, v152
	v_add_f32_e32 v63, v95, v153
	v_add_f32_e32 v48, v80, v52
	v_add_f32_e32 v49, v81, v53
	v_add_f32_e32 v52, v84, v60
	v_add_f32_e32 v53, v85, v61
	v_add_f32_e32 v56, v88, v144
	v_add_f32_e32 v57, v89, v145
	v_add_f32_e32 v60, v92, v150
	v_add_f32_e32 v61, v93, v151
	s_add_i32 s1, s38, s39
	s_add_i32 s10, s1, -2
	s_cmp_lt_i32 s10, 0
	s_cbranch_scc1 .LBB0_814
	v_add_u32_e32 v81, 0xffffffa5, v232
	v_add_u32_e32 v80, 0xffffff85, v232
	v_cmp_le_i32_e32 vcc, v81, v226
	s_nop 1
	v_cndmask_b32_e32 v48, v216, v48, vcc
	v_cmp_lt_i32_e32 vcc, v80, v226
	s_nop 1
	v_cndmask_b32_e32 v65, v216, v65, vcc
	v_cmp_le_i32_e32 vcc, v80, v226
	v_add_u32_e32 v80, 0xffffffa6, v232
	s_nop 0
	v_cndmask_b32_e32 v64, v216, v64, vcc
	v_cmp_le_i32_e32 vcc, v80, v226
	v_add_u32_e32 v80, 0xffffff87, v232
	s_nop 0
	v_cndmask_b32_e32 v49, v216, v49, vcc
	v_cmp_le_i32_e32 vcc, v80, v226
	v_add_u32_e32 v80, 0xffffffa7, v232
	s_nop 0
	v_cndmask_b32_e32 v66, v216, v66, vcc
	v_cmp_le_i32_e32 vcc, v80, v226
	v_add_u32_e32 v80, 0xffffff88, v232
	s_nop 0
	v_cndmask_b32_e32 v50, v216, v50, vcc
	v_cmp_le_i32_e32 vcc, v80, v226
	v_add_u32_e32 v80, 0xffffffa8, v232
	s_nop 0
	v_cndmask_b32_e32 v67, v216, v67, vcc
	v_cmp_le_i32_e32 vcc, v80, v226
	v_add_u32_e32 v80, 0xffffff8d, v232
	s_nop 0
	v_cndmask_b32_e32 v51, v216, v51, vcc
	v_cmp_le_i32_e32 vcc, v80, v226
	v_add_u32_e32 v80, 0xffffffad, v232
	s_nop 0
	v_cndmask_b32_e32 v68, v216, v68, vcc
	v_cmp_le_i32_e32 vcc, v80, v226
	v_add_u32_e32 v80, 0xffffff8e, v232
	s_nop 0
	v_cndmask_b32_e32 v52, v216, v52, vcc
	v_cmp_le_i32_e32 vcc, v80, v226
	v_add_u32_e32 v80, 0xffffffae, v232
	s_nop 0
	v_cndmask_b32_e32 v69, v216, v69, vcc
	v_cmp_le_i32_e32 vcc, v80, v226
	v_add_u32_e32 v80, 0xffffff8f, v232
	s_nop 0
	v_cndmask_b32_e32 v53, v216, v53, vcc
	v_cmp_le_i32_e32 vcc, v80, v226
	v_add_u32_e32 v80, 0xffffffaf, v232
	s_nop 0
	v_cndmask_b32_e32 v70, v216, v70, vcc
	v_cmp_le_i32_e32 vcc, v80, v226
	v_add_u32_e32 v80, 0xffffff90, v232
	s_nop 0
	v_cndmask_b32_e32 v54, v216, v54, vcc
	v_cmp_le_i32_e32 vcc, v80, v226
	v_add_u32_e32 v80, 0xffffffb0, v232
	s_nop 0
	v_cndmask_b32_e32 v71, v216, v71, vcc
	v_cmp_le_i32_e32 vcc, v80, v226
	v_add_u32_e32 v80, 0xffffff95, v232
	s_nop 0
	v_cndmask_b32_e32 v55, v216, v55, vcc
	v_cmp_le_i32_e32 vcc, v80, v226
	v_add_u32_e32 v80, 0xffffffb5, v232
	s_nop 0
	v_cndmask_b32_e32 v72, v216, v72, vcc
	v_cmp_le_i32_e32 vcc, v80, v226
	v_add_u32_e32 v80, 0xffffff96, v232
	s_nop 0
	v_cndmask_b32_e32 v56, v216, v56, vcc
	v_cmp_le_i32_e32 vcc, v80, v226
	v_add_u32_e32 v80, 0xffffffb6, v232
	s_nop 0
	v_cndmask_b32_e32 v73, v216, v73, vcc
	v_cmp_le_i32_e32 vcc, v80, v226
	v_add_u32_e32 v80, 0xffffff97, v232
	s_nop 0
	v_cndmask_b32_e32 v57, v216, v57, vcc
	v_cmp_le_i32_e32 vcc, v80, v226
	v_add_u32_e32 v80, 0xffffffb7, v232
	s_nop 0
	v_cndmask_b32_e32 v74, v216, v74, vcc
	v_cmp_le_i32_e32 vcc, v80, v226
	v_add_u32_e32 v80, 0xffffff98, v232
	s_nop 0
	v_cndmask_b32_e32 v58, v216, v58, vcc
	v_cmp_le_i32_e32 vcc, v80, v226
	v_add_u32_e32 v80, 0xffffffb8, v232
	s_nop 0
	v_cndmask_b32_e32 v75, v216, v75, vcc
	v_cmp_le_i32_e32 vcc, v80, v226
	v_add_u32_e32 v80, 0xffffff9d, v232
	s_nop 0
	v_cndmask_b32_e32 v59, v216, v59, vcc
	v_cmp_le_i32_e32 vcc, v80, v226
	v_add_u32_e32 v80, 0xffffffbd, v232
	s_nop 0
	v_cndmask_b32_e32 v76, v216, v76, vcc
	v_cmp_le_i32_e32 vcc, v80, v226
	v_add_u32_e32 v80, 0xffffff9e, v232
	s_nop 0
	v_cndmask_b32_e32 v60, v216, v60, vcc
	v_cmp_le_i32_e32 vcc, v80, v226
	v_add_u32_e32 v80, 0xffffffbe, v232
	s_nop 0
	v_cndmask_b32_e32 v77, v216, v77, vcc
	v_cmp_le_i32_e32 vcc, v80, v226
	v_add_u32_e32 v80, 0xffffff9f, v232
	s_nop 0
	v_cndmask_b32_e32 v61, v216, v61, vcc
	v_cmp_le_i32_e32 vcc, v80, v226
	v_add_u32_e32 v80, 0xffffffbf, v232
	s_nop 0
	v_cndmask_b32_e32 v78, v216, v78, vcc
	v_cmp_le_i32_e32 vcc, v80, v226
	v_add_u32_e32 v80, 0xffffffa0, v232
	s_nop 0
	v_cndmask_b32_e32 v62, v216, v62, vcc
	v_cmp_le_i32_e32 vcc, v80, v226
	v_subrev_u32_e32 v80, 64, v232
	s_nop 0
	v_cndmask_b32_e32 v79, v216, v79, vcc
	v_cmp_le_i32_e32 vcc, v80, v226
	s_nop 1
	v_cndmask_b32_e32 v63, v216, v63, vcc

.LBB0_818:
	s_waitcnt lgkmcnt(0)
	ds_read_b128 v[80:83], v223 offset:49248
	ds_read_b128 v[84:87], v223 offset:49216
	ds_read_b128 v[88:91], v223 offset:49184
	ds_read_b128 v[92:95], v223 offset:49152
	s_waitcnt lgkmcnt(3)
	v_mul_f32_e32 v30, v30, v82
	v_mul_f32_e32 v31, v31, v83
	s_waitcnt lgkmcnt(2)
	v_mul_f32_e32 v26, v26, v86
	v_mul_f32_e32 v27, v27, v87
	s_waitcnt lgkmcnt(1)
	v_mul_f32_e32 v22, v22, v90
	v_mul_f32_e32 v23, v23, v91
	s_waitcnt lgkmcnt(0)
	v_mul_f32_e32 v18, v18, v94
	v_mul_f32_e32 v19, v19, v95
	v_mul_f32_e32 v28, v28, v80
	v_mul_f32_e32 v29, v29, v81
	v_mul_f32_e32 v24, v24, v84
	v_mul_f32_e32 v25, v25, v85
	v_mul_f32_e32 v20, v20, v88
	v_mul_f32_e32 v21, v21, v89
	v_mul_f32_e32 v16, v16, v92
	v_mul_f32_e32 v17, v17, v93
	v_mul_f32_e32 v14, v14, v82
	v_mul_f32_e32 v15, v15, v83
	v_mul_f32_e32 v10, v10, v86
	v_mul_f32_e32 v11, v11, v87
	v_mul_f32_e32 v6, v6, v90
	v_mul_f32_e32 v7, v7, v91
	v_mul_f32_e32 v2, v2, v94
	v_mul_f32_e32 v3, v3, v95
	v_mul_f32_e32 v12, v12, v80
	v_mul_f32_e32 v13, v13, v81
	v_mul_f32_e32 v8, v8, v84
	v_mul_f32_e32 v9, v9, v85
	v_mul_f32_e32 v4, v4, v88
	v_mul_f32_e32 v5, v5, v89
	v_mul_f32_e32 v0, v0, v92
	v_mul_f32_e32 v1, v1, v93

; __device__ __forceinline__ void cmask(f32x16&p0,f32x16&p1,int jb,int qrel,int hi){
;   const float NEG=-INFINITY; int kb=64*jb+4*hi;
;   #pragma unroll
;   for(int r=0;r<16;++r){int kv=kb+(r&3)+8*(r>>2); if(kv>qrel)p0[r]=NEG; if(kv+32>qrel)p1[r]=NEG;}
; }
.LBB0_823:
	ds_read_b128 v[48:51], v233 offset:256
	ds_read_b128 v[52:55], v233 offset:384
	ds_read_b128 v[56:59], v233 offset:288
	ds_read_b128 v[60:63], v233 offset:416
	ds_read_b128 v[72:75], v233 offset:320
	ds_read_b128 v[236:239], v233 offset:448
	ds_read_b128 v[76:79], v233 offset:352
	ds_read_b128 v[240:243], v233 offset:480
	s_waitcnt lgkmcnt(7)
	v_add_f32_e32 v66, v98, v50
	v_add_f32_e32 v67, v99, v51
	s_waitcnt lgkmcnt(5)
	v_add_f32_e32 v70, v102, v58
	v_add_f32_e32 v71, v103, v59
	s_waitcnt lgkmcnt(3)
	v_add_f32_e32 v74, v106, v74
	v_add_f32_e32 v75, v107, v75
	s_waitcnt lgkmcnt(1)
	v_add_f32_e32 v78, v110, v78
	v_add_f32_e32 v79, v111, v79
	v_add_f32_e32 v64, v96, v48
	v_add_f32_e32 v65, v97, v49
	v_add_f32_e32 v68, v100, v56
	v_add_f32_e32 v69, v101, v57
	v_add_f32_e32 v72, v104, v72
	v_add_f32_e32 v73, v105, v73
	v_add_f32_e32 v76, v108, v76
	v_add_f32_e32 v77, v109, v77
	v_add_f32_e32 v50, v82, v54
	v_add_f32_e32 v51, v83, v55
	v_add_f32_e32 v54, v86, v62
	v_add_f32_e32 v55, v87, v63
	v_add_f32_e32 v58, v90, v238
	v_add_f32_e32 v59, v91, v239
	s_waitcnt lgkmcnt(0)
	v_add_f32_e32 v62, v94, v242
	v_add_f32_e32 v63, v95, v243
	v_add_f32_e32 v48, v80, v52
	v_add_f32_e32 v49, v81, v53
	v_add_f32_e32 v52, v84, v60
	v_add_f32_e32 v53, v85, v61
	v_add_f32_e32 v56, v88, v236
	v_add_f32_e32 v57, v89, v237
	v_add_f32_e32 v60, v92, v240
	v_add_f32_e32 v61, v93, v241
	s_add_i32 s1, s1, -1
	s_cmp_lt_i32 s1, 0
	s_cbranch_scc1 .LBB0_825
	v_subrev_u32_e32 v81, 27, v232
	v_subrev_u32_e32 v80, 59, v232
	v_cmp_le_i32_e32 vcc, v81, v226
	s_nop 1
	v_cndmask_b32_e32 v48, v216, v48, vcc
	v_cmp_lt_i32_e32 vcc, v80, v226
	s_nop 1
	v_cndmask_b32_e32 v65, v216, v65, vcc
	v_cmp_le_i32_e32 vcc, v80, v226
	v_subrev_u32_e32 v80, 26, v232
	s_nop 0
	v_cndmask_b32_e32 v64, v216, v64, vcc
	v_cmp_le_i32_e32 vcc, v80, v226
	v_subrev_u32_e32 v80, 57, v232
	s_nop 0
	v_cndmask_b32_e32 v49, v216, v49, vcc
	v_cmp_le_i32_e32 vcc, v80, v226
	v_subrev_u32_e32 v80, 25, v232
	s_nop 0
	v_cndmask_b32_e32 v66, v216, v66, vcc
	v_cmp_le_i32_e32 vcc, v80, v226
	v_subrev_u32_e32 v80, 56, v232
	s_nop 0
	v_cndmask_b32_e32 v50, v216, v50, vcc
	v_cmp_le_i32_e32 vcc, v80, v226
	v_subrev_u32_e32 v80, 24, v232
	s_nop 0
	v_cndmask_b32_e32 v67, v216, v67, vcc
	v_cmp_le_i32_e32 vcc, v80, v226
	v_subrev_u32_e32 v80, 51, v232
	s_nop 0
	v_cndmask_b32_e32 v51, v216, v51, vcc
	v_cmp_le_i32_e32 vcc, v80, v226
	v_subrev_u32_e32 v80, 19, v232
	s_nop 0
	v_cndmask_b32_e32 v68, v216, v68, vcc
	v_cmp_le_i32_e32 vcc, v80, v226
	v_subrev_u32_e32 v80, 50, v232
	s_nop 0
	v_cndmask_b32_e32 v52, v216, v52, vcc
	v_cmp_le_i32_e32 vcc, v80, v226
	v_subrev_u32_e32 v80, 18, v232
	s_nop 0
	v_cndmask_b32_e32 v69, v216, v69, vcc
	v_cmp_le_i32_e32 vcc, v80, v226
	v_subrev_u32_e32 v80, 49, v232
	s_nop 0
	v_cndmask_b32_e32 v53, v216, v53, vcc
	v_cmp_le_i32_e32 vcc, v80, v226
	v_subrev_u32_e32 v80, 17, v232
	s_nop 0
	v_cndmask_b32_e32 v70, v216, v70, vcc
	v_cmp_le_i32_e32 vcc, v80, v226
	v_subrev_u32_e32 v80, 48, v232
	s_nop 0
	v_cndmask_b32_e32 v54, v216, v54, vcc
	v_cmp_le_i32_e32 vcc, v80, v226
	v_add_u32_e32 v80, -16, v232
	s_nop 0
	v_cndmask_b32_e32 v71, v216, v71, vcc
	v_cmp_le_i32_e32 vcc, v80, v226
	v_subrev_u32_e32 v80, 43, v232
	s_nop 0
	v_cndmask_b32_e32 v55, v216, v55, vcc
	v_cmp_le_i32_e32 vcc, v80, v226
	v_add_u32_e32 v80, -11, v232
	s_nop 0
	v_cndmask_b32_e32 v72, v216, v72, vcc
	v_cmp_le_i32_e32 vcc, v80, v226
	v_subrev_u32_e32 v80, 42, v232
	s_nop 0
	v_cndmask_b32_e32 v56, v216, v56, vcc
	v_cmp_le_i32_e32 vcc, v80, v226
	v_add_u32_e32 v80, -10, v232
	s_nop 0
	v_cndmask_b32_e32 v73, v216, v73, vcc
	v_cmp_le_i32_e32 vcc, v80, v226
	v_subrev_u32_e32 v80, 41, v232
	s_nop 0
	v_cndmask_b32_e32 v57, v216, v57, vcc
	v_cmp_le_i32_e32 vcc, v80, v226
	v_add_u32_e32 v80, -9, v232
	s_nop 0
	v_cndmask_b32_e32 v74, v216, v74, vcc
	v_cmp_le_i32_e32 vcc, v80, v226
	v_subrev_u32_e32 v80, 40, v232
	s_nop 0
	v_cndmask_b32_e32 v58, v216, v58, vcc
	v_cmp_le_i32_e32 vcc, v80, v226
	v_add_u32_e32 v80, -8, v232
	s_nop 0
	v_cndmask_b32_e32 v75, v216, v75, vcc
	v_cmp_le_i32_e32 vcc, v80, v226
	v_subrev_u32_e32 v80, 35, v232
	s_nop 0
	v_cndmask_b32_e32 v59, v216, v59, vcc
	v_cmp_le_i32_e32 vcc, v80, v226
	v_add_u32_e32 v80, -3, v232
	s_nop 0
	v_cndmask_b32_e32 v76, v216, v76, vcc
	v_cmp_le_i32_e32 vcc, v80, v226
	v_subrev_u32_e32 v80, 34, v232
	s_nop 0
	v_cndmask_b32_e32 v60, v216, v60, vcc
	v_cmp_le_i32_e32 vcc, v80, v226
	v_add_u32_e32 v80, -2, v232
	s_nop 0
	v_cndmask_b32_e32 v77, v216, v77, vcc
	v_cmp_le_i32_e32 vcc, v80, v226
	v_subrev_u32_e32 v80, 33, v232
	s_nop 0
	v_cndmask_b32_e32 v61, v216, v61, vcc
	v_cmp_le_i32_e32 vcc, v80, v226
	v_add_u32_e32 v80, -1, v232
	s_nop 0
	v_cndmask_b32_e32 v78, v216, v78, vcc
	v_cmp_le_i32_e32 vcc, v80, v226
	v_subrev_u32_e32 v80, 32, v232
	s_nop 0
	v_cndmask_b32_e32 v62, v216, v62, vcc
	v_cmp_le_i32_e32 vcc, v80, v226
	s_nop 1
	v_cndmask_b32_e32 v79, v216, v79, vcc
	v_cmp_le_i32_e32 vcc, v232, v226
	s_nop 1
	v_cndmask_b32_e32 v63, v216, v63, vcc

; __device__ __forceinline__ unsigned cvt_pk_bf16(float lo, float hi) { f32x2 v = {lo, hi}; bf16x2_t b = __builtin_convertvector(v, bf16x2_t); return __builtin_bit_cast(unsigned, b); }
; __device__ __forceinline__ float xor32_add(float x) { auto r = __builtin_amdgcn_permlane32_swap(__float_as_uint(x), __float_as_uint(x), false, false); return __uint_as_float(r[0]) + __uint_as_float(r[1]); }
; __device__ __forceinline__ void store_ot(bf16_t* orow, const f32x16& o0, const f32x16& o1, int h) {
;     u32x2 w[8];
; #pragma unroll
;     for (int g4 = 0; g4 < 4; ++g4) { w[g4].x = cvt_pk_bf16(o0[4 * g4], o0[4 * g4 + 1]); w[g4].y = cvt_pk_bf16(o0[4 * g4 + 2], o0[4 * g4 + 3]); w[4 + g4].x = cvt_pk_bf16(o1[4 * g4], o1[4 * g4 + 1]); w[4 + g4].y = cvt_pk_bf16(o1[4 * g4 + 2], o1[4 * g4 + 3]); }
; #pragma unroll
;     for (int k = 0; k < 8; k += 2) { const auto rx = __builtin_amdgcn_permlane32_swap(w[k].x, w[k + 1].x, false, false), ry = __builtin_amdgcn_permlane32_swap(w[k].y, w[k + 1].y, false, false);
;         u32x4 v; v.x = rx[0]; v.y = ry[0]; v.z = rx[1]; v.w = ry[1];
;         *(u32x4*)(orow + 8 * k + 8 * h) = v; }
; }
; __device__ __forceinline__ void nsa_unit(int b, int g, int tq, const Args& a, LAS unsigned char* lds, int tid, int wave, int lane, int& nxt) {
;     ...
;             const float lt = xor32_add(l); const float sc = (lt > 0.f) ? g_w / lt : 0.f; acc0 += oa * sc; acc1 += ob * sc;
;         }
;         {
;             float m = 0.f, l = 0.f; bool first = true; f32x16 oa = {}, ob = {};
;             for (;;) {
;                 const int j2 = ut ? pop_tile<1>(ut) : -1;
;                 NL_DMA(1, (j2 >= 0 ? j2 : j0), o2);
;                 NL_STEP(1, selbits);
;                 NL_WAITBAR(2);
;                 if (j1 < 0) break;
;                 j0 = j1; j1 = j2; { const int ot = o0; o0 = o1; o1 = o2; o2 = ot; }
;             }
;             asm volatile("s_waitcnt vmcnt(0)" ::: "memory");
;             const float lt = xor32_add(l); int l2 = lane; asm volatile("" : "+v"(l2)); const size_t row2 = (size_t)b * SEQ + 64 * tq + 32 * th + (l2 & 31);
;             const float sc = (lt > 0.f) ? g_s / lt : 0.f;
;             acc0 += oa * sc; acc1 += ob * sc;
;             store_ot(ON + row2 * 1024 + head * 64, acc0, acc1, l2 >> 5);
.LBB0_884:
	v_mov_b32_e32 v3, v167
	v_mov_b32_e32 v2, v166
	s_nop 0
	v_permlane32_swap_b32_e32 v167, v3
	v_permlane32_swap_b32_e32 v166, v2
	v_add_f32_e32 v2, v166, v2
	v_add_f32_e32 v3, v167, v3
	v_mul_f32_e32 v0, v177, v165
	v_div_scale_f32 v4, s[0:1], v3, v3, v176
	v_rcp_f32_e32 v5, v4
	s_add_i32 s92, s92, s93
	s_waitcnt vmcnt(0)
	v_fma_f32 v6, -v4, v5, 1.0
	v_fmac_f32_e32 v5, v6, v5
	v_div_scale_f32 v6, vcc, v176, v3, v176
	v_mul_f32_e32 v7, v6, v5
	v_fma_f32 v8, -v4, v7, v6
	v_fmac_f32_e32 v7, v8, v5
	v_fma_f32 v4, -v4, v7, v6
	v_div_fmas_f32 v4, v4, v5, v7
	v_div_fixup_f32 v4, v4, v3, v176
	v_cmp_lt_f32_e32 vcc, 0, v3
	v_div_scale_f32 v3, s[0:1], v2, v2, v175
	s_nop 0
	v_cndmask_b32_e32 v4, 0, v4, vcc
	v_mul_f32_e32 v6, v78, v4
	v_mul_f32_e32 v7, v79, v4
	v_mul_f32_e32 v8, v76, v4
	v_mul_f32_e32 v9, v77, v4
	v_mul_f32_e32 v10, v74, v4
	v_mul_f32_e32 v11, v75, v4
	v_mul_f32_e32 v12, v72, v4
	v_mul_f32_e32 v13, v73, v4
	v_mul_f32_e32 v14, v70, v4
	v_mul_f32_e32 v15, v71, v4
	v_mul_f32_e32 v68, v68, v4
	v_mul_f32_e32 v69, v69, v4
	v_mul_f32_e32 v66, v66, v4
	v_mul_f32_e32 v67, v67, v4
	v_mul_f32_e32 v64, v64, v4
	v_mul_f32_e32 v65, v65, v4
	v_fma_f32 v14, v38, v0, v14
	v_fma_f32 v15, v39, v0, v15
	v_fma_f32 v12, v40, v0, v12
	v_fma_f32 v13, v41, v0, v13
	v_fma_f32 v10, v42, v0, v10
	v_fma_f32 v11, v43, v0, v11
	v_fma_f32 v8, v44, v0, v8
	v_fma_f32 v9, v45, v0, v9
	v_fma_f32 v6, v46, v0, v6
	v_fma_f32 v7, v47, v0, v7
	v_mul_f32_e32 v38, v62, v4
	v_mul_f32_e32 v39, v63, v4
	v_mul_f32_e32 v40, v60, v4
	v_mul_f32_e32 v41, v61, v4
	v_mul_f32_e32 v42, v58, v4
	v_mul_f32_e32 v43, v59, v4
	v_mul_f32_e32 v44, v56, v4
	v_mul_f32_e32 v45, v57, v4
	v_mul_f32_e32 v46, v54, v4
	v_mul_f32_e32 v47, v55, v4
	v_mul_f32_e32 v52, v52, v4
	v_mul_f32_e32 v53, v53, v4
	v_mul_f32_e32 v50, v50, v4
	v_mul_f32_e32 v51, v51, v4
	v_mul_f32_e32 v5, v49, v4
	v_mul_f32_e32 v4, v48, v4
	v_fma_f32 v32, v32, v0, v64
	v_fma_f32 v33, v33, v0, v65
	v_fma_f32 v4, v16, v0, v4
	v_fma_f32 v5, v17, v0, v5
	v_fma_f32 v16, v18, v0, v50
	v_fma_f32 v17, v19, v0, v51
	v_fma_f32 v18, v20, v0, v52
	v_fma_f32 v19, v21, v0, v53
	v_fma_f32 v20, v22, v0, v46
	v_fma_f32 v21, v23, v0, v47
	v_fma_f32 v22, v24, v0, v44
	v_fma_f32 v23, v25, v0, v45
	v_rcp_f32_e32 v44, v3
	v_fma_f32 v34, v34, v0, v66
	v_fma_f32 v35, v35, v0, v67
	v_fma_f32 v36, v36, v0, v68
	v_fma_f32 v37, v37, v0, v69
	v_fma_f32 v24, v26, v0, v42
	v_fma_f32 v25, v27, v0, v43
	v_fma_f32 v26, v28, v0, v40
	v_fma_f32 v27, v29, v0, v41
	v_fma_f32 v28, v30, v0, v38
	v_fma_f32 v29, v31, v0, v39
	v_fma_f32 v0, -v3, v44, 1.0
	v_fmac_f32_e32 v44, v0, v44
	v_div_scale_f32 v0, vcc, v175, v2, v175
	v_mul_f32_e32 v30, v0, v44
	v_fma_f32 v31, -v3, v30, v0
	v_fmac_f32_e32 v30, v31, v44
	v_fma_f32 v0, -v3, v30, v0
	v_div_fmas_f32 v0, v0, v44, v30
	v_div_fixup_f32 v0, v0, v2, v175
	v_cmp_lt_f32_e32 vcc, 0, v2
	s_nop 1
	v_cndmask_b32_e32 v2, 0, v0, vcc
	v_and_or_b32 v0, v174, 31, s92
	v_or_b32_e32 v0, s77, v0
	v_fma_f32 v28, v110, v2, v28
	v_fma_f32 v29, v111, v2, v29
	v_fma_f32 v26, v108, v2, v26
	v_fma_f32 v27, v109, v2, v27
	v_fma_f32 v24, v106, v2, v24
	v_fma_f32 v25, v107, v2, v25
	v_fma_f32 v22, v104, v2, v22
	v_fma_f32 v23, v105, v2, v23
	v_fma_f32 v20, v102, v2, v20
	v_fma_f32 v21, v103, v2, v21
	v_fma_f32 v18, v100, v2, v18
	v_fma_f32 v19, v101, v2, v19
	v_fma_f32 v16, v98, v2, v16
	v_fma_f32 v17, v99, v2, v17
	v_fma_f32 v4, v96, v2, v4
	v_fma_f32 v5, v97, v2, v5
	v_fma_f32 v30, v94, v2, v6
	v_fma_f32 v31, v95, v2, v7
	v_fma_f32 v38, v92, v2, v8
	v_fma_f32 v39, v93, v2, v9
	v_fma_f32 v40, v90, v2, v10
	v_fma_f32 v41, v91, v2, v11
	v_fma_f32 v12, v88, v2, v12
	v_fma_f32 v13, v89, v2, v13
	v_fma_f32 v10, v86, v2, v14
	v_fma_f32 v11, v87, v2, v15
	v_fma_f32 v8, v84, v2, v36
	v_fma_f32 v9, v85, v2, v37
	v_fma_f32 v14, v82, v2, v34
	v_fma_f32 v15, v83, v2, v35
	v_fma_f32 v6, v80, v2, v32
	v_fma_f32 v7, v81, v2, v33
	v_lshlrev_b64 v[2:3], 11, v[0:1]
	v_lshl_add_u64 v[2:3], s[52:53], 0, v[2:3]
	v_ashrrev_i32_e32 v0, 2, v174
	v_lshl_add_u64 v[32:33], s[58:59], 1, v[2:3]
	v_cvt_pk_bf16_f32 v2, v4, v5
	v_cvt_pk_bf16_f32 v4, v18, v19
	v_and_b32_e32 v18, -8, v0
	v_cvt_pk_bf16_f32 v3, v16, v17
	v_cvt_pk_bf16_f32 v6, v6, v7
	v_cvt_pk_bf16_f32 v7, v14, v15
	v_cvt_pk_bf16_f32 v5, v20, v21
	v_cvt_pk_bf16_f32 v8, v8, v9
	v_cvt_pk_bf16_f32 v9, v10, v11
	v_cvt_pk_bf16_f32 v10, v22, v23
	v_cvt_pk_bf16_f32 v11, v24, v25
	v_cvt_pk_bf16_f32 v14, v12, v13
	v_cvt_pk_bf16_f32 v15, v40, v41
	v_cvt_pk_bf16_f32 v12, v26, v27
	v_cvt_pk_bf16_f32 v13, v28, v29
	v_cvt_pk_bf16_f32 v16, v38, v39
	v_cvt_pk_bf16_f32 v17, v30, v31
	v_ashrrev_i32_e32 v19, 31, v18
	v_lshl_add_u64 v[18:19], v[18:19], 1, v[32:33]
	v_permlane32_swap_b32_e32 v2, v4
	v_permlane32_swap_b32_e32 v3, v5
	v_permlane32_swap_b32_e32 v10, v12
	v_permlane32_swap_b32_e32 v11, v13
	v_permlane32_swap_b32_e32 v6, v8
	v_permlane32_swap_b32_e32 v7, v9
	v_permlane32_swap_b32_e32 v14, v16
	v_permlane32_swap_b32_e32 v15, v17
	global_store_dwordx4 v[18:19], v[2:5], off
	global_store_dwordx4 v[18:19], v[10:13], off offset:32
	global_store_dwordx4 v[18:19], v[6:9], off offset:64
	global_store_dwordx4 v[18:19], v[14:17], off offset:96
	s_waitcnt lgkmcnt(0)
	s_barrier

; #define LAS __attribute__((address_space(3)))
; #define MFMA32(a, b, c) __builtin_amdgcn_mfma_f32_32x32x16_bf16((a), (b), (c), 0, 0, 0)
; __device__ __forceinline__ void qk_tile(f32x16& p0, f32x16& p1, LAS const unsigned char* Kt, const bf16x8 (&qf)[4], int lane) {
;     LAS const unsigned char* kp = Kt + (lane & 31) * KVP + 16 * (lane >> 5);
;     f32x16 z = {}; p0 = z; p1 = z;
; #pragma unroll
;     for (int s = 0; s < 4; ++s) { const bf16x8 a0 = *(LAS const bf16x8*)(kp + 32 * s), a1 = *(LAS const bf16x8*)(kp + 32 * KVP + 32 * s);
;         p0 = MFMA32(a0, qf[s], p0); p1 = MFMA32(a1, qf[s], p1); }
; }
; __device__ __forceinline__ void nsa_unit(int b, int g, int tq, const Args& a, LAS unsigned char* lds, int tid, int wave, int lane, int& nxt) {
;     ...
;     tile_st(cmpb, ck0, tid); tile_st_v(cmpb + 2 * KVT, cv0, tid); tile_st(cmpb + KVT, ck1, tid); tile_st_v(cmpb + 3 * KVT, cv1, tid);
;     if (tid == 0) uni[0] = 0u;
;     __syncthreads();
;     f32x16 acc0, acc1;
;     {
.LBB0_895:
	s_or_b64 exec, exec, s[8:9]
	v_mul_lo_u32 v19, v80, s80
	v_add3_u32 v0, 0, v19, v0
	s_waitcnt vmcnt(14)
	s_waitcnt vmcnt(13)
	s_waitcnt vmcnt(12)
	s_waitcnt vmcnt(11)
	s_waitcnt vmcnt(8)
	s_waitcnt vmcnt(6)
	ds_write_b128 v0, v[6:9] offset:49152
	v_lshlrev_b32_e32 v7, 2, v86
	v_and_b32_e32 v7, 64, v7
	s_movk_i32 s0, 0x70
	v_and_b32_e32 v6, 0xffffff80, v18
	v_bitop3_b32 v7, v18, v7, s0 bitop3:0x6c
	v_add3_u32 v8, s81, v6, v7
	s_waitcnt vmcnt(4)
	ds_write_b128 v8, v[2:5]
	s_waitcnt vmcnt(2)
	ds_write_b128 v0, v[10:13] offset:58368
	v_add3_u32 v0, s82, v6, v7
	s_waitcnt vmcnt(0)
	ds_write_b128 v0, v[14:17]
	s_and_saveexec_b64 s[4:5], vcc
	v_mov_b32_e32 v0, s83
	ds_write_b32 v0, v1
	s_or_b64 exec, exec, s[4:5]
	v_lshrrev_b32_e32 v2, 1, v86
	v_mad_u32_u24 v0, v84, s80, 0
	v_and_b32_e32 v2, 16, v2
	v_add_u32_e32 v89, v0, v2
	s_waitcnt lgkmcnt(0)
	s_barrier
	ds_read_b128 v[2:5], v89 offset:49152
	ds_read_b128 v[36:39], v89 offset:49184
	ds_read_b128 v[18:21], v89 offset:53760
	ds_read_b128 v[40:43], v89 offset:53792
	s_waitcnt lgkmcnt(3)
	v_mfma_f32_32x32x16_bf16 v[2:17], v[2:5], v[144:147], 0
	ds_read_b128 v[44:47], v89 offset:49216
	ds_read_b128 v[48:51], v89 offset:49248
	ds_read_b128 v[52:55], v89 offset:53824
	ds_read_b128 v[56:59], v89 offset:53856
	v_lshlrev_b32_e32 v90, 6, v83
	s_mul_i32 s0, s6, 0x500
	v_subrev_u32_e32 v0, 31, v178
	v_or_b32_e32 v91, 16, v90
	v_or_b32_e32 v92, 32, v90
	v_or_b32_e32 v93, 48, v90
	s_waitcnt lgkmcnt(5)
	v_mfma_f32_32x32x16_bf16 v[18:33], v[18:21], v[144:147], 0
	s_add_i32 s96, s0, 0
	s_add_i32 s96, s96, 0x1d600
	v_or_b32_e32 v94, 0x80, v90
	v_or_b32_e32 v95, 0x90, v90
	v_or_b32_e32 v96, 0xa0, v90
	v_or_b32_e32 v97, 0xb0, v90
	v_or_b32_e32 v98, 0x100, v90
	s_waitcnt lgkmcnt(4)
	v_mfma_f32_32x32x16_bf16 v[18:33], v[40:43], v[148:151], v[18:33]
	v_sub_u32_e32 v40, v0, v92
	v_sub_u32_e32 v42, v0, v93
	v_med3_i32 v41, v40, -1, v170
	v_med3_i32 v40, v40, s86, v171
	v_med3_i32 v43, v42, -1, v170
	v_med3_i32 v42, v42, s86, v171
	v_lshl_add_u32 v40, v40, 2, s96
	v_mfma_f32_32x32x16_bf16 v[2:17], v[36:39], v[148:151], v[2:17]
	v_sub_u32_e32 v36, v0, v90
	v_sub_u32_e32 v38, v0, v91
	v_med3_i32 v37, v36, -1, v170
	v_med3_i32 v36, v36, s86, v171
	v_med3_i32 v39, v38, -1, v170
	v_med3_i32 v38, v38, s86, v171
	v_lshl_add_u32 v36, v36, 2, s96
	s_waitcnt lgkmcnt(1)
	v_mfma_f32_32x32x16_bf16 v[18:33], v[52:55], v[152:155], v[18:33]
	v_lshl_add_u32 v38, v38, 2, s96
	v_lshl_add_u32 v42, v42, 2, s96
	v_lshl_add_u32 v37, v37, 2, s96
	v_add_u32_e32 v36, 0xfffff900, v36
	v_lshl_add_u32 v39, v39, 2, s96
	v_add_u32_e32 v38, 0xfffff900, v38
	v_lshl_add_u32 v41, v41, 2, s96
	v_mfma_f32_32x32x16_bf16 v[2:17], v[44:47], v[152:155], v[2:17]
	v_add_u32_e32 v40, 0xfffff900, v40
	v_lshl_add_u32 v43, v43, 2, s96
	v_add_u32_e32 v42, 0xfffff900, v42
	ds_read_b32 v37, v37 offset:256
	ds_read_b32 v36, v36
	ds_read_b32 v39, v39 offset:256
	ds_read_b32 v38, v38
	ds_read_b32 v41, v41 offset:256
	ds_read_b32 v40, v40
	ds_read_b32 v43, v43 offset:256
	ds_read_b32 v42, v42
	v_or_b32_e32 v99, 0x110, v90
	v_or_b32_e32 v100, 0x120, v90
	v_or_b32_e32 v101, 0x130, v90
	s_waitcnt lgkmcnt(8)
	v_mfma_f32_32x32x16_bf16 v[18:33], v[56:59], v[156:159], v[18:33]
	v_or_b32_e32 v102, 0x180, v90
	v_or_b32_e32 v103, 0x190, v90
	v_or_b32_e32 v104, 0x1a0, v90
	v_or_b32_e32 v105, 0x1b0, v90
	v_cmp_gt_u32_e64 s[4:5], 32, v174
	v_or_b32_e32 v87, s78, v85
	v_lshlrev_b32_e32 v179, 2, v83
	v_mfma_f32_32x32x16_bf16 v[2:17], v[48:51], v[156:159], v[2:17]
	s_waitcnt lgkmcnt(6)
	s_nop 2
	v_add_f32_e32 v18, v18, v36
	s_waitcnt lgkmcnt(4)
	v_add_f32_e32 v19, v19, v38
	s_waitcnt lgkmcnt(2)
	v_add_f32_e32 v20, v20, v40
	s_waitcnt lgkmcnt(0)
	v_add_f32_e32 v21, v21, v42
	v_sub_u32_e32 v36, v0, v94
	v_sub_u32_e32 v38, v0, v95
	v_sub_u32_e32 v40, v0, v96
	v_sub_u32_e32 v42, v0, v97
	v_add_f32_e32 v2, v2, v37
	v_add_f32_e32 v3, v3, v39
	v_add_f32_e32 v4, v4, v41
	v_add_f32_e32 v5, v5, v43
	v_med3_i32 v37, v36, -1, v170
	v_med3_i32 v36, v36, s86, v171
	v_med3_i32 v39, v38, -1, v170
	v_med3_i32 v38, v38, s86, v171
	v_med3_i32 v41, v40, -1, v170
	v_med3_i32 v40, v40, s86, v171
	v_med3_i32 v43, v42, -1, v170
	v_med3_i32 v42, v42, s86, v171
	v_lshl_add_u32 v36, v36, 2, s96
	v_lshl_add_u32 v38, v38, 2, s96
	v_lshl_add_u32 v40, v40, 2, s96
	v_lshl_add_u32 v42, v42, 2, s96
	v_lshl_add_u32 v37, v37, 2, s96
	v_add_u32_e32 v36, 0xfffff900, v36
	v_lshl_add_u32 v39, v39, 2, s96
	v_add_u32_e32 v38, 0xfffff900, v38
	v_lshl_add_u32 v41, v41, 2, s96
	v_add_u32_e32 v40, 0xfffff900, v40
	v_lshl_add_u32 v43, v43, 2, s96
	v_add_u32_e32 v42, 0xfffff900, v42
	ds_read_b32 v37, v37 offset:256
	ds_read_b32 v36, v36
	ds_read_b32 v39, v39 offset:256
	ds_read_b32 v38, v38
	ds_read_b32 v41, v41 offset:256
	ds_read_b32 v40, v40
	ds_read_b32 v43, v43 offset:256
	ds_read_b32 v42, v42
	s_waitcnt lgkmcnt(6)
	v_add_f32_e32 v22, v22, v36
	s_waitcnt lgkmcnt(4)
	v_add_f32_e32 v23, v23, v38
	s_waitcnt lgkmcnt(3)
	v_add_f32_e32 v36, v8, v41
	s_waitcnt lgkmcnt(2)
	v_add_f32_e32 v24, v24, v40
	s_waitcnt lgkmcnt(0)
	v_add_f32_e32 v25, v25, v42
	v_sub_u32_e32 v8, v0, v98
	v_sub_u32_e32 v38, v0, v99
	v_sub_u32_e32 v40, v0, v100
	v_sub_u32_e32 v42, v0, v101
	v_add_f32_e32 v6, v6, v37
	v_add_f32_e32 v7, v7, v39
	v_add_f32_e32 v9, v9, v43
	v_med3_i32 v37, v8, -1, v170
	v_med3_i32 v8, v8, s86, v171
	v_med3_i32 v39, v38, -1, v170
	v_med3_i32 v38, v38, s86, v171
	v_med3_i32 v41, v40, -1, v170
	v_med3_i32 v40, v40, s86, v171
	v_med3_i32 v43, v42, -1, v170
	v_med3_i32 v42, v42, s86, v171
	v_lshl_add_u32 v8, v8, 2, s96
	v_lshl_add_u32 v38, v38, 2, s96
	v_lshl_add_u32 v40, v40, 2, s96
	v_lshl_add_u32 v42, v42, 2, s96
	v_lshl_add_u32 v37, v37, 2, s96
	v_add_u32_e32 v8, 0xfffff900, v8
	v_lshl_add_u32 v39, v39, 2, s96
	v_add_u32_e32 v38, 0xfffff900, v38
	v_lshl_add_u32 v41, v41, 2, s96
	v_add_u32_e32 v40, 0xfffff900, v40
	v_lshl_add_u32 v43, v43, 2, s96
	v_add_u32_e32 v42, 0xfffff900, v42
	ds_read_b32 v37, v37 offset:256
	ds_read_b32 v8, v8
	ds_read_b32 v39, v39 offset:256
	ds_read_b32 v38, v38
	ds_read_b32 v41, v41 offset:256
	ds_read_b32 v40, v40
	ds_read_b32 v43, v43 offset:256
	ds_read_b32 v42, v42
	s_waitcnt lgkmcnt(6)
; #define LAS __attribute__((address_space(3)))
; __device__ __forceinline__ void nsa_unit(int b, int g, int tq, const Args& a, LAS unsigned char* lds, int tid, int wave, int lane, int& nxt) {
;     ...
;         f32x16 p0, p1; float mx = NEG, sum = 0.f;
;         f32x16 z = {}; acc0 = z; acc1 = z;
;         LAS float* ip = imp + (hr * 64 + tl) * 33 + h; float carry = 0.f;
	v_add_f32_e32 v26, v26, v8
	s_waitcnt lgkmcnt(4)
	v_add_f32_e32 v27, v27, v38
	s_waitcnt lgkmcnt(2)
	v_add_f32_e32 v28, v28, v40
	s_waitcnt lgkmcnt(1)
	v_add_f32_e32 v38, v13, v43
	v_sub_u32_e32 v8, v0, v102
	v_sub_u32_e32 v13, v0, v103
	v_sub_u32_e32 v40, v0, v104
	v_sub_u32_e32 v0, v0, v105
	v_add_f32_e32 v10, v10, v37
	v_add_f32_e32 v11, v11, v39
	v_add_f32_e32 v37, v12, v41
	s_waitcnt lgkmcnt(0)
	v_add_f32_e32 v29, v29, v42
	v_med3_i32 v12, v8, -1, v170
	v_med3_i32 v8, v8, s86, v171
	v_med3_i32 v39, v13, -1, v170
	v_med3_i32 v13, v13, s86, v171
	v_med3_i32 v41, v40, -1, v170
	v_med3_i32 v40, v40, s86, v171
	v_med3_i32 v42, v0, -1, v170
	v_med3_i32 v0, v0, s86, v171
	v_lshl_add_u32 v8, v8, 2, s96
	v_lshl_add_u32 v13, v13, 2, s96
	v_lshl_add_u32 v40, v40, 2, s96
	v_lshl_add_u32 v0, v0, 2, s96
	v_lshl_add_u32 v12, v12, 2, s96
	v_add_u32_e32 v8, 0xfffff900, v8
	v_lshl_add_u32 v39, v39, 2, s96
	v_add_u32_e32 v13, 0xfffff900, v13
	v_lshl_add_u32 v41, v41, 2, s96
	v_add_u32_e32 v40, 0xfffff900, v40
	v_lshl_add_u32 v42, v42, 2, s96
	v_add_u32_e32 v0, 0xfffff900, v0
	ds_read_b32 v12, v12 offset:256
	ds_read_b32 v8, v8
	ds_read_b32 v39, v39 offset:256
	ds_read_b32 v13, v13
	ds_read_b32 v41, v41 offset:256
	ds_read_b32 v40, v40
	ds_read_b32 v42, v42 offset:256
	ds_read_b32 v0, v0
	s_waitcnt lgkmcnt(5)
	v_add_f32_e32 v15, v15, v39
	v_add_f32_e32 v43, v14, v12
	s_waitcnt lgkmcnt(2)
	v_add_f32_e32 v39, v32, v40
	v_add_f32_e32 v30, v30, v8
	s_waitcnt lgkmcnt(0)
	v_add_f32_e32 v40, v33, v0
	v_max_f32_e32 v0, v3, v19
	v_max3_f32 v0, v2, v18, v0
	v_max_f32_e32 v8, v4, v20
	v_max_f32_e32 v12, v5, v21
	v_max3_f32 v0, v0, v8, v12
	v_max_f32_e32 v8, v6, v22
	v_max_f32_e32 v12, v7, v23
	v_max3_f32 v0, v0, v8, v12
	v_max_f32_e32 v8, v36, v24
	v_max_f32_e32 v12, v9, v25
	v_max3_f32 v0, v0, v8, v12
	v_max_f32_e32 v8, v10, v26
	v_max_f32_e32 v12, v11, v27
	v_add_f32_e32 v31, v31, v13
	v_max3_f32 v0, v0, v8, v12
	v_max_f32_e32 v8, v37, v28
	v_max_f32_e32 v12, v38, v29
	v_add_f32_e32 v16, v16, v41
	v_add_f32_e32 v17, v17, v42
	v_max3_f32 v0, v0, v8, v12
	v_max_f32_e32 v8, v43, v30
	v_max_f32_e32 v12, v15, v31
	v_max3_f32 v0, v0, v8, v12
	v_max_f32_e32 v8, v16, v39
	v_max_f32_e32 v12, v17, v40
	v_max3_f32 v0, v0, v8, v12
	v_mov_b32_e32 v8, v0
	s_nop 1
	v_permlane32_swap_b32_e32 v0, v8
	v_max3_f32 v81, v0, v8, s55
	v_sub_f32_e32 v0, v2, v81
	v_sub_f32_e32 v2, v4, v81
	v_sub_f32_e32 v4, v10, v81
	v_exp_f32_e32 v41, v0
	v_sub_f32_e32 v0, v18, v81
	v_exp_f32_e32 v42, v2
	v_sub_f32_e32 v2, v20, v81
	v_exp_f32_e32 v59, v4
	v_sub_f32_e32 v4, v26, v81
	v_exp_f32_e32 v51, v0
	v_sub_f32_e32 v0, v3, v81
	v_exp_f32_e32 v53, v2
	v_sub_f32_e32 v2, v5, v81
	v_sub_f32_e32 v3, v6, v81
	v_exp_f32_e32 v76, v4
	v_sub_f32_e32 v4, v25, v81
	v_sub_f32_e32 v6, v37, v81
	v_exp_f32_e32 v60, v2
	v_sub_f32_e32 v2, v21, v81
	v_exp_f32_e32 v14, v4
	v_sub_f32_e32 v4, v11, v81
	v_exp_f32_e32 v11, v6
	v_sub_f32_e32 v6, v28, v81
	v_exp_f32_e32 v8, v2
	v_sub_f32_e32 v2, v7, v81
	v_exp_f32_e32 v77, v6
	v_sub_f32_e32 v6, v38, v81
	v_exp_f32_e32 v56, v2
	v_sub_f32_e32 v2, v23, v81
	v_exp_f32_e32 v54, v6
	v_sub_f32_e32 v6, v29, v81
	v_exp_f32_e32 v58, v2
	v_sub_f32_e32 v2, v9, v81
	v_exp_f32_e32 v50, v6
	v_sub_f32_e32 v6, v43, v81
	v_sub_f32_e32 v9, v31, v81
	v_exp_f32_e32 v32, v0
	v_exp_f32_e32 v72, v6
	v_sub_f32_e32 v6, v30, v81
	v_exp_f32_e32 v10, v9
	v_sub_f32_e32 v9, v16, v81
	v_exp_f32_e32 v78, v6
	v_sub_f32_e32 v6, v15, v81
	v_exp_f32_e32 v15, v9
	v_sub_f32_e32 v9, v39, v81
	v_exp_f32_e32 v79, v9
	v_sub_f32_e32 v9, v17, v81
	v_exp_f32_e32 v5, v3
	v_sub_f32_e32 v3, v22, v81
	v_exp_f32_e32 v48, v9
	v_sub_f32_e32 v9, v40, v81
	v_exp_f32_e32 v74, v3
	v_sub_f32_e32 v3, v36, v81
	v_exp_f32_e32 v52, v9
	v_add_f32_e32 v9, v41, v32
	v_add_f32_e32 v16, v42, v60
	v_exp_f32_e32 v7, v3
	v_exp_f32_e32 v2, v2
	v_add_f32_e32 v9, v9, v16
	v_mov_b32_e32 v16, v60
	v_mov_b32_e32 v17, v60
	s_nop 1
	v_permlane32_swap_b32_e32 v16, v17
	v_cndmask_b32_e64 v16, v16, v17, s[4:5]
	v_mul_lo_u32 v18, v87, s85
	v_cndmask_b32_e64 v17, v16, 0, s[4:5]
	v_add3_u32 v88, s84, v18, v179
	v_add_f32_e32 v9, v17, v9
	v_add_f32_e32 v17, v5, v56
	v_add_f32_e32 v18, v7, v2
	v_sub_f32_e32 v0, v19, v81
	v_add_f32_e32 v17, v17, v18
	v_mov_b32_e32 v18, v2
	v_mov_b32_e32 v19, v2
	v_exp_f32_e32 v12, v4
	s_nop 0
	v_permlane32_swap_b32_e32 v18, v19
	v_cndmask_b32_e64 v18, v18, v19, s[4:5]
	v_cndmask_b32_e64 v16, v18, v16, s[4:5]
	v_add_f32_e32 v16, v16, v17
	ds_write2_b32 v88, v9, v16 offset1:2
	v_add_f32_e32 v9, v59, v12
	v_add_f32_e32 v16, v11, v54
	v_exp_f32_e32 v6, v6
	v_add_f32_e32 v9, v9, v16
	v_mov_b32_e32 v16, v54
	v_mov_b32_e32 v17, v54
	s_nop 1
	v_permlane32_swap_b32_e32 v16, v17
	v_cndmask_b32_e64 v16, v16, v17, s[4:5]
	v_cndmask_b32_e64 v17, v16, v18, s[4:5]
	v_add_f32_e32 v9, v9, v17
	v_add_f32_e32 v17, v72, v6
	v_add_f32_e32 v18, v15, v48
	v_add_f32_e32 v17, v17, v18
	v_mov_b32_e32 v18, v48
	v_mov_b32_e32 v19, v48
	v_exp_f32_e32 v0, v0
	s_nop 0
	v_permlane32_swap_b32_e32 v18, v19
	v_cndmask_b32_e64 v18, v18, v19, s[4:5]
	v_cndmask_b32_e64 v16, v18, v16, s[4:5]
	v_add_f32_e32 v16, v17, v16
	v_sub_f32_e32 v3, v24, v81
	ds_write2_b32 v88, v9, v16 offset0:4 offset1:6
	v_add_f32_e32 v9, v51, v0
	v_add_f32_e32 v16, v53, v8
	v_exp_f32_e32 v75, v3
	v_add_f32_e32 v9, v9, v16
	v_mov_b32_e32 v16, v8
	v_mov_b32_e32 v17, v8
	s_nop 1
	v_permlane32_swap_b32_e32 v16, v17
	v_cndmask_b32_e64 v16, v16, v17, s[4:5]
	v_cndmask_b32_e64 v17, v16, v18, s[4:5]
	v_add_f32_e32 v9, v9, v17
	v_add_f32_e32 v17, v74, v58
	v_add_f32_e32 v18, v75, v14
	v_sub_f32_e32 v4, v27, v81
	v_add_f32_e32 v17, v17, v18
	v_mov_b32_e32 v18, v14
	v_mov_b32_e32 v19, v14
; __device__ __forceinline__ void nsa_unit(int b, int g, int tq, const Args& a, LAS unsigned char* lds, int tid, int wave, int lane, int& nxt) {
;     ...
;         CMP_TILE(0);
;         const float m_t0 = mx;
;         if (nct > 1) CMP_TILE(1);
	v_exp_f32_e32 v4, v4
	s_nop 0
	v_permlane32_swap_b32_e32 v18, v19
	v_cndmask_b32_e64 v18, v18, v19, s[4:5]
	v_cndmask_b32_e64 v16, v18, v16, s[4:5]
	v_add_f32_e32 v16, v17, v16
	ds_write2_b32 v88, v9, v16 offset0:8 offset1:10
	v_add_f32_e32 v9, v76, v4
	v_add_f32_e32 v16, v77, v50
	v_add_f32_e32 v9, v9, v16
	v_mov_b32_e32 v16, v50
	v_mov_b32_e32 v17, v50
	s_nop 1
	v_permlane32_swap_b32_e32 v16, v17
	v_cndmask_b32_e64 v16, v16, v17, s[4:5]
	v_cndmask_b32_e64 v17, v16, v18, s[4:5]
	v_add_f32_e32 v9, v9, v17
	v_add_f32_e32 v17, v78, v10
	v_add_f32_e32 v18, v79, v52
	v_add_f32_e32 v17, v17, v18
	v_mov_b32_e32 v18, v52
	v_mov_b32_e32 v19, v52
	s_nop 1
	v_permlane32_swap_b32_e32 v18, v19
	v_cndmask_b32_e64 v106, v18, v19, s[4:5]
	v_cndmask_b32_e64 v16, v106, v16, s[4:5]
	v_add_f32_e32 v16, v17, v16
	ds_write2_b32 v88, v9, v16 offset0:12 offset1:14
	v_bfe_u32 v9, v174, 2, 2
	v_and_or_b32 v9, v34, 4, v9
	v_and_b32_e32 v16, 16, v86
	v_lshlrev_b32_e32 v17, 2, v174
	v_lshlrev_b32_e32 v20, 5, v35
	v_lshlrev_b32_e32 v128, 7, v9
	v_and_or_b32 v16, v17, 12, v16
	v_and_b32_e32 v180, 64, v20
	v_add_u32_e32 v9, s81, v128
	v_lshlrev_b32_e32 v181, 1, v16
	v_add3_u32 v107, v9, v181, v180
	ds_read_b64_tr_b16 v[16:17], v107
	ds_read_b64_tr_b16 v[18:19], v107 offset:1024
	v_bitop3_b32 v182, v181, v20, 64 bitop3:0x72
	v_add_u32_e32 v108, v9, v182
	v_add_f32_e32 v33, v41, v51
	v_add_f32_e32 v61, v42, v53
	v_cvt_pk_bf16_f32 v36, v41, v32
	v_cvt_pk_bf16_f32 v37, v42, v60
	ds_read_b64_tr_b16 v[40:41], v108
	ds_read_b64_tr_b16 v[42:43], v108 offset:1024
	ds_read_b64_tr_b16 v[62:63], v107 offset:2048
	ds_read_b64_tr_b16 v[64:65], v107 offset:3072
	v_cvt_pk_bf16_f32 v38, v5, v56
	v_cvt_pk_bf16_f32 v39, v7, v2
	v_add_f32_e32 v32, v32, v0
	v_add_f32_e32 v33, v33, v1
	ds_read_b64_tr_b16 v[66:67], v108 offset:2048
	ds_read_b64_tr_b16 v[68:69], v108 offset:3072
	s_waitcnt lgkmcnt(6)
	v_mfma_f32_32x32x16_bf16 v[16:31], v[16:19], v[36:39], 0
	v_add_f32_e64 v70, v32, v32
	v_add_f32_e64 v71, v32, v33
	v_add_f32_e32 v3, v7, v75
	v_add_f32_e32 v7, v72, v78
	v_mov_b32_e32 v9, v71
	v_cvt_pk_bf16_f32 v70, v59, v12
	v_cvt_pk_bf16_f32 v71, v11, v54
	v_cvt_pk_bf16_f32 v72, v72, v6
	s_waitcnt lgkmcnt(4)
	v_mfma_f32_32x32x16_bf16 v[32:47], v[40:43], v[36:39], 0
	v_cvt_pk_bf16_f32 v73, v15, v48
	v_add_f32_e64 v60, v60, v8
	v_add_f32_e64 v61, v61, v9
	v_add_f32_e32 v13, v59, v76
	v_add_f32_e32 v61, v60, v61
	v_add_f32_e32 v60, v60, v60
	v_mov_b32_e32 v59, v61
	v_add_f32_e32 v57, v5, v74
	v_add_f32_e32 v56, v56, v58
	v_add_f32_e32 v57, v57, v59
	s_waitcnt lgkmcnt(2)
	v_mfma_f32_32x32x16_bf16 v[16:31], v[62:65], v[70:73], v[16:31]
	ds_read_b64_tr_b16 v[60:61], v107 offset:4096
	ds_read_b64_tr_b16 v[62:63], v107 offset:5120
	v_add_f32_e32 v57, v56, v57
	v_add_f32_e32 v56, v56, v56
	v_add_f32_e32 v49, v15, v79
	v_mov_b32_e32 v15, v57
	v_cvt_pk_bf16_f32 v56, v51, v0
	v_cvt_pk_bf16_f32 v57, v53, v8
	v_cvt_pk_bf16_f32 v58, v74, v58
	s_waitcnt lgkmcnt(2)
	v_mfma_f32_32x32x16_bf16 v[32:47], v[66:69], v[70:73], v[32:47]
	ds_read_b64_tr_b16 v[64:65], v108 offset:4096
	ds_read_b64_tr_b16 v[66:67], v108 offset:5120
	ds_read_b64_tr_b16 v[68:69], v107 offset:6144
	ds_read_b64_tr_b16 v[70:71], v107 offset:7168
	v_cvt_pk_bf16_f32 v59, v75, v14
	v_add_f32_e32 v2, v2, v14
	v_add_f32_e32 v3, v3, v15
	v_add_f32_e32 v55, v11, v77
	v_add_f32_e32 v3, v2, v3
	v_add_f32_e32 v2, v2, v2
	v_mov_b32_e32 v5, v3
	v_add_f32_e32 v2, v12, v4
	v_add_f32_e32 v3, v13, v5
	s_waitcnt lgkmcnt(4)
	v_mfma_f32_32x32x16_bf16 v[16:31], v[60:63], v[56:59], v[16:31]
	ds_read_b64_tr_b16 v[12:13], v108 offset:6144
	ds_read_b64_tr_b16 v[14:15], v108 offset:7168
	v_add_f32_e32 v3, v2, v3
	v_add_f32_e32 v2, v2, v2
	v_mov_b32_e32 v51, v3
	v_add_f32_e32 v2, v54, v50
	v_add_f32_e32 v3, v55, v51
	v_cvt_pk_bf16_f32 v54, v76, v4
	v_cvt_pk_bf16_f32 v55, v77, v50
	v_add_f32_e32 v3, v2, v3
	v_add_f32_e32 v2, v2, v2
	s_waitcnt lgkmcnt(4)
	v_mfma_f32_32x32x16_bf16 v[32:47], v[64:67], v[56:59], v[32:47]
	v_cvt_pk_bf16_f32 v56, v78, v10
	v_cvt_pk_bf16_f32 v57, v79, v52
	v_mov_b32_e32 v11, v3
	v_add_f32_e64 v2, v6, v10
	v_add_f32_e64 v3, v7, v11
	s_cmp_lt_u32 s38, 16
	v_add_f32_e32 v3, v2, v3
	v_add_f32_e32 v2, v2, v2
	v_mov_b32_e32 v53, v3
	s_waitcnt lgkmcnt(2)
	v_mfma_f32_32x32x16_bf16 v[16:31], v[68:71], v[54:57], v[16:31]
	v_add_f32_e64 v2, v48, v52
	v_add_f32_e64 v3, v49, v53
	v_add_f32_e32 v0, v2, v3
	v_add_f32_e32 v3, 0, v0
	s_waitcnt lgkmcnt(0)
	v_mfma_f32_32x32x16_bf16 v[32:47], v[12:15], v[54:57], v[32:47]
	s_cbranch_scc1 .LBB0_899
; #define LAS __attribute__((address_space(3)))
; #define MFMA32(a, b, c) __builtin_amdgcn_mfma_f32_32x32x16_bf16((a), (b), (c), 0, 0, 0)
; __device__ __forceinline__ void qk_tile(f32x16& p0, f32x16& p1, LAS const unsigned char* Kt, const bf16x8 (&qf)[4], int lane) {
;     LAS const unsigned char* kp = Kt + (lane & 31) * KVP + 16 * (lane >> 5);
;     f32x16 z = {}; p0 = z; p1 = z;
; #pragma unroll
;     for (int s = 0; s < 4; ++s) { const bf16x8 a0 = *(LAS const bf16x8*)(kp + 32 * s), a1 = *(LAS const bf16x8*)(kp + 32 * KVP + 32 * s);
;         p0 = MFMA32(a0, qf[s], p0); p1 = MFMA32(a1, qf[s], p1); }
; }
	ds_read_b128 v[4:7], v89 offset:58368
	ds_read_b128 v[8:11], v89 offset:58400
	v_add_u32_e32 v0, 0xfffffbe1, v178
	v_sub_u32_e32 v2, v0, v90
	s_waitcnt lgkmcnt(1)
	v_mfma_f32_32x32x16_bf16 v[48:63], v[4:7], v[144:147], 0
	ds_read_b128 v[4:7], v89 offset:62976
	ds_read_b128 v[12:15], v89 offset:63008
	s_waitcnt lgkmcnt(1)
	v_mfma_f32_32x32x16_bf16 v[64:79], v[4:7], v[144:147], 0
	v_mfma_f32_32x32x16_bf16 v[48:63], v[8:11], v[148:151], v[48:63]
	ds_read_b128 v[4:7], v89 offset:58432
	ds_read_b128 v[8:11], v89 offset:58464
	ds_read_b128 v[108:111], v89 offset:63040
	ds_read_b128 v[112:115], v89 offset:63072
	v_med3_i32 v89, v2, -1, v170
	v_med3_i32 v2, v2, s86, v171
	v_lshl_add_u32 v2, v2, 2, s96
	v_lshl_add_u32 v89, v89, 2, s96
	v_add_u32_e32 v2, 0xfffff900, v2
	s_waitcnt lgkmcnt(4)
	v_mfma_f32_32x32x16_bf16 v[64:79], v[12:15], v[148:151], v[64:79]
	v_sub_u32_e32 v12, v0, v91
	v_med3_i32 v13, v12, -1, v170
	v_med3_i32 v12, v12, s86, v171
	v_lshl_add_u32 v13, v13, 2, s96
	v_sub_u32_e32 v15, v0, v96
	s_waitcnt lgkmcnt(3)
	v_mfma_f32_32x32x16_bf16 v[48:63], v[4:7], v[152:155], v[48:63]
	v_sub_u32_e32 v5, v0, v92
	v_sub_u32_e32 v7, v0, v93
	v_lshl_add_u32 v4, v12, 2, s96
	v_med3_i32 v6, v5, -1, v170
	v_med3_i32 v5, v5, s86, v171
	v_med3_i32 v12, v7, -1, v170
	v_med3_i32 v7, v7, s86, v171
	s_waitcnt lgkmcnt(1)
	v_mfma_f32_32x32x16_bf16 v[64:79], v[108:111], v[152:155], v[64:79]
	v_lshl_add_u32 v5, v5, 2, s96
	v_lshl_add_u32 v7, v7, 2, s96
	v_add_u32_e32 v4, 0xfffff900, v4
	v_lshl_add_u32 v6, v6, 2, s96
	v_add_u32_e32 v5, 0xfffff900, v5
	v_add_u32_e32 v7, 0xfffff900, v7
	v_lshl_add_u32 v12, v12, 2, s96
	v_mfma_f32_32x32x16_bf16 v[48:63], v[8:11], v[156:159], v[48:63]
	ds_read_b32 v8, v89 offset:256
	ds_read_b32 v2, v2
	ds_read_b32 v9, v13 offset:256
	ds_read_b32 v4, v4
	ds_read_b32 v6, v6 offset:256
	ds_read_b32 v5, v5
	ds_read_b32 v10, v12 offset:256
	ds_read_b32 v7, v7
	v_sub_u32_e32 v13, v0, v95
	v_med3_i32 v14, v13, -1, v170
	v_med3_i32 v13, v13, s86, v171
	v_lshl_add_u32 v13, v13, 2, s96
	v_lshl_add_u32 v14, v14, 2, s96
	v_add_u32_e32 v13, 0xfffff900, v13
	s_waitcnt lgkmcnt(8)
	v_mfma_f32_32x32x16_bf16 v[64:79], v[112:115], v[156:159], v[64:79]
	s_waitcnt lgkmcnt(5)
	v_add_f32_e32 v9, v49, v9
	v_sub_u32_e32 v49, v0, v97
	v_add_f32_e32 v8, v48, v8
	s_waitcnt lgkmcnt(3)
	v_add_f32_e32 v6, v50, v6
	v_med3_i32 v48, v15, -1, v170
	v_med3_i32 v15, v15, s86, v171
	v_med3_i32 v50, v49, -1, v170
	s_nop 2
	v_add_f32_e32 v11, v64, v2
	v_sub_u32_e32 v2, v0, v94
	v_med3_i32 v12, v2, -1, v170
	v_med3_i32 v2, v2, s86, v171
	v_med3_i32 v49, v49, s86, v171
	v_lshl_add_u32 v2, v2, 2, s96
	v_lshl_add_u32 v15, v15, 2, s96
	v_lshl_add_u32 v49, v49, 2, s96
	v_lshl_add_u32 v12, v12, 2, s96
	v_add_u32_e32 v2, 0xfffff900, v2
	v_lshl_add_u32 v48, v48, 2, s96
	v_add_u32_e32 v15, 0xfffff900, v15
	v_lshl_add_u32 v50, v50, 2, s96
	v_add_u32_e32 v49, 0xfffff900, v49
	ds_read_b32 v12, v12 offset:256
	ds_read_b32 v2, v2
	ds_read_b32 v14, v14 offset:256
	ds_read_b32 v13, v13
	ds_read_b32 v48, v48 offset:256
	ds_read_b32 v15, v15
	ds_read_b32 v50, v50 offset:256
	ds_read_b32 v49, v49
	v_add_f32_e32 v4, v65, v4
	s_waitcnt lgkmcnt(9)
	v_add_f32_e32 v10, v51, v10
	s_waitcnt lgkmcnt(7)
	v_add_f32_e32 v12, v52, v12
	s_waitcnt lgkmcnt(6)
	v_add_f32_e32 v52, v68, v2
	s_waitcnt lgkmcnt(3)
	v_add_f32_e32 v48, v54, v48
	v_sub_u32_e32 v2, v0, v98
	v_sub_u32_e32 v51, v0, v99
	v_sub_u32_e32 v54, v0, v100
	v_sub_u32_e32 v65, v0, v101
	v_add_f32_e32 v5, v66, v5
	v_add_f32_e32 v14, v53, v14
	s_waitcnt lgkmcnt(1)
	v_add_f32_e32 v55, v55, v50
	v_med3_i32 v50, v2, -1, v170
	v_med3_i32 v2, v2, s86, v171
	v_med3_i32 v53, v51, -1, v170
	v_med3_i32 v51, v51, s86, v171
	v_med3_i32 v64, v54, -1, v170
	v_med3_i32 v54, v54, s86, v171
	v_med3_i32 v66, v65, -1, v170
	v_med3_i32 v65, v65, s86, v171
	v_lshl_add_u32 v2, v2, 2, s96
	v_lshl_add_u32 v51, v51, 2, s96
	v_lshl_add_u32 v54, v54, 2, s96
	v_lshl_add_u32 v65, v65, 2, s96
	v_lshl_add_u32 v50, v50, 2, s96
	v_add_u32_e32 v2, 0xfffff900, v2
	v_lshl_add_u32 v53, v53, 2, s96
	v_add_u32_e32 v51, 0xfffff900, v51
	v_lshl_add_u32 v64, v64, 2, s96
	v_add_u32_e32 v54, 0xfffff900, v54
	v_lshl_add_u32 v66, v66, 2, s96
	v_add_u32_e32 v65, 0xfffff900, v65
	ds_read_b32 v50, v50 offset:256
	ds_read_b32 v2, v2
	ds_read_b32 v53, v53 offset:256
	ds_read_b32 v51, v51
	ds_read_b32 v64, v64 offset:256
	ds_read_b32 v54, v54
	ds_read_b32 v66, v66 offset:256
	ds_read_b32 v65, v65
	v_add_f32_e32 v7, v67, v7
	s_waitcnt lgkmcnt(6)
	v_add_f32_e32 v67, v72, v2
	s_waitcnt lgkmcnt(4)
	v_add_f32_e32 v68, v73, v51
	s_waitcnt lgkmcnt(3)
	v_add_f32_e32 v58, v58, v64
	s_waitcnt lgkmcnt(2)
	v_add_f32_e32 v64, v74, v54
	v_sub_u32_e32 v2, v0, v102
	v_sub_u32_e32 v51, v0, v103
	v_sub_u32_e32 v54, v0, v104
	v_sub_u32_e32 v0, v0, v105
	v_add_f32_e32 v13, v69, v13
	v_add_f32_e32 v56, v56, v50
	v_add_f32_e32 v57, v57, v53
	s_waitcnt lgkmcnt(1)
	v_add_f32_e32 v59, v59, v66
	v_med3_i32 v50, v2, -1, v170
	v_med3_i32 v2, v2, s86, v171
	v_med3_i32 v53, v51, -1, v170
	v_med3_i32 v51, v51, s86, v171
	v_med3_i32 v66, v54, -1, v170
	v_med3_i32 v54, v54, s86, v171
	v_med3_i32 v69, v0, -1, v170
	v_med3_i32 v0, v0, s86, v171
	v_lshl_add_u32 v2, v2, 2, s96
	v_lshl_add_u32 v51, v51, 2, s96
	v_lshl_add_u32 v54, v54, 2, s96
	v_lshl_add_u32 v0, v0, 2, s96
	v_lshl_add_u32 v50, v50, 2, s96
	v_add_u32_e32 v2, 0xfffff900, v2
	v_lshl_add_u32 v53, v53, 2, s96
	v_add_u32_e32 v51, 0xfffff900, v51
	v_lshl_add_u32 v66, v66, 2, s96
	v_add_u32_e32 v54, 0xfffff900, v54
	v_lshl_add_u32 v69, v69, 2, s96
	v_add_u32_e32 v0, 0xfffff900, v0
	ds_read_b32 v50, v50 offset:256
	ds_read_b32 v2, v2
	ds_read_b32 v53, v53 offset:256
	ds_read_b32 v51, v51
	ds_read_b32 v66, v66 offset:256
	ds_read_b32 v54, v54
	ds_read_b32 v69, v69 offset:256
	ds_read_b32 v0, v0
	v_add_f32_e32 v15, v70, v15
	v_add_f32_e32 v49, v71, v49
	s_waitcnt lgkmcnt(7)
	v_add_f32_e32 v70, v60, v50
	s_waitcnt lgkmcnt(1)
	v_add_f32_e32 v63, v63, v69
	s_waitcnt lgkmcnt(0)
	v_add_f32_e32 v69, v79, v0
	v_max_f32_e32 v0, v9, v4
	v_add_f32_e32 v71, v76, v2
	v_max3_f32 v0, v8, v11, v0
	v_max_f32_e32 v2, v6, v5
	v_max_f32_e32 v50, v10, v7
	v_max3_f32 v0, v0, v2, v50
	v_max_f32_e32 v2, v12, v52
	v_max_f32_e32 v50, v14, v13
	v_max3_f32 v0, v0, v2, v50
	v_max_f32_e32 v2, v48, v15
	v_max_f32_e32 v50, v55, v49
	v_add_f32_e32 v65, v75, v65
	v_max3_f32 v0, v0, v2, v50
	v_max_f32_e32 v2, v56, v67
	v_max_f32_e32 v50, v57, v68
	v_add_f32_e32 v72, v61, v53
	v_add_f32_e32 v73, v77, v51
	v_max3_f32 v0, v0, v2, v50
	v_max_f32_e32 v2, v58, v64
	v_max_f32_e32 v50, v59, v65
	v_add_f32_e32 v62, v62, v66
	v_add_f32_e32 v74, v78, v54
	v_max3_f32 v0, v0, v2, v50
	v_max_f32_e32 v2, v70, v71
	v_max_f32_e32 v50, v72, v73
	v_max3_f32 v0, v0, v2, v50
	v_max_f32_e32 v2, v62, v74
	v_max_f32_e32 v50, v63, v69
	v_max3_f32 v0, v0, v2, v50
	v_mov_b32_e32 v2, v0
	s_nop 1
	v_permlane32_swap_b32_e32 v0, v2
	v_max_f32_e32 v2, v2, v2
	v_max_f32_e32 v0, v0, v0
	v_max_f32_e32 v0, v0, v2
	v_max3_f32 v66, v81, v0, s55
	v_sub_f32_e32 v0, v81, v66
	v_exp_f32_e32 v2, v0
	v_sub_f32_e32 v0, v8, v66
	v_exp_f32_e32 v75, v0
	v_sub_f32_e32 v0, v11, v66
	v_exp_f32_e32 v92, v0
	v_sub_f32_e32 v0, v9, v66
	v_exp_f32_e32 v50, v0
	v_sub_f32_e32 v0, v4, v66
	v_sub_f32_e32 v4, v10, v66
	v_sub_f32_e32 v6, v6, v66
	v_sub_f32_e32 v5, v5, v66
	v_exp_f32_e32 v60, v4
	v_sub_f32_e32 v4, v7, v66
	v_exp_f32_e32 v76, v6
	v_exp_f32_e32 v93, v5
	v_sub_f32_e32 v5, v12, v66
	v_exp_f32_e32 v6, v4
	v_sub_f32_e32 v4, v14, v66
	v_exp_f32_e32 v77, v5
	v_sub_f32_e32 v5, v52, v66
	v_exp_f32_e32 v52, v4
	v_sub_f32_e32 v4, v13, v66
	v_sub_f32_e32 v10, v58, v66
	v_exp_f32_e32 v54, v4
	v_sub_f32_e32 v4, v55, v66
	v_exp_f32_e32 v55, v10
	v_sub_f32_e32 v10, v64, v66
	v_exp_f32_e32 v95, v10
	v_sub_f32_e32 v10, v68, v66
	v_exp_f32_e32 v94, v5
	v_sub_f32_e32 v5, v48, v66
	v_sub_f32_e32 v8, v56, v66
	v_exp_f32_e32 v14, v10
	v_sub_f32_e32 v10, v59, v66
	v_sub_f32_e32 v56, v62, v66
	v_sub_f32_e32 v62, v69, v66
	v_add_f32_e32 v68, v75, v50
	v_add_f32_e32 v69, v76, v60
	v_exp_f32_e32 v7, v5
	v_exp_f32_e32 v4, v4
	v_sub_f32_e32 v11, v70, v66
	v_exp_f32_e32 v48, v10
	v_sub_f32_e32 v10, v65, v66
	v_exp_f32_e32 v65, v56
	v_sub_f32_e32 v56, v74, v66
	v_add_f32_e32 v68, v68, v69
	v_mov_b32_e32 v69, v60
	v_mov_b32_e32 v70, v60
	v_exp_f32_e32 v97, v56
	v_sub_f32_e32 v56, v73, v66
	v_permlane32_swap_b32_e32 v69, v70
	v_exp_f32_e32 v58, v56
	v_sub_f32_e32 v56, v63, v66
	v_mul_f32_e32 v63, v2, v106
	v_cndmask_b32_e64 v69, v69, v70, s[4:5]
	v_exp_f32_e32 v13, v8
	v_sub_f32_e32 v8, v67, v66
	v_cndmask_b32_e64 v63, v69, v63, s[4:5]
	v_exp_f32_e32 v67, v8
	v_sub_f32_e32 v8, v49, v66
	v_add_f32_e32 v63, v68, v63
	v_add_f32_e32 v68, v77, v52
	v_add_f32_e32 v70, v7, v4
	v_exp_f32_e32 v12, v8
	v_sub_f32_e32 v8, v57, v66
	v_exp_f32_e32 v59, v11
	v_sub_f32_e32 v11, v71, v66
	v_add_f32_e32 v68, v68, v70
	v_mov_b32_e32 v70, v4
	v_mov_b32_e32 v71, v4
	v_exp_f32_e32 v8, v8
	s_nop 0
	v_permlane32_swap_b32_e32 v70, v71
	v_cndmask_b32_e64 v70, v70, v71, s[4:5]
	v_cndmask_b32_e64 v69, v70, v69, s[4:5]
	v_add_f32_e32 v68, v69, v68
	v_exp_f32_e32 v64, v10
	v_sub_f32_e32 v10, v72, v66
	ds_write2_b32 v88, v63, v68 offset0:16 offset1:18
	v_add_f32_e32 v63, v13, v8
	v_add_f32_e32 v68, v55, v48
	v_exp_f32_e32 v10, v10
	v_exp_f32_e32 v56, v56
	v_add_f32_e32 v63, v63, v68
	v_mov_b32_e32 v68, v48
	v_mov_b32_e32 v69, v48
	s_nop 1
	v_permlane32_swap_b32_e32 v68, v69
	v_cndmask_b32_e64 v68, v68, v69, s[4:5]
	v_cndmask_b32_e64 v69, v68, v70, s[4:5]
	v_add_f32_e32 v63, v63, v69
	v_add_f32_e32 v69, v59, v10
	v_add_f32_e32 v70, v65, v56
	v_add_f32_e32 v69, v69, v70
	v_mov_b32_e32 v70, v56
	v_mov_b32_e32 v71, v56
	v_exp_f32_e32 v0, v0
	s_nop 0
	v_permlane32_swap_b32_e32 v70, v71
	v_cndmask_b32_e64 v70, v70, v71, s[4:5]
	v_cndmask_b32_e64 v68, v70, v68, s[4:5]
	v_add_f32_e32 v68, v69, v68
	v_sub_f32_e32 v5, v15, v66
	ds_write2_b32 v88, v63, v68 offset0:20 offset1:22
	v_add_f32_e32 v63, v92, v0
	v_add_f32_e32 v68, v93, v6
	v_exp_f32_e32 v15, v5
	v_add_f32_e32 v63, v63, v68
	v_mov_b32_e32 v68, v6
	v_mov_b32_e32 v69, v6
	s_nop 1
	v_permlane32_swap_b32_e32 v68, v69
	v_cndmask_b32_e64 v68, v68, v69, s[4:5]
	v_cndmask_b32_e64 v69, v68, v70, s[4:5]
	v_add_f32_e32 v63, v63, v69
	v_add_f32_e32 v69, v94, v54
	v_add_f32_e32 v70, v15, v12
	v_add_f32_e32 v69, v69, v70
	v_mov_b32_e32 v70, v12
	v_mov_b32_e32 v71, v12
	s_nop 1
	v_permlane32_swap_b32_e32 v70, v71
	v_cndmask_b32_e64 v70, v70, v71, s[4:5]
	v_cndmask_b32_e64 v68, v70, v68, s[4:5]
	v_add_f32_e32 v68, v69, v68
	ds_write2_b32 v88, v63, v68 offset0:24 offset1:26
	v_add_f32_e32 v63, v67, v14
	v_add_f32_e32 v68, v95, v64
	v_exp_f32_e32 v96, v11
	v_exp_f32_e32 v62, v62
	v_add_f32_e32 v63, v63, v68
	v_mov_b32_e32 v68, v64
	v_mov_b32_e32 v69, v64
	s_nop 1
	v_permlane32_swap_b32_e32 v68, v69
	v_cndmask_b32_e64 v68, v68, v69, s[4:5]
	v_cndmask_b32_e64 v69, v68, v70, s[4:5]
	v_add_f32_e32 v63, v63, v69
	v_add_f32_e32 v69, v96, v58
	v_add_f32_e32 v70, v97, v62
	v_add_f32_e32 v69, v69, v70
	v_mov_b32_e32 v70, v62
	v_mov_b32_e32 v71, v62
	s_nop 1
	v_permlane32_swap_b32_e32 v70, v71
	v_cndmask_b32_e64 v70, v70, v71, s[4:5]
	v_cndmask_b32_e64 v68, v70, v68, s[4:5]
	v_add_f32_e32 v68, v69, v68
	ds_write2_b32 v88, v63, v68 offset0:28 offset1:30
	v_add_u32_e32 v63, s82, v128
	v_add3_u32 v98, v63, v181, v180
	v_add_f32_e32 v51, v75, v92
	v_cvt_pk_bf16_f32 v68, v75, v50
	ds_read_b64_tr_b16 v[72:73], v98
	ds_read_b64_tr_b16 v[74:75], v98 offset:1024
	v_add_u32_e32 v63, v63, v182
	v_add_f32_e32 v61, v76, v93
	v_add_f32_e32 v53, v77, v94
	v_cvt_pk_bf16_f32 v69, v76, v60
	v_cvt_pk_bf16_f32 v70, v77, v52
	ds_read_b64_tr_b16 v[76:77], v63
	ds_read_b64_tr_b16 v[78:79], v63 offset:1024
	ds_read_b64_tr_b16 v[88:89], v98 offset:2048
	ds_read_b64_tr_b16 v[90:91], v98 offset:3072
	v_mul_f32_e32 v30, v30, v2
	v_mul_f32_e32 v31, v31, v2
	v_mul_f32_e32 v28, v28, v2
	v_mul_f32_e32 v29, v29, v2
	v_mul_f32_e32 v26, v26, v2
	v_mul_f32_e32 v27, v27, v2
	v_mul_f32_e32 v24, v24, v2
	v_mul_f32_e32 v25, v25, v2
	v_mul_f32_e32 v22, v22, v2
	v_mul_f32_e32 v23, v23, v2
	v_mul_f32_e32 v20, v20, v2
	v_mul_f32_e32 v21, v21, v2
	v_mul_f32_e32 v18, v18, v2
	v_mul_f32_e32 v19, v19, v2
	v_mul_f32_e32 v16, v16, v2
	v_mul_f32_e32 v17, v17, v2
	v_mul_f32_e32 v46, v46, v2
	v_mul_f32_e32 v47, v47, v2
	v_mul_f32_e32 v44, v44, v2
	v_mul_f32_e32 v45, v45, v2
	v_mul_f32_e32 v42, v42, v2
	v_mul_f32_e32 v43, v43, v2
	v_mul_f32_e32 v40, v40, v2
	v_mul_f32_e32 v41, v41, v2
	v_mul_f32_e32 v38, v38, v2
	v_mul_f32_e32 v39, v39, v2
	v_cvt_pk_bf16_f32 v71, v7, v4
	v_mul_f32_e32 v36, v36, v2
	v_mul_f32_e32 v37, v37, v2
	v_mul_f32_e32 v34, v34, v2
	v_mul_f32_e32 v35, v35, v2
	v_mul_f32_e32 v32, v32, v2
	v_mul_f32_e32 v33, v33, v2
	s_waitcnt lgkmcnt(4)
; __device__ __forceinline__ float xor32_add(float x) { auto r = __builtin_amdgcn_permlane32_swap(__float_as_uint(x), __float_as_uint(x), false, false); return __uint_as_float(r[0]) + __uint_as_float(r[1]); }
; __device__ __forceinline__ void nsa_unit(int b, int g, int tq, const Args& a, LAS unsigned char* lds, int tid, int wave, int lane, int& nxt) {
;     ...
;         CMP_TILE(0);
;         const float m_t0 = mx;
;         if (nct > 1) CMP_TILE(1);
;         sum = xor32_add(sum);
	v_mfma_f32_32x32x16_bf16 v[16:31], v[72:75], v[68:71], v[16:31]
	ds_read_b64_tr_b16 v[72:73], v63 offset:2048
	ds_read_b64_tr_b16 v[74:75], v63 offset:3072
	v_add_f32_e64 v50, v50, v0
	v_add_f32_e64 v51, v51, v1
	v_add_f32_e32 v5, v7, v15
	v_add_f32_e32 v51, v50, v51
	v_add_f32_e32 v50, v50, v50
	v_mov_b32_e32 v7, v51
	v_add_f32_e32 v50, v60, v6
	v_add_f32_e32 v51, v61, v7
	v_add_f32_e32 v49, v55, v95
	s_waitcnt lgkmcnt(4)
	v_mfma_f32_32x32x16_bf16 v[32:47], v[76:79], v[68:71], v[32:47]
	v_cvt_pk_bf16_f32 v68, v13, v8
	v_cvt_pk_bf16_f32 v69, v55, v48
	v_cvt_pk_bf16_f32 v70, v59, v10
	v_cvt_pk_bf16_f32 v71, v65, v56
	v_add_f32_e32 v51, v50, v51
	v_add_f32_e32 v50, v50, v50
	v_mov_b32_e32 v55, v51
	ds_read_b64_tr_b16 v[76:77], v98 offset:4096
	ds_read_b64_tr_b16 v[78:79], v98 offset:5120
	s_waitcnt lgkmcnt(4)
	v_mfma_f32_32x32x16_bf16 v[16:31], v[88:91], v[68:71], v[16:31]
	v_add_f32_e64 v50, v52, v54
	v_add_f32_e64 v51, v53, v55
	v_add_f32_e32 v9, v13, v67
	v_add_f32_e32 v51, v50, v51
	v_add_f32_e32 v50, v50, v50
	v_mov_b32_e32 v13, v51
	v_cvt_pk_bf16_f32 v50, v92, v0
	v_cvt_pk_bf16_f32 v51, v93, v6
	v_cvt_pk_bf16_f32 v52, v94, v54
	s_waitcnt lgkmcnt(2)
	v_mfma_f32_32x32x16_bf16 v[32:47], v[72:75], v[68:71], v[32:47]
	ds_read_b64_tr_b16 v[68:69], v63 offset:4096
	ds_read_b64_tr_b16 v[70:71], v63 offset:5120
	ds_read_b64_tr_b16 v[72:73], v98 offset:6144
	ds_read_b64_tr_b16 v[74:75], v98 offset:7168
	v_cvt_pk_bf16_f32 v53, v15, v12
	v_add_f32_e32 v4, v4, v12
	v_add_f32_e32 v5, v5, v13
	v_add_f32_e32 v57, v65, v97
	v_add_f32_e32 v5, v4, v5
	v_add_f32_e32 v4, v4, v4
	v_mov_b32_e32 v15, v5
	v_add_f32_e32 v4, v8, v14
	v_add_f32_e32 v5, v9, v15
	s_waitcnt lgkmcnt(4)
	v_mfma_f32_32x32x16_bf16 v[16:31], v[76:79], v[50:53], v[16:31]
	v_add_f32_e64 v8, v4, v4
	v_add_f32_e64 v9, v4, v5
	ds_read_b64_tr_b16 v[4:5], v63 offset:6144
	ds_read_b64_tr_b16 v[6:7], v63 offset:7168
	v_mov_b32_e32 v65, v9
	v_add_f32_e32 v8, v48, v64
	v_add_f32_e32 v9, v49, v65
	v_cvt_pk_bf16_f32 v12, v67, v14
	v_add_f32_e32 v9, v8, v9
	v_add_f32_e32 v8, v8, v8
	v_cvt_pk_bf16_f32 v13, v95, v64
	s_waitcnt lgkmcnt(4)
	v_mfma_f32_32x32x16_bf16 v[32:47], v[68:71], v[50:53], v[32:47]
	v_cvt_pk_bf16_f32 v14, v96, v58
	v_cvt_pk_bf16_f32 v15, v97, v62
	v_add_f32_e32 v11, v59, v96
	v_mov_b32_e32 v59, v9
	v_add_f32_e64 v8, v10, v58
	v_add_f32_e64 v9, v11, v59
	v_add_f32_e32 v9, v8, v9
	v_add_f32_e32 v8, v8, v8
	s_waitcnt lgkmcnt(2)
	v_mfma_f32_32x32x16_bf16 v[16:31], v[72:75], v[12:15], v[16:31]
	v_mov_b32_e32 v63, v9
	v_add_f32_e64 v8, v56, v62
	v_add_f32_e64 v9, v57, v63
	v_add_f32_e32 v0, v8, v9
	v_fmac_f32_e32 v0, v3, v2
	v_mov_b32_e32 v3, v0
	s_waitcnt lgkmcnt(0)
	v_mfma_f32_32x32x16_bf16 v[32:47], v[4:7], v[12:15], v[32:47]
	s_branch .LBB0_900

; #define LAS __attribute__((address_space(3)))
;     ...
;         if (j + 3 <= tq) { const float c = sel ? cfar - m : NEG;
; #pragma unroll
;             for (int r = 0; r < 16; ++r) { X0[r] = c; X1[r] = c; }
;         } else { LAS const float* ab = aux + (t - kb + 1);
; #pragma unroll
;             for (int r = 0; r < 16; ++r) { X0[r] = ab[63 - ((r & 3) + 8 * (r >> 2))] - m; X1[r] = ab[31 - ((r & 3) + 8 * (r >> 2))] - m; }
;             if (MODE == 1 && !sel) {
; #pragma unroll
;                 for (int r = 0; r < 16; ++r) { X0[r] = NEG; X1[r] = NEG; } }
;         }
;         if (MODE == 2 && j + 8 == tq) {
; #pragma unroll
;             for (int r = 0; r < 16; ++r) { const int d0 = t - (kb + (r & 3) + 8 * (r >> 2)); if (d0 >= 512) X0[r] = NEG; if (d0 - 32 >= 512) X1[r] = NEG; } }
.LBB0_958:
	v_lshl_or_b32 v2, s14, 6, v179
	s_andn2_b64 vcc, exec, s[6:7]
	v_sub_u32_e32 v3, v178, v2
	s_nop 3
	v_mov_b32_e32 v80, v95
	v_mov_b32_e32 v81, v95
	v_mov_b32_e32 v82, v95
	v_mov_b32_e32 v83, v95
	v_mov_b32_e32 v84, v95
	v_mov_b32_e32 v85, v95
	v_mov_b32_e32 v86, v95
	v_mov_b32_e32 v87, v95
	v_mov_b32_e32 v88, v95
	v_mov_b32_e32 v89, v95
	v_mov_b32_e32 v90, v95
	v_mov_b32_e32 v91, v95
	v_mov_b32_e32 v92, v95
	v_mov_b32_e32 v93, v95
	v_mov_b32_e32 v94, v95
	s_cbranch_vccnz .LBB0_960
	v_lshl_add_u32 v96, v3, 2, s96
	ds_read2_b32 v[4:5], v96 offset0:63 offset1:64
	ds_read2_b32 v[6:7], v96 offset0:31 offset1:32
	ds_read2_b32 v[8:9], v96 offset0:61 offset1:62
	ds_read2_b32 v[10:11], v96 offset0:29 offset1:30
	ds_read2_b32 v[14:15], v96 offset0:23 offset1:24
	ds_read2_b32 v[82:83], v96 offset0:21 offset1:22
	ds_read2_b32 v[86:87], v96 offset0:15 offset1:16
	ds_read2_b32 v[90:91], v96 offset0:13 offset1:14
	ds_read2_b32 v[12:13], v96 offset0:55 offset1:56
	ds_read2_b32 v[80:81], v96 offset0:53 offset1:54
	ds_read2_b32 v[84:85], v96 offset0:47 offset1:48
	s_waitcnt lgkmcnt(5)
	v_sub_f32_e32 v88, v82, v0
	v_sub_f32_e32 v89, v83, v0
	ds_read2_b32 v[82:83], v96 offset0:45 offset1:46
	s_waitcnt lgkmcnt(5)
	v_sub_f32_e32 v92, v86, v0
	v_sub_f32_e32 v93, v87, v0
	ds_read2_b32 v[86:87], v96 offset0:39 offset1:40
	ds_read2_b32 v[94:95], v96 offset0:7 offset1:8
	ds_read2_b32 v[112:113], v96 offset0:5 offset1:6
	ds_read2_b32 v[96:97], v96 offset0:37 offset1:38
	v_sub_f32_e32 v4, v4, v0
	v_sub_f32_e32 v5, v5, v0
	v_sub_f32_e32 v6, v6, v0
	v_sub_f32_e32 v7, v7, v0
	v_sub_f32_e32 v8, v8, v0
	v_sub_f32_e32 v9, v9, v0
	v_sub_f32_e32 v10, v10, v0
	v_sub_f32_e32 v11, v11, v0
	s_waitcnt lgkmcnt(7)
	v_sub_f32_e32 v12, v12, v0
	v_sub_f32_e32 v13, v13, v0
	v_sub_f32_e32 v14, v14, v0
	v_sub_f32_e32 v15, v15, v0
	s_waitcnt lgkmcnt(6)
	v_sub_f32_e32 v80, v80, v0
	v_sub_f32_e32 v81, v81, v0
	s_waitcnt lgkmcnt(5)
	v_sub_f32_e32 v84, v84, v0
	v_sub_f32_e32 v85, v85, v0
	s_waitcnt lgkmcnt(4)
	v_sub_f32_e32 v82, v82, v0
	v_sub_f32_e32 v83, v83, v0
	v_sub_f32_e32 v114, v90, v0
	v_sub_f32_e32 v115, v91, v0
	s_waitcnt lgkmcnt(3)
	v_sub_f32_e32 v86, v86, v0
	v_sub_f32_e32 v87, v87, v0
	s_waitcnt lgkmcnt(2)
	v_sub_f32_e32 v116, v94, v0
	v_sub_f32_e32 v117, v95, v0
	s_waitcnt lgkmcnt(0)
	v_sub_f32_e32 v90, v96, v0
	v_sub_f32_e32 v91, v97, v0
	v_sub_f32_e32 v94, v113, v0
	v_mov_b32_e32 v96, v5
	v_mov_b32_e32 v97, v4
	v_mov_b32_e32 v98, v9
	v_mov_b32_e32 v99, v8
	v_mov_b32_e32 v100, v13
	v_mov_b32_e32 v101, v12
	v_mov_b32_e32 v102, v81
	v_mov_b32_e32 v103, v80
	v_mov_b32_e32 v104, v85
	v_mov_b32_e32 v105, v84
	v_mov_b32_e32 v106, v83
	v_mov_b32_e32 v107, v82
	v_mov_b32_e32 v108, v87
	v_mov_b32_e32 v109, v86
	v_mov_b32_e32 v110, v91
	v_mov_b32_e32 v111, v90
	v_sub_f32_e32 v95, v112, v0
	v_mov_b32_e32 v112, v7
	v_mov_b32_e32 v80, v7
	v_mov_b32_e32 v81, v6
	v_mov_b32_e32 v82, v11
	v_mov_b32_e32 v83, v10
	v_mov_b32_e32 v84, v15
	v_mov_b32_e32 v85, v14
	v_mov_b32_e32 v86, v89
	v_mov_b32_e32 v87, v88
	v_mov_b32_e32 v88, v93
	v_mov_b32_e32 v89, v92
	v_mov_b32_e32 v90, v115
	v_mov_b32_e32 v91, v114
	v_mov_b32_e32 v92, v117
	v_mov_b32_e32 v93, v116

.LBB0_968:
	s_and_b64 vcc, exec, s[6:7]
	s_cbranch_vccz .LBB0_972
	s_and_b64 vcc, exec, s[4:5]
	s_cbranch_vccnz .LBB0_971
	v_exp_f32_e64 v4, -v2
	s_nop 0
	v_mul_f32_e32 v167, v167, v4
	v_mul_f32_e32 v62, v62, v4
	v_mul_f32_e32 v63, v63, v4
	v_mul_f32_e32 v60, v60, v4
	v_mul_f32_e32 v61, v61, v4
	v_mul_f32_e32 v58, v58, v4
	v_mul_f32_e32 v59, v59, v4
	v_mul_f32_e32 v56, v56, v4
	v_mul_f32_e32 v57, v57, v4
	v_mul_f32_e32 v54, v54, v4
	v_mul_f32_e32 v55, v55, v4
	v_mul_f32_e32 v52, v52, v4
	v_mul_f32_e32 v53, v53, v4
	v_mul_f32_e32 v50, v50, v4
	v_mul_f32_e32 v51, v51, v4
	v_mul_f32_e32 v48, v48, v4
	v_mul_f32_e32 v49, v49, v4
	v_mul_f32_e32 v78, v78, v4
	v_mul_f32_e32 v79, v79, v4
	v_mul_f32_e32 v76, v76, v4
	v_mul_f32_e32 v77, v77, v4
	v_mul_f32_e32 v74, v74, v4
	v_mul_f32_e32 v75, v75, v4
	v_mul_f32_e32 v72, v72, v4
	v_mul_f32_e32 v73, v73, v4
	v_mul_f32_e32 v70, v70, v4
	v_mul_f32_e32 v71, v71, v4
	v_mul_f32_e32 v68, v68, v4
	v_mul_f32_e32 v69, v69, v4
	v_mul_f32_e32 v66, v66, v4
	v_mul_f32_e32 v67, v67, v4
	v_mul_f32_e32 v64, v64, v4
	v_mul_f32_e32 v65, v65, v4

; template <int MODE> __device__ __forceinline__ int pop_tile(unsigned& tiles) { int j; if (MODE == 2) { j = 31 - __builtin_clz(tiles); tiles &= ~(1u << j); } else { j = __builtin_ctz(tiles); tiles &= tiles - 1u; } return j; }
; #define NL_WAITBAR(n) do { asm volatile("s_waitcnt vmcnt(" #n ") lgkmcnt(0)" ::: "memory"); __builtin_amdgcn_s_barrier(); asm volatile("" ::: "memory"); } while (0)
; __device__ __forceinline__ void nsa_unit(int b, int g, int tq, const Args& a, LAS unsigned char* lds, int tid, int wave, int lane, int& nxt) {
;     ...
;         NL_WAITBAR(2);
;         {
;             float m = 0.f, l = 0.f; bool first = true; f32x16 oa = {}, ob = {};
;             for (;;) {
;                 int j2, m2; if (wt) { j2 = pop_tile<2>(wt); m2 = 2; } else if (ut) { j2 = pop_tile<1>(ut); m2 = 1; } else { j2 = -1; m2 = 2; }
;                 NL_DMA(m2, (j2 >= 0 ? j2 : j0), o2);
;                 NL_STEP(2, 0u);
;                 NL_WAITBAR(2);
;                 j0 = j1; m0 = m1; j1 = j2; m1 = m2; { const int ot = o0; o0 = o1; o1 = o2; o2 = ot; }
;                 if (m0 != 2) break;
.LBB0_972:
	v_add_u32_e32 v10, s50, v188
	v_add3_u32 v114, v10, v181, v180
	v_exp_f32_e32 v14, v96
	v_exp_f32_e32 v15, v97
	v_exp_f32_e32 v98, v98
	v_exp_f32_e32 v99, v99
	v_exp_f32_e32 v100, v100
	v_exp_f32_e32 v101, v101
	v_exp_f32_e32 v102, v102
	v_exp_f32_e32 v103, v103
	ds_read_b64_tr_b16 v[6:7], v114 offset:8192
	ds_read_b64_tr_b16 v[8:9], v114 offset:9216
	v_add_u32_e32 v115, v10, v182
	v_exp_f32_e32 v96, v80
	v_exp_f32_e32 v97, v81
	v_exp_f32_e32 v112, v82
	v_exp_f32_e32 v113, v83
	ds_read_b64_tr_b16 v[10:11], v115 offset:8192
	ds_read_b64_tr_b16 v[12:13], v115 offset:9216
	ds_read_b64_tr_b16 v[80:81], v114 offset:10240
	ds_read_b64_tr_b16 v[82:83], v114 offset:11264
	v_cvt_pk_bf16_f32 v2, v14, v15
	v_cvt_pk_bf16_f32 v3, v98, v99
	v_cvt_pk_bf16_f32 v4, v100, v101
	v_cvt_pk_bf16_f32 v5, v102, v103
	v_exp_f32_e32 v104, v104
	v_exp_f32_e32 v105, v105
	s_waitcnt lgkmcnt(4)
	v_mfma_f32_32x32x16_bf16 v[48:63], v[6:9], v[2:5], v[48:63]
	v_exp_f32_e32 v106, v106
	v_exp_f32_e32 v107, v107
	v_exp_f32_e32 v108, v108
	v_exp_f32_e32 v109, v109
	ds_read_b64_tr_b16 v[6:7], v115 offset:10240
	ds_read_b64_tr_b16 v[8:9], v115 offset:11264
	v_exp_f32_e32 v110, v110
	v_exp_f32_e32 v111, v111
	s_waitcnt lgkmcnt(4)
	v_mfma_f32_32x32x16_bf16 v[64:79], v[10:13], v[2:5], v[64:79]
	v_cvt_pk_bf16_f32 v2, v104, v105
	v_cvt_pk_bf16_f32 v3, v106, v107
	v_cvt_pk_bf16_f32 v4, v108, v109
	v_cvt_pk_bf16_f32 v5, v110, v111
	v_exp_f32_e32 v84, v84
	v_exp_f32_e32 v85, v85
	v_exp_f32_e32 v86, v86
	s_waitcnt lgkmcnt(2)
	v_mfma_f32_32x32x16_bf16 v[48:63], v[80:83], v[2:5], v[48:63]
	v_exp_f32_e32 v87, v87
	ds_read_b64_tr_b16 v[80:81], v114 offset:12288
	ds_read_b64_tr_b16 v[82:83], v114 offset:13312
	v_cvt_pk_bf16_f32 v10, v96, v97
	v_cvt_pk_bf16_f32 v11, v112, v113
	v_cvt_pk_bf16_f32 v12, v84, v85
	v_cvt_pk_bf16_f32 v13, v86, v87
	v_exp_f32_e32 v92, v92
	s_waitcnt lgkmcnt(2)
	v_mfma_f32_32x32x16_bf16 v[64:79], v[6:9], v[2:5], v[64:79]
	ds_read_b64_tr_b16 v[2:3], v115 offset:12288
	ds_read_b64_tr_b16 v[4:5], v115 offset:13312
	ds_read_b64_tr_b16 v[6:7], v114 offset:14336
	ds_read_b64_tr_b16 v[8:9], v114 offset:15360
	v_exp_f32_e32 v93, v93
	v_exp_f32_e32 v88, v88
	v_exp_f32_e32 v89, v89
	v_exp_f32_e32 v90, v90
	v_exp_f32_e32 v91, v91
	v_exp_f32_e32 v94, v94
	s_waitcnt lgkmcnt(4)
	v_mfma_f32_32x32x16_bf16 v[48:63], v[80:83], v[10:13], v[48:63]
	v_exp_f32_e32 v95, v95
	ds_read_b64_tr_b16 v[80:81], v115 offset:14336
	ds_read_b64_tr_b16 v[82:83], v115 offset:15360
	v_add_f32_e32 v14, v96, v14
	v_add_f32_e32 v15, v97, v15
	v_add_f32_e32 v96, v92, v108
	v_add_f32_e32 v97, v93, v109
	v_add_f32_e32 v106, v90, v106
	v_add_f32_e32 v107, v91, v107
	v_add_f32_e32 v98, v112, v98
	v_add_f32_e32 v99, v113, v99
	v_add_f32_e32 v110, v94, v110
	v_add_f32_e32 v111, v95, v111
	s_waitcnt lgkmcnt(4)
	v_mfma_f32_32x32x16_bf16 v[64:79], v[2:5], v[10:13], v[64:79]
	v_add_f32_e64 v2, v84, v100
	v_add_f32_e64 v3, v85, v101
	v_cvt_pk_bf16_f32 v4, v92, v93
	v_add_f32_e64 v10, v2, v96
	v_add_f32_e64 v11, v3, v97
	v_cvt_pk_bf16_f32 v2, v88, v89
	v_cvt_pk_bf16_f32 v3, v90, v91
	v_cvt_pk_bf16_f32 v5, v94, v95
	v_add_f32_e32 v86, v86, v102
	v_add_f32_e32 v87, v87, v103
	v_add_f32_e32 v102, v88, v104
	v_add_f32_e32 v103, v89, v105
	s_waitcnt lgkmcnt(2)
	v_mfma_f32_32x32x16_bf16 v[48:63], v[6:9], v[2:5], v[48:63]
	v_add_f32_e64 v12, v14, v102
	v_add_f32_e64 v13, v15, v103
	v_add_f32_e64 v6, v86, v110
	v_add_f32_e64 v7, v87, v111
	v_add_f32_e64 v8, v98, v106
	v_add_f32_e64 v9, v99, v107
	s_waitcnt vmcnt(2) lgkmcnt(0)
	s_barrier
	v_add_f32_e32 v6, v8, v6
	v_add_f32_e32 v7, v9, v7
	v_add_f32_e32 v8, v12, v10
	v_add_f32_e32 v9, v13, v11
	s_waitcnt lgkmcnt(0)
	v_mfma_f32_32x32x16_bf16 v[64:79], v[80:83], v[2:5], v[64:79]
	v_add_f32_e64 v6, v8, v6
	v_add_f32_e64 v7, v9, v7
	s_cmp_eq_u32 s54, 2
	v_add_f32_e32 v6, v6, v7
	v_add_f32_e32 v167, v167, v6
	s_mov_b64 s[62:63], 0
	s_cbranch_scc0 .LBB0_975
	s_mov_b32 s4, s50
	s_mov_b32 s50, s1
	s_mov_b32 s54, s87
	s_mov_b32 s14, s44
	s_branch .LBB0_946

; __device__ __forceinline__ float xor32_add(float x) { auto r = __builtin_amdgcn_permlane32_swap(__float_as_uint(x), __float_as_uint(x), false, false); return __uint_as_float(r[0]) + __uint_as_float(r[1]); }
; template <int MODE> __device__ __forceinline__ int pop_tile(unsigned& tiles) { int j; if (MODE == 2) { j = 31 - __builtin_clz(tiles); tiles &= ~(1u << j); } else { j = __builtin_ctz(tiles); tiles &= tiles - 1u; } return j; }
; #define NL_WAITBAR(n) do { asm volatile("s_waitcnt vmcnt(" #n ") lgkmcnt(0)" ::: "memory"); __builtin_amdgcn_s_barrier(); asm volatile("" ::: "memory"); } while (0)
; __device__ __forceinline__ void nsa_unit(int b, int g, int tq, const Args& a, LAS unsigned char* lds, int tid, int wave, int lane, int& nxt) {
;     ...
;         NL_WAITBAR(2);
;         {
;             float m = 0.f, l = 0.f; bool first = true; f32x16 oa = {}, ob = {};
;             for (;;) {
;                 int j2, m2; if (wt) { j2 = pop_tile<2>(wt); m2 = 2; } else if (ut) { j2 = pop_tile<1>(ut); m2 = 1; } else { j2 = -1; m2 = 2; }
;                 NL_DMA(m2, (j2 >= 0 ? j2 : j0), o2);
;                 NL_STEP(2, 0u);
;                 NL_WAITBAR(2);
;                 j0 = j1; m0 = m1; j1 = j2; m1 = m2; { const int ot = o0; o0 = o1; o1 = o2; o2 = ot; }
;                 if (m0 != 2) break;
;             }
;             const float lt = xor32_add(l); const float sc = (lt > 0.f) ? g_w / lt : 0.f; acc0 += oa * sc; acc1 += ob * sc;
;         }
;         {
;             float m = 0.f, l = 0.f; bool first = true; f32x16 oa = {}, ob = {};
;             for (;;) {
;                 const int j2 = ut ? pop_tile<1>(ut) : -1;
;                 NL_DMA(1, (j2 >= 0 ? j2 : j0), o2);
;                 NL_STEP(1, selbits);
;                 NL_WAITBAR(2);
;                 if (j1 < 0) break;
.LBB0_979:
	s_nop 9
	v_max_f32_e32 v0, v97, v97
	v_max_f32_e32 v2, v96, v96
	v_max_f32_e32 v0, v2, v0
	v_max3_f32 v2, v98, v99, v81
	v_max3_f32 v0, v0, v80, v82
	v_max3_f32 v0, v0, v83, v100
	v_max3_f32 v2, v2, v102, v103
	v_max3_f32 v0, v0, v101, v84
	v_max3_f32 v2, v2, v86, v87
	v_max3_f32 v0, v0, v85, v104
	v_max3_f32 v2, v2, v106, v107
	v_max3_f32 v0, v0, v105, v88
	v_max3_f32 v2, v2, v90, v91
	v_max3_f32 v0, v0, v89, v108
	v_max3_f32 v2, v2, v110, v111
	v_max3_f32 v0, v0, v109, v92
	v_max3_f32 v2, v2, v94, v95
	v_max3_f32 v0, v0, v93, v2
	v_mov_b32_e32 v2, v0
	s_nop 1
	v_permlane32_swap_b32_e32 v0, v2
	v_max_f32_e32 v2, v2, v2
	v_max_f32_e32 v0, v0, v0
	v_max_f32_e32 v0, v0, v2
	v_sub_f32_e32 v10, v82, v0
	s_add_i32 s4, s1, 0
	v_exp_f32_e32 v120, v10
	v_add_u32_e32 v10, s4, v128
	v_sub_f32_e32 v2, v90, v0
	v_sub_f32_e32 v3, v89, v0
	v_sub_f32_e32 v4, v88, v0
	v_sub_f32_e32 v5, v87, v0
	v_sub_f32_e32 v6, v86, v0
	v_sub_f32_e32 v7, v85, v0
	v_sub_f32_e32 v8, v84, v0
	v_sub_f32_e32 v9, v83, v0
	v_sub_f32_e32 v85, v103, v0
	v_sub_f32_e32 v86, v102, v0
	v_sub_f32_e32 v87, v101, v0
	v_sub_f32_e32 v88, v100, v0
	v_sub_f32_e32 v89, v99, v0
	v_sub_f32_e32 v90, v98, v0
	v_sub_f32_e32 v15, v97, v0
	v_sub_f32_e32 v14, v96, v0
	v_add3_u32 v192, v10, v181, v180
	v_exp_f32_e32 v14, v14
	v_exp_f32_e32 v15, v15
	v_exp_f32_e32 v118, v90
	v_exp_f32_e32 v119, v89
	v_exp_f32_e32 v121, v9
	v_exp_f32_e32 v122, v88
	v_exp_f32_e32 v124, v8
	v_exp_f32_e32 v123, v87
	v_exp_f32_e32 v125, v7
	v_exp_f32_e32 v126, v86
	v_exp_f32_e32 v130, v6
	v_exp_f32_e32 v127, v85
	ds_read_b64_tr_b16 v[6:7], v192 offset:8192
	ds_read_b64_tr_b16 v[8:9], v192 offset:9216
	v_sub_f32_e32 v11, v81, v0
	v_sub_f32_e32 v12, v80, v0
	v_sub_f32_e32 v13, v106, v0
	v_add_u32_e32 v193, v10, v182
	v_exp_f32_e32 v116, v12
	v_exp_f32_e32 v117, v11
	v_exp_f32_e32 v136, v13
	ds_read_b64_tr_b16 v[10:11], v193 offset:8192
	ds_read_b64_tr_b16 v[12:13], v193 offset:9216
	ds_read_b64_tr_b16 v[112:113], v192 offset:10240
	ds_read_b64_tr_b16 v[114:115], v192 offset:11264
	v_sub_f32_e32 v92, v92, v0
	v_sub_f32_e32 v91, v91, v0
	v_sub_f32_e32 v80, v109, v0
	v_sub_f32_e32 v81, v108, v0
	v_sub_f32_e32 v82, v107, v0
	v_sub_f32_e32 v83, v105, v0
	v_sub_f32_e32 v84, v104, v0
	v_exp_f32_e32 v131, v5
	v_exp_f32_e32 v134, v4
	v_exp_f32_e32 v135, v3
	v_exp_f32_e32 v138, v2
	v_cvt_pk_bf16_f32 v2, v14, v15
	v_cvt_pk_bf16_f32 v3, v118, v119
	v_cvt_pk_bf16_f32 v4, v122, v123
	v_cvt_pk_bf16_f32 v5, v126, v127
	v_sub_f32_e32 v166, v95, v0
	v_sub_f32_e32 v189, v94, v0
	v_sub_f32_e32 v141, v93, v0
	v_sub_f32_e32 v143, v111, v0
	v_sub_f32_e32 v142, v110, v0
	v_exp_f32_e32 v132, v84
	v_exp_f32_e32 v133, v83
	s_waitcnt lgkmcnt(4)
	v_mfma_f32_32x32x16_bf16 v[96:111], v[6:9], v[2:5], 0
	v_exp_f32_e32 v137, v82
	v_exp_f32_e32 v139, v91
	v_exp_f32_e32 v128, v81
	v_exp_f32_e32 v140, v92
	v_exp_f32_e32 v129, v80
	ds_read_b64_tr_b16 v[6:7], v193 offset:10240
	ds_read_b64_tr_b16 v[8:9], v193 offset:11264
	v_exp_f32_e32 v142, v142
	s_waitcnt lgkmcnt(4)
	v_mfma_f32_32x32x16_bf16 v[80:95], v[10:13], v[2:5], 0
	v_exp_f32_e32 v143, v143
	v_cvt_pk_bf16_f32 v2, v132, v133
	v_cvt_pk_bf16_f32 v3, v136, v137
	v_cvt_pk_bf16_f32 v4, v128, v129
	v_cvt_pk_bf16_f32 v5, v142, v143
	v_cvt_pk_bf16_f32 v10, v116, v117
	v_cvt_pk_bf16_f32 v11, v120, v121
	s_waitcnt lgkmcnt(2)
	v_mfma_f32_32x32x16_bf16 v[96:111], v[112:115], v[2:5], v[96:111]
	ds_read_b64_tr_b16 v[112:113], v192 offset:12288
	ds_read_b64_tr_b16 v[114:115], v192 offset:13312
	v_cvt_pk_bf16_f32 v12, v124, v125
	v_cvt_pk_bf16_f32 v13, v130, v131
	v_exp_f32_e32 v141, v141
	v_exp_f32_e32 v190, v189
	v_exp_f32_e32 v191, v166
	v_add_f32_e32 v14, v116, v14
	v_add_f32_e32 v15, v117, v15
	s_waitcnt lgkmcnt(2)
	v_mfma_f32_32x32x16_bf16 v[80:95], v[6:9], v[2:5], v[80:95]
	ds_read_b64_tr_b16 v[2:3], v193 offset:12288
	ds_read_b64_tr_b16 v[4:5], v193 offset:13312
	ds_read_b64_tr_b16 v[6:7], v192 offset:14336
	ds_read_b64_tr_b16 v[8:9], v192 offset:15360
	v_add_f32_e64 v116, v140, v128
	v_add_f32_e64 v117, v141, v129
	v_add_f32_e32 v136, v138, v136
	v_add_f32_e32 v137, v139, v137
	v_add_f32_e32 v118, v120, v118
	v_add_f32_e32 v119, v121, v119
	v_add_f32_e32 v120, v190, v142
	v_add_f32_e32 v121, v191, v143
	v_add_f32_e32 v126, v130, v126
	v_add_f32_e32 v127, v131, v127
	v_add_f32_e32 v130, v134, v132
	v_add_f32_e32 v131, v135, v133
	s_waitcnt lgkmcnt(4)
	v_mfma_f32_32x32x16_bf16 v[96:111], v[112:115], v[10:13], v[96:111]
	ds_read_b64_tr_b16 v[112:113], v193 offset:14336
	ds_read_b64_tr_b16 v[114:115], v193 offset:15360
	s_waitcnt vmcnt(2) lgkmcnt(0)
	s_barrier
	s_andn2_b64 vcc, exec, s[60:61]
	s_waitcnt lgkmcnt(4)
	v_mfma_f32_32x32x16_bf16 v[80:95], v[2:5], v[10:13], v[80:95]
	v_add_f32_e64 v2, v124, v122
	v_add_f32_e64 v3, v125, v123
	v_cvt_pk_bf16_f32 v4, v140, v141
	v_add_f32_e64 v10, v2, v116
	v_add_f32_e64 v11, v3, v117
	v_cvt_pk_bf16_f32 v2, v134, v135
	v_cvt_pk_bf16_f32 v3, v138, v139
	v_cvt_pk_bf16_f32 v5, v190, v191
	v_add_f32_e32 v12, v14, v130
	v_add_f32_e32 v13, v15, v131
	s_waitcnt lgkmcnt(2)
	v_mfma_f32_32x32x16_bf16 v[96:111], v[6:9], v[2:5], v[96:111]
	v_add_f32_e64 v6, v126, v120
	v_add_f32_e64 v7, v127, v121
	v_add_f32_e64 v8, v118, v136
	v_add_f32_e64 v9, v119, v137
	v_add_f32_e64 v6, v8, v6
	v_add_f32_e64 v7, v9, v7
	v_add_f32_e32 v8, v12, v10
	v_add_f32_e32 v9, v13, v11
	s_nop 0
	v_add_f32_e32 v6, v8, v6
	v_add_f32_e32 v7, v9, v7
	s_waitcnt lgkmcnt(0)
	v_mfma_f32_32x32x16_bf16 v[80:95], v[112:115], v[2:5], v[80:95]
	v_add_f32_e32 v6, v6, v7
	v_add_f32_e32 v166, 0, v6
	s_cbranch_vccnz .LBB0_884
	s_and_b32 s0, s12, s0
	s_and_b64 s[4:5], s[6:7], exec
	s_cselect_b32 s4, -1, s11
	v_add_f32_e32 v0, 0, v0

; #define LAS __attribute__((address_space(3)))
;     ...
;         } else { LAS const float* ab = aux + (t - kb + 1);
; #pragma unroll
;             for (int r = 0; r < 16; ++r) { X0[r] = ab[63 - ((r & 3) + 8 * (r >> 2))] - m; X1[r] = ab[31 - ((r & 3) + 8 * (r >> 2))] - m; }
;             if (MODE == 1 && !sel) {
; #pragma unroll
;                 for (int r = 0; r < 16; ++r) { X0[r] = NEG; X1[r] = NEG; } }
.LBB0_983:
	s_andn2_b64 vcc, exec, s[8:9]
	s_cbranch_vccnz .LBB0_985
	v_lshl_or_b32 v2, s97, 6, v179
	v_sub_u32_e32 v2, v178, v2
	s_nop 7
	v_lshl_add_u32 v126, v2, 2, s96
	ds_read2_b32 v[2:3], v126 offset0:63 offset1:64
	ds_read2_b32 v[4:5], v126 offset0:31 offset1:32
	ds_read2_b32 v[6:7], v126 offset0:61 offset1:62
	ds_read2_b32 v[8:9], v126 offset0:29 offset1:30
	s_add_i32 s8, s51, 0
	s_waitcnt lgkmcnt(3)
	v_sub_f32_e32 v10, v2, v0
	v_sub_f32_e32 v11, v3, v0
	ds_read2_b32 v[2:3], v126 offset0:55 offset1:56
	s_waitcnt lgkmcnt(3)
	v_sub_f32_e32 v12, v4, v0
	v_sub_f32_e32 v13, v5, v0
	ds_read2_b32 v[4:5], v126 offset0:23 offset1:24
	ds_read2_b32 v[116:117], v126 offset0:15 offset1:16
	ds_read2_b32 v[118:119], v126 offset0:13 offset1:14
	s_waitcnt lgkmcnt(3)
	v_sub_f32_e32 v112, v2, v0
	v_sub_f32_e32 v113, v3, v0
	ds_read2_b32 v[2:3], v126 offset0:21 offset1:22
	v_sub_f32_e32 v14, v8, v0
	v_sub_f32_e32 v15, v9, v0
	ds_read2_b32 v[8:9], v126 offset0:53 offset1:54
	ds_read2_b32 v[120:121], v126 offset0:39 offset1:40
	s_waitcnt lgkmcnt(5)
	v_sub_f32_e32 v114, v4, v0
	v_sub_f32_e32 v115, v5, v0
	ds_read2_b32 v[4:5], v126 offset0:47 offset1:48
	s_waitcnt lgkmcnt(3)
	v_sub_f32_e32 v190, v2, v0
	v_sub_f32_e32 v191, v3, v0
	ds_read2_b32 v[2:3], v126 offset0:45 offset1:46
	ds_read2_b32 v[122:123], v126 offset0:7 offset1:8
	ds_read2_b32 v[124:125], v126 offset0:37 offset1:38
	ds_read2_b32 v[126:127], v126 offset0:5 offset1:6
	s_waitcnt lgkmcnt(6)
	v_sub_f32_e32 v8, v8, v0
	v_sub_f32_e32 v9, v9, v0
	v_sub_f32_e32 v6, v6, v0
	v_sub_f32_e32 v7, v7, v0
	s_waitcnt lgkmcnt(4)
	v_sub_f32_e32 v4, v4, v0
	v_sub_f32_e32 v5, v5, v0
	s_waitcnt lgkmcnt(3)
	v_sub_f32_e32 v2, v2, v0
	v_sub_f32_e32 v3, v3, v0
	s_waitcnt lgkmcnt(1)
	v_sub_f32_e32 v130, v124, v0
	v_sub_f32_e32 v131, v125, v0
	v_cndmask_b32_e64 v135, v8, v173, s[4:5]
	v_add_u32_e32 v8, s8, v183
	v_cndmask_b32_e64 v143, v130, v173, s[4:5]
	v_cndmask_b32_e64 v142, v131, v173, s[4:5]
	v_cndmask_b32_e64 v139, v2, v173, s[4:5]
	v_cndmask_b32_e64 v138, v3, v173, s[4:5]
	v_cndmask_b32_e64 v137, v4, v173, s[4:5]
	v_cndmask_b32_e64 v136, v5, v173, s[4:5]
	ds_read_b128 v[2:5], v8
	v_cndmask_b32_e64 v134, v9, v173, s[4:5]
	v_cndmask_b32_e64 v131, v6, v173, s[4:5]
	v_cndmask_b32_e64 v130, v7, v173, s[4:5]
	ds_read_b128 v[6:9], v8 offset:4096
	v_sub_f32_e32 v116, v116, v0
	v_sub_f32_e32 v117, v117, v0
	v_sub_f32_e32 v118, v118, v0
	v_sub_f32_e32 v119, v119, v0
	v_sub_f32_e32 v128, v120, v0
	v_sub_f32_e32 v129, v121, v0
	v_sub_f32_e32 v120, v122, v0
	v_sub_f32_e32 v121, v123, v0
	s_waitcnt lgkmcnt(2)
	v_sub_f32_e32 v122, v126, v0
	v_sub_f32_e32 v123, v127, v0
	v_cndmask_b32_e64 v125, v120, v173, s[4:5]
	v_cndmask_b32_e64 v127, v122, v173, s[4:5]
	v_cndmask_b32_e64 v126, v123, v173, s[4:5]
	v_cndmask_b32_e64 v124, v121, v173, s[4:5]
	v_cndmask_b32_e64 v123, v118, v173, s[4:5]
	v_cndmask_b32_e64 v122, v119, v173, s[4:5]
	v_cndmask_b32_e64 v121, v116, v173, s[4:5]
	v_cndmask_b32_e64 v120, v117, v173, s[4:5]
	v_cndmask_b32_e64 v119, v190, v173, s[4:5]
	v_cndmask_b32_e64 v141, v128, v173, s[4:5]
	v_cndmask_b32_e64 v140, v129, v173, s[4:5]
	v_cndmask_b32_e64 v133, v112, v173, s[4:5]
	v_cndmask_b32_e64 v132, v113, v173, s[4:5]
	v_cndmask_b32_e64 v129, v10, v173, s[4:5]
	v_cndmask_b32_e64 v128, v11, v173, s[4:5]
	v_cndmask_b32_e64 v118, v191, v173, s[4:5]
	v_cndmask_b32_e64 v117, v114, v173, s[4:5]
	v_cndmask_b32_e64 v116, v115, v173, s[4:5]
	v_cndmask_b32_e64 v115, v14, v173, s[4:5]
	v_cndmask_b32_e64 v114, v15, v173, s[4:5]
	v_cndmask_b32_e64 v113, v12, v173, s[4:5]
	v_cndmask_b32_e64 v112, v13, v173, s[4:5]
	v_add_u32_e32 v194, s8, v184
	v_add_u32_e32 v195, s8, v186
	v_add_u32_e32 v212, s8, v187
	ds_read_b128 v[196:199], v194
	ds_read_b128 v[200:203], v194 offset:4096
	ds_read_b128 v[204:207], v195
	ds_read_b128 v[208:211], v195 offset:4096
	ds_read_b128 v[216:219], v212
	ds_read_b128 v[220:223], v212 offset:4096
	s_waitcnt lgkmcnt(6)
	v_mfma_f32_32x32x16_bf16 v[128:143], v[2:5], v[144:147], v[128:143]
	v_mfma_f32_32x32x16_bf16 v[112:127], v[6:9], v[144:147], v[112:127]
	s_waitcnt lgkmcnt(4)
	v_mfma_f32_32x32x16_bf16 v[128:143], v[196:199], v[148:151], v[128:143]
	v_mfma_f32_32x32x16_bf16 v[112:127], v[200:203], v[148:151], v[112:127]
	s_waitcnt lgkmcnt(2)
	v_mfma_f32_32x32x16_bf16 v[128:143], v[204:207], v[152:155], v[128:143]
	v_mfma_f32_32x32x16_bf16 v[112:127], v[208:211], v[152:155], v[112:127]
	s_waitcnt lgkmcnt(0)
	v_mfma_f32_32x32x16_bf16 v[128:143], v[216:219], v[156:159], v[128:143]
	v_mfma_f32_32x32x16_bf16 v[112:127], v[220:223], v[156:159], v[112:127]
; __device__ __forceinline__ float xor32_add(float x) { auto r = __builtin_amdgcn_permlane32_swap(__float_as_uint(x), __float_as_uint(x), false, false); return __uint_as_float(r[0]) + __uint_as_float(r[1]); }
; template <int MODE> __device__ __forceinline__ int pop_tile(unsigned& tiles) { int j; if (MODE == 2) { j = 31 - __builtin_clz(tiles); tiles &= ~(1u << j); } else { j = __builtin_ctz(tiles); tiles &= tiles - 1u; } return j; }
; #define NL_WAITBAR(n) do { asm volatile("s_waitcnt vmcnt(" #n ") lgkmcnt(0)" ::: "memory"); __builtin_amdgcn_s_barrier(); asm volatile("" ::: "memory"); } while (0)
; __device__ __forceinline__ void nsa_unit(int b, int g, int tq, const Args& a, LAS unsigned char* lds, int tid, int wave, int lane, int& nxt) {
;     ...
;         NL_WAITBAR(2);
;         {
;             float m = 0.f, l = 0.f; bool first = true; f32x16 oa = {}, ob = {};
;             for (;;) {
;                 int j2, m2; if (wt) { j2 = pop_tile<2>(wt); m2 = 2; } else if (ut) { j2 = pop_tile<1>(ut); m2 = 1; } else { j2 = -1; m2 = 2; }
;                 NL_DMA(m2, (j2 >= 0 ? j2 : j0), o2);
;                 NL_STEP(2, 0u);
;                 NL_WAITBAR(2);
;                 j0 = j1; m0 = m1; j1 = j2; m1 = m2; { const int ot = o0; o0 = o1; o1 = o2; o2 = ot; }
;                 if (m0 != 2) break;
;             }
;             const float lt = xor32_add(l); const float sc = (lt > 0.f) ? g_w / lt : 0.f; acc0 += oa * sc; acc1 += ob * sc;
;         }
;         {
;             float m = 0.f, l = 0.f; bool first = true; f32x16 oa = {}, ob = {};
;             for (;;) {
;                 const int j2 = ut ? pop_tile<1>(ut) : -1;
;                 NL_DMA(1, (j2 >= 0 ? j2 : j0), o2);
;                 NL_STEP(1, selbits);
;                 NL_WAITBAR(2);
;                 if (j1 < 0) break;
;                 j0 = j1; j1 = j2; { const int ot = o0; o0 = o1; o1 = o2; o2 = ot; }
;             }
.LBB0_985:
	s_nop 9
	v_max_f32_e32 v2, v129, v129
	v_max_f32_e32 v3, v128, v128
	v_max_f32_e32 v2, v3, v2
	v_max3_f32 v3, v130, v131, v113
	v_max3_f32 v2, v2, v112, v114
	v_max3_f32 v2, v2, v115, v132
	v_max3_f32 v3, v3, v134, v135
	v_max3_f32 v2, v2, v133, v116
	v_max3_f32 v3, v3, v118, v119
	v_max3_f32 v2, v2, v117, v136
	v_max3_f32 v3, v3, v138, v139
	v_max3_f32 v2, v2, v137, v120
	v_max3_f32 v3, v3, v122, v123
	v_max3_f32 v2, v2, v121, v140
	v_max3_f32 v3, v3, v142, v143
	v_max3_f32 v2, v2, v141, v124
	v_max3_f32 v3, v3, v126, v127
	v_max3_f32 v2, v2, v125, v3
	v_mov_b32_e32 v3, v2
	s_nop 1
	v_permlane32_swap_b32_e32 v2, v3
	v_max_f32_e32 v3, v3, v3
	v_max_f32_e32 v2, v2, v2
	v_max_f32_e32 v2, v2, v3
	v_cmp_lt_f32_e32 vcc, s91, v2
	s_cbranch_vccz .LBB0_987
	s_nop 0
	v_cndmask_b32_e32 v3, 0, v2, vcc
	v_exp_f32_e64 v2, -v3
	v_sub_f32_e32 v127, v127, v3
	v_sub_f32_e32 v126, v126, v3
	v_sub_f32_e32 v125, v125, v3
	v_sub_f32_e32 v124, v124, v3
	v_sub_f32_e32 v123, v123, v3
	v_sub_f32_e32 v122, v122, v3
	v_sub_f32_e32 v121, v121, v3
	v_sub_f32_e32 v120, v120, v3
	v_sub_f32_e32 v119, v119, v3
	v_sub_f32_e32 v118, v118, v3
	v_sub_f32_e32 v117, v117, v3
	v_sub_f32_e32 v116, v116, v3
	v_sub_f32_e32 v115, v115, v3
	v_sub_f32_e32 v114, v114, v3
	v_sub_f32_e32 v113, v113, v3
	v_sub_f32_e32 v112, v112, v3
	v_sub_f32_e32 v143, v143, v3
	v_sub_f32_e32 v142, v142, v3
	v_sub_f32_e32 v141, v141, v3
	v_sub_f32_e32 v140, v140, v3
	v_sub_f32_e32 v139, v139, v3
	v_sub_f32_e32 v138, v138, v3
	v_sub_f32_e32 v137, v137, v3
	v_sub_f32_e32 v136, v136, v3
	v_sub_f32_e32 v135, v135, v3
	v_sub_f32_e32 v134, v134, v3
	v_sub_f32_e32 v133, v133, v3
	v_sub_f32_e32 v132, v132, v3
	v_sub_f32_e32 v131, v131, v3
	v_sub_f32_e32 v130, v130, v3
	v_sub_f32_e32 v129, v129, v3
	v_sub_f32_e32 v128, v128, v3
	v_add_f32_e32 v0, v0, v3
	v_mul_f32_e32 v166, v166, v2
	v_mul_f32_e32 v110, v110, v2
	v_mul_f32_e32 v111, v111, v2
	v_mul_f32_e32 v108, v108, v2
	v_mul_f32_e32 v109, v109, v2
	v_mul_f32_e32 v106, v106, v2
	v_mul_f32_e32 v107, v107, v2
	v_mul_f32_e32 v104, v104, v2
	v_mul_f32_e32 v105, v105, v2
	v_mul_f32_e32 v102, v102, v2
	v_mul_f32_e32 v103, v103, v2
	v_mul_f32_e32 v100, v100, v2
	v_mul_f32_e32 v101, v101, v2
	v_mul_f32_e32 v98, v98, v2
	v_mul_f32_e32 v99, v99, v2
	v_mul_f32_e32 v96, v96, v2
	v_mul_f32_e32 v97, v97, v2
	v_mul_f32_e32 v94, v94, v2
	v_mul_f32_e32 v95, v95, v2
	v_mul_f32_e32 v92, v92, v2
	v_mul_f32_e32 v93, v93, v2
	v_mul_f32_e32 v90, v90, v2
	v_mul_f32_e32 v91, v91, v2
	v_mul_f32_e32 v88, v88, v2
	v_mul_f32_e32 v89, v89, v2
	v_mul_f32_e32 v86, v86, v2
	v_mul_f32_e32 v87, v87, v2
	v_mul_f32_e32 v84, v84, v2
	v_mul_f32_e32 v85, v85, v2
	v_mul_f32_e32 v82, v82, v2
	v_mul_f32_e32 v83, v83, v2
	v_mul_f32_e32 v80, v80, v2
	v_mul_f32_e32 v81, v81, v2
.LBB0_987:
	v_add_u32_e32 v10, s51, v188
	v_add3_u32 v189, v10, v181, v180
	v_exp_f32_e32 v14, v128
	v_exp_f32_e32 v15, v129
	v_exp_f32_e32 v130, v130
	v_exp_f32_e32 v131, v131
	v_exp_f32_e32 v132, v132
	v_exp_f32_e32 v133, v133
	v_exp_f32_e32 v134, v134
	v_exp_f32_e32 v135, v135
	ds_read_b64_tr_b16 v[6:7], v189 offset:8192
	ds_read_b64_tr_b16 v[8:9], v189 offset:9216
	v_add_u32_e32 v192, v10, v182
	v_exp_f32_e32 v128, v112
	v_exp_f32_e32 v129, v113
	v_exp_f32_e32 v190, v114
	v_exp_f32_e32 v191, v115
	ds_read_b64_tr_b16 v[10:11], v192 offset:8192
	ds_read_b64_tr_b16 v[12:13], v192 offset:9216
	ds_read_b64_tr_b16 v[112:113], v189 offset:10240
	ds_read_b64_tr_b16 v[114:115], v189 offset:11264
	v_cvt_pk_bf16_f32 v2, v14, v15
	v_cvt_pk_bf16_f32 v3, v130, v131
	v_cvt_pk_bf16_f32 v4, v132, v133
	v_cvt_pk_bf16_f32 v5, v134, v135
	v_exp_f32_e32 v136, v136
	v_exp_f32_e32 v137, v137
	s_waitcnt lgkmcnt(4)
	v_mfma_f32_32x32x16_bf16 v[96:111], v[6:9], v[2:5], v[96:111]
	v_exp_f32_e32 v138, v138
	v_exp_f32_e32 v139, v139
	v_exp_f32_e32 v140, v140
	v_exp_f32_e32 v141, v141
	ds_read_b64_tr_b16 v[6:7], v192 offset:10240
	ds_read_b64_tr_b16 v[8:9], v192 offset:11264
	v_exp_f32_e32 v142, v142
	v_exp_f32_e32 v143, v143
	s_waitcnt lgkmcnt(4)
	v_mfma_f32_32x32x16_bf16 v[80:95], v[10:13], v[2:5], v[80:95]
	v_cvt_pk_bf16_f32 v2, v136, v137
	v_cvt_pk_bf16_f32 v3, v138, v139
	v_cvt_pk_bf16_f32 v4, v140, v141
	v_cvt_pk_bf16_f32 v5, v142, v143
	v_exp_f32_e32 v116, v116
	v_exp_f32_e32 v117, v117
	v_exp_f32_e32 v118, v118
	s_waitcnt lgkmcnt(2)
	v_mfma_f32_32x32x16_bf16 v[96:111], v[112:115], v[2:5], v[96:111]
	v_exp_f32_e32 v119, v119
	ds_read_b64_tr_b16 v[112:113], v189 offset:12288
	ds_read_b64_tr_b16 v[114:115], v189 offset:13312
	v_cvt_pk_bf16_f32 v10, v128, v129
	v_cvt_pk_bf16_f32 v11, v190, v191
	v_cvt_pk_bf16_f32 v12, v116, v117
	v_cvt_pk_bf16_f32 v13, v118, v119
	v_exp_f32_e32 v124, v124
	s_waitcnt lgkmcnt(2)
	v_mfma_f32_32x32x16_bf16 v[80:95], v[6:9], v[2:5], v[80:95]
	ds_read_b64_tr_b16 v[2:3], v192 offset:12288
	ds_read_b64_tr_b16 v[4:5], v192 offset:13312
	ds_read_b64_tr_b16 v[6:7], v189 offset:14336
	ds_read_b64_tr_b16 v[8:9], v189 offset:15360
	v_exp_f32_e32 v125, v125
	v_exp_f32_e32 v120, v120
	v_exp_f32_e32 v121, v121
	v_exp_f32_e32 v122, v122
	v_exp_f32_e32 v123, v123
	v_exp_f32_e32 v126, v126
	s_waitcnt lgkmcnt(4)
	v_mfma_f32_32x32x16_bf16 v[96:111], v[112:115], v[10:13], v[96:111]
	v_exp_f32_e32 v127, v127
	ds_read_b64_tr_b16 v[112:113], v192 offset:14336
	ds_read_b64_tr_b16 v[114:115], v192 offset:15360
	v_add_f32_e32 v14, v128, v14
	v_add_f32_e32 v15, v129, v15
	v_add_f32_e32 v128, v124, v140
	v_add_f32_e32 v129, v125, v141
	v_add_f32_e32 v138, v122, v138
	v_add_f32_e32 v139, v123, v139
	v_add_f32_e32 v130, v190, v130
	v_add_f32_e32 v131, v191, v131
	v_add_f32_e32 v142, v126, v142
	v_add_f32_e32 v143, v127, v143
	s_waitcnt lgkmcnt(4)
	v_mfma_f32_32x32x16_bf16 v[80:95], v[2:5], v[10:13], v[80:95]
	v_add_f32_e64 v2, v116, v132
	v_add_f32_e64 v3, v117, v133
	v_cvt_pk_bf16_f32 v4, v124, v125
	v_add_f32_e64 v10, v2, v128
	v_add_f32_e64 v11, v3, v129
	v_cvt_pk_bf16_f32 v2, v120, v121
	v_cvt_pk_bf16_f32 v3, v122, v123
	v_cvt_pk_bf16_f32 v5, v126, v127
	v_add_f32_e32 v118, v118, v134
	v_add_f32_e32 v119, v119, v135
	v_add_f32_e32 v134, v120, v136
	v_add_f32_e32 v135, v121, v137
	s_waitcnt lgkmcnt(2)
	v_mfma_f32_32x32x16_bf16 v[96:111], v[6:9], v[2:5], v[96:111]
	v_add_f32_e64 v12, v14, v134
	v_add_f32_e64 v13, v15, v135
	v_add_f32_e64 v6, v118, v142
	v_add_f32_e64 v7, v119, v143
	v_add_f32_e64 v8, v130, v138
	v_add_f32_e64 v9, v131, v139
	s_and_b32 s0, s13, s0
	v_add_f32_e32 v6, v8, v6
	v_add_f32_e32 v7, v9, v7
	v_add_f32_e32 v8, v12, v10
	v_add_f32_e32 v9, v13, v11
	s_waitcnt vmcnt(2) lgkmcnt(0)
	s_waitcnt lgkmcnt(0)
	v_mfma_f32_32x32x16_bf16 v[80:95], v[112:115], v[2:5], v[80:95]
	v_add_f32_e64 v6, v8, v6
	v_add_f32_e64 v7, v9, v7
	s_barrier
	s_and_b64 s[4:5], s[6:7], exec
	v_add_f32_e32 v6, v6, v7
	s_cselect_b32 s4, -1, s1
	v_add_f32_e32 v166, v166, v6
	s_cmp_gt_i32 s11, -1
	s_cbranch_scc0 .LBB0_884
	s_mov_b32 s1, s51
	s_mov_b32 s51, s12
	s_mov_b32 s97, s11
	s_branch .LBB0_981
